# GEMM mainloops: LDS-read wait moved from before each super-phase barrier to its first consumer after the barrier
# speedup vs baseline: 1.0012x; 1.0012x over previous
; #define PG8_STAGE(bufoff, gbase, voff) do { _Pragma("unroll") for (int _i = 0; _i < 2; ++_i) \
;         __builtin_amdgcn_global_load_lds((const unsigned*)((const char*)(gbase) + (voff)[_i]), (PG8_LAS unsigned*)(lds + (bufoff) + ldsw + _i * 8192), 16, 0, 0); } while (0)
; #define PG8_LDA(dst, b, h) do { _Pragma("unroll") for (int m = 0; m < 4; ++m) _Pragma("unroll") for (int k = 0; k < 2; ++k) dst[m][k] = *(const PG8_LAS bf16x8*)(lds + PG8_SA(b, h) + aoff + m * 2048 + k * 1024); } while (0)
; #define PG8_LDB(dst, b, h) do { _Pragma("unroll") for (int n = 0; n < 2; ++n) _Pragma("unroll") for (int k = 0; k < 2; ++k) dst[n][k] = *(const PG8_LAS bf16x8*)(lds + PG8_SB(b, h) + boff + n * 2048 + k * 1024); } while (0)
; #define PG8_MMA(ai, bj, At, Bt) do { __builtin_amdgcn_s_setprio(1); _Pragma("unroll") for (int m = 0; m < 4; ++m) _Pragma("unroll") for (int n = 0; n < 2; ++n) _Pragma("unroll") for (int k = 0; k < 2; ++k) \
;         acc[ai][bj][m][n] = __builtin_amdgcn_mfma_f32_16x16x32_bf16(Bt[n][k], At[m][k], acc[ai][bj][m][n], 0, 0, 0); __builtin_amdgcn_s_setprio(0); } while (0)
; #define PG8_WAIT_V(n) asm volatile("s_waitcnt vmcnt(" #n ")" ::: "memory")
; #define PG8_WAIT_L(n) asm volatile("s_waitcnt lgkmcnt(" #n ")" ::: "memory")
; #define PG8_BAR __builtin_amdgcn_s_barrier()
; #define PG8_SCHED __builtin_amdgcn_sched_barrier(0)
; template <class Epi, class Sched, bool ALIGN_EPI = false, bool SP2 = false>
; __device__ __forceinline__ void gemm_phase(PG8_LAS unsigned char* lds, const Gemm g, const Sched& S, const Epi& E) {
;     ...
;             PG8_LDB(B0, 0, 0); PG8_LDB(B1, 0, 1); PG8_SCHED; PG8_LDA(At, 0, 0); PG8_STAGE(PG8_SA(1, 1), a1 + hstep, voffA);
;             PG8_WAIT_V(8); PG8_WAIT_L(0); PG8_BAR; PG8_MMA(0, 0, At, B0); PG8_MMA(0, 1, At, B1); PG8_BAR; PG8_SCHED;
;             PG8_LDA(At, 0, 1); PG8_STAGE(PG8_SB(0, 0), b2, voffB); PG8_STAGE(PG8_SB(0, 1), b2 + hstep, voffB); PG8_STAGE(PG8_SA(0, 0), a2, voffA);
;             PG8_WAIT_V(8); PG8_WAIT_L(0); PG8_BAR; PG8_MMA(1, 0, At, B0); PG8_MMA(1, 1, At, B1); PG8_BAR; PG8_SCHED;
.LBB0_217:
	ds_read_b128 v[152:155], v165
	ds_read_b128 v[174:177], v165 offset:1024
	ds_read_b128 v[182:185], v165 offset:2048
	ds_read_b128 v[186:189], v165 offset:3072
	ds_read_b128 v[190:193], v167
	ds_read_b128 v[194:197], v167 offset:1024
	ds_read_b128 v[198:201], v167 offset:2048
	ds_read_b128 v[202:205], v167 offset:3072
	s_add_u32 s12, s10, 0xfff80080
	s_addc_u32 s13, s11, -1
	s_cmp_eq_u32 s49, 28
	s_cselect_b32 s47, s9, s13
	s_cselect_b32 s46, s15, s12
	s_cselect_b32 s13, s33, s48
	s_cselect_b32 s12, s39, s41
	v_lshl_add_u64 v[156:157], s[10:11], 0, v[144:145]
	s_add_i32 m0, s67, 0xc000
	ds_read_b128 v[206:209], v168
	ds_read_b128 v[210:213], v168 offset:1024
	ds_read_b128 v[214:217], v168 offset:2048
	ds_read_b128 v[218:221], v168 offset:3072
	ds_read_b128 v[222:225], v168 offset:4096
	ds_read_b128 v[226:229], v168 offset:5120
	ds_read_b128 v[230:233], v168 offset:6144
	ds_read_b128 v[234:237], v168 offset:7168
	global_load_lds_dwordx4 v[156:157], off
	v_lshl_add_u64 v[156:157], s[10:11], 0, v[146:147]
	s_add_i32 m0, s67, 0xe000
	s_nop 0
	global_load_lds_dwordx4 v[156:157], off
	s_waitcnt vmcnt(8)
	s_barrier
	s_setprio 1
	s_waitcnt lgkmcnt(0)
	v_mfma_f32_16x16x32_bf16 v[124:127], v[152:155], v[206:209], v[124:127]
	v_mfma_f32_16x16x32_bf16 v[120:123], v[182:185], v[206:209], v[120:123]
	v_mfma_f32_16x16x32_bf16 v[108:111], v[152:155], v[214:217], v[108:111]
	v_mfma_f32_16x16x32_bf16 v[104:107], v[182:185], v[214:217], v[104:107]
	v_mfma_f32_16x16x32_bf16 v[92:95], v[152:155], v[222:225], v[92:95]
	v_mfma_f32_16x16x32_bf16 v[88:91], v[182:185], v[222:225], v[88:91]
	v_mfma_f32_16x16x32_bf16 v[76:79], v[152:155], v[230:233], v[76:79]
	v_mfma_f32_16x16x32_bf16 v[72:75], v[182:185], v[230:233], v[72:75]
	v_mfma_f32_16x16x32_bf16 v[124:127], v[174:177], v[210:213], v[124:127]
	v_mfma_f32_16x16x32_bf16 v[120:123], v[186:189], v[210:213], v[120:123]
	v_mfma_f32_16x16x32_bf16 v[108:111], v[174:177], v[218:221], v[108:111]
	v_mfma_f32_16x16x32_bf16 v[104:107], v[186:189], v[218:221], v[104:107]
	v_mfma_f32_16x16x32_bf16 v[92:95], v[174:177], v[226:229], v[92:95]
	v_mfma_f32_16x16x32_bf16 v[88:91], v[186:189], v[226:229], v[88:91]
	v_mfma_f32_16x16x32_bf16 v[76:79], v[174:177], v[234:237], v[76:79]
	v_mfma_f32_16x16x32_bf16 v[72:75], v[186:189], v[234:237], v[72:75]
	s_setprio 0
	s_cmp_eq_u32 s14, 16
	s_cbranch_scc1 .Lp1_skipb1_0
	s_setprio 1
	v_mfma_f32_16x16x32_bf16 v[116:119], v[190:193], v[206:209], v[116:119]
	v_mfma_f32_16x16x32_bf16 v[112:115], v[198:201], v[206:209], v[112:115]
	v_mfma_f32_16x16x32_bf16 v[100:103], v[190:193], v[214:217], v[100:103]
	v_mfma_f32_16x16x32_bf16 v[96:99], v[198:201], v[214:217], v[96:99]
	v_mfma_f32_16x16x32_bf16 v[84:87], v[190:193], v[222:225], v[84:87]
	v_mfma_f32_16x16x32_bf16 v[80:83], v[198:201], v[222:225], v[80:83]
	v_mfma_f32_16x16x32_bf16 v[68:71], v[190:193], v[230:233], v[68:71]
	v_mfma_f32_16x16x32_bf16 v[64:67], v[198:201], v[230:233], v[64:67]
	v_mfma_f32_16x16x32_bf16 v[116:119], v[194:197], v[210:213], v[116:119]
	v_mfma_f32_16x16x32_bf16 v[112:115], v[202:205], v[210:213], v[112:115]
	v_mfma_f32_16x16x32_bf16 v[100:103], v[194:197], v[218:221], v[100:103]
	v_mfma_f32_16x16x32_bf16 v[96:99], v[202:205], v[218:221], v[96:99]
	v_mfma_f32_16x16x32_bf16 v[84:87], v[194:197], v[226:229], v[84:87]
	v_mfma_f32_16x16x32_bf16 v[80:83], v[202:205], v[226:229], v[80:83]
	v_mfma_f32_16x16x32_bf16 v[68:71], v[194:197], v[234:237], v[68:71]
	v_mfma_f32_16x16x32_bf16 v[64:67], v[202:205], v[234:237], v[64:67]
	s_setprio 0
.Lp1_skipb1_0:
	s_barrier
	s_add_i32 s50, s79, s66
	v_lshl_add_u64 v[156:157], s[12:13], 0, v[130:131]
	s_mov_b32 m0, s50
	ds_read_b128 v[206:209], v168 offset:16384
	ds_read_b128 v[210:213], v168 offset:17408
	ds_read_b128 v[214:217], v168 offset:18432
	ds_read_b128 v[218:221], v168 offset:19456
	ds_read_b128 v[222:225], v168 offset:20480
	ds_read_b128 v[226:229], v168 offset:21504
	ds_read_b128 v[230:233], v168 offset:22528
	ds_read_b128 v[234:237], v168 offset:23552
	global_load_lds_dwordx4 v[156:157], off
	s_add_i32 m0, s50, 0x2000
	s_add_u32 s50, s12, 0x80000
	v_lshl_add_u64 v[238:239], s[12:13], 0, v[134:135]
	s_addc_u32 s51, s13, 0
	s_add_i32 s52, s72, s66
	global_load_lds_dwordx4 v[238:239], off
	v_lshl_add_u64 v[240:241], s[50:51], 0, v[130:131]
	s_mov_b32 m0, s52
	v_lshl_add_u64 v[242:243], s[46:47], 0, v[132:133]
	global_load_lds_dwordx4 v[240:241], off
	v_lshl_add_u64 v[240:241], s[50:51], 0, v[134:135]
	s_add_i32 m0, s52, 0x2000
	s_nop 0
	global_load_lds_dwordx4 v[240:241], off
	v_lshl_add_u64 v[240:241], s[46:47], 0, v[128:129]
	s_mov_b32 m0, s67
	s_nop 0
	global_load_lds_dwordx4 v[240:241], off
	s_mov_b32 m0, s68
	s_nop 0
	global_load_lds_dwordx4 v[242:243], off
	s_waitcnt vmcnt(8)
	s_barrier
	s_setprio 1
	s_waitcnt lgkmcnt(0)
	v_mfma_f32_16x16x32_bf16 v[60:63], v[152:155], v[206:209], v[60:63]
	v_mfma_f32_16x16x32_bf16 v[56:59], v[182:185], v[206:209], v[56:59]
	v_mfma_f32_16x16x32_bf16 v[44:47], v[152:155], v[214:217], v[44:47]
	v_mfma_f32_16x16x32_bf16 v[40:43], v[182:185], v[214:217], v[40:43]
	v_mfma_f32_16x16x32_bf16 v[28:31], v[152:155], v[222:225], v[28:31]
	v_mfma_f32_16x16x32_bf16 v[24:27], v[182:185], v[222:225], v[24:27]
	v_mfma_f32_16x16x32_bf16 v[12:15], v[152:155], v[230:233], v[12:15]
	v_mfma_f32_16x16x32_bf16 v[8:11], v[182:185], v[230:233], v[8:11]
	v_mfma_f32_16x16x32_bf16 v[60:63], v[174:177], v[210:213], v[60:63]
	v_mfma_f32_16x16x32_bf16 v[56:59], v[186:189], v[210:213], v[56:59]
	v_mfma_f32_16x16x32_bf16 v[44:47], v[174:177], v[218:221], v[44:47]
	v_mfma_f32_16x16x32_bf16 v[40:43], v[186:189], v[218:221], v[40:43]
	v_mfma_f32_16x16x32_bf16 v[28:31], v[174:177], v[226:229], v[28:31]
	v_mfma_f32_16x16x32_bf16 v[24:27], v[186:189], v[226:229], v[24:27]
	v_mfma_f32_16x16x32_bf16 v[12:15], v[174:177], v[234:237], v[12:15]
	v_mfma_f32_16x16x32_bf16 v[8:11], v[186:189], v[234:237], v[8:11]
	s_setprio 0
	s_cmp_eq_u32 s14, 16
	s_cbranch_scc1 .Lp1_skipb1_1
; #define PG8_STAGE(bufoff, gbase, voff) do { _Pragma("unroll") for (int _i = 0; _i < 2; ++_i) \
;         __builtin_amdgcn_global_load_lds((const unsigned*)((const char*)(gbase) + (voff)[_i]), (PG8_LAS unsigned*)(lds + (bufoff) + ldsw + _i * 8192), 16, 0, 0); } while (0)
; #define PG8_LDA(dst, b, h) do { _Pragma("unroll") for (int m = 0; m < 4; ++m) _Pragma("unroll") for (int k = 0; k < 2; ++k) dst[m][k] = *(const PG8_LAS bf16x8*)(lds + PG8_SA(b, h) + aoff + m * 2048 + k * 1024); } while (0)
; #define PG8_LDB(dst, b, h) do { _Pragma("unroll") for (int n = 0; n < 2; ++n) _Pragma("unroll") for (int k = 0; k < 2; ++k) dst[n][k] = *(const PG8_LAS bf16x8*)(lds + PG8_SB(b, h) + boff + n * 2048 + k * 1024); } while (0)
; #define PG8_MMA(ai, bj, At, Bt) do { __builtin_amdgcn_s_setprio(1); _Pragma("unroll") for (int m = 0; m < 4; ++m) _Pragma("unroll") for (int n = 0; n < 2; ++n) _Pragma("unroll") for (int k = 0; k < 2; ++k) \
;         acc[ai][bj][m][n] = __builtin_amdgcn_mfma_f32_16x16x32_bf16(Bt[n][k], At[m][k], acc[ai][bj][m][n], 0, 0, 0); __builtin_amdgcn_s_setprio(0); } while (0)
; #define PG8_WAIT_V(n) asm volatile("s_waitcnt vmcnt(" #n ")" ::: "memory")
; #define PG8_WAIT_L(n) asm volatile("s_waitcnt lgkmcnt(" #n ")" ::: "memory")
; #define PG8_BAR __builtin_amdgcn_s_barrier()
; #define PG8_SCHED __builtin_amdgcn_sched_barrier(0)
; template <class Epi, class Sched, bool ALIGN_EPI = false, bool SP2 = false>
; __device__ __forceinline__ void gemm_phase(PG8_LAS unsigned char* lds, const Gemm g, const Sched& S, const Epi& E) {
;     ...
;             PG8_WAIT_V(8); PG8_WAIT_L(0); PG8_BAR; PG8_MMA(1, 0, At, B0); PG8_MMA(1, 1, At, B1); PG8_BAR; PG8_SCHED;
;             PG8_LDB(B0, 1, 0); PG8_LDB(B1, 1, 1); PG8_SCHED; PG8_LDA(At, 1, 0); PG8_STAGE(PG8_SA(0, 1), a2 + hstep, voffA);
;             PG8_WAIT_V(8); PG8_WAIT_L(0); PG8_BAR; PG8_MMA(0, 0, At, B0); PG8_MMA(0, 1, At, B1); PG8_BAR; PG8_SCHED;
	s_setprio 1
	v_mfma_f32_16x16x32_bf16 v[52:55], v[190:193], v[206:209], v[52:55]
	v_mfma_f32_16x16x32_bf16 v[48:51], v[198:201], v[206:209], v[48:51]
	v_mfma_f32_16x16x32_bf16 v[36:39], v[190:193], v[214:217], v[36:39]
	v_mfma_f32_16x16x32_bf16 v[32:35], v[198:201], v[214:217], v[32:35]
	v_mfma_f32_16x16x32_bf16 v[20:23], v[190:193], v[222:225], v[20:23]
	v_mfma_f32_16x16x32_bf16 v[16:19], v[198:201], v[222:225], v[16:19]
	v_mfma_f32_16x16x32_bf16 v[4:7], v[190:193], v[230:233], v[4:7]
	v_mfma_f32_16x16x32_bf16 v[0:3], v[198:201], v[230:233], v[0:3]
	v_mfma_f32_16x16x32_bf16 v[52:55], v[194:197], v[210:213], v[52:55]
	v_mfma_f32_16x16x32_bf16 v[48:51], v[202:205], v[210:213], v[48:51]
	v_mfma_f32_16x16x32_bf16 v[36:39], v[194:197], v[218:221], v[36:39]
	v_mfma_f32_16x16x32_bf16 v[32:35], v[202:205], v[218:221], v[32:35]
	v_mfma_f32_16x16x32_bf16 v[20:23], v[194:197], v[226:229], v[20:23]
	v_mfma_f32_16x16x32_bf16 v[16:19], v[202:205], v[226:229], v[16:19]
	v_mfma_f32_16x16x32_bf16 v[4:7], v[194:197], v[234:237], v[4:7]
	v_mfma_f32_16x16x32_bf16 v[0:3], v[202:205], v[234:237], v[0:3]
	s_setprio 0
.Lp1_skipb1_1:
	s_barrier
	s_add_i32 s50, 0, 0x18000
	v_add_u32_e32 v136, s50, v141
	s_add_i32 s51, 0, 0x1c000
	ds_read_b128 v[152:155], v136
	ds_read_b128 v[174:177], v136 offset:1024
	ds_read_b128 v[182:185], v136 offset:2048
	ds_read_b128 v[186:189], v136 offset:3072
	v_add_u32_e32 v136, s51, v141
	ds_read_b128 v[190:193], v136
	ds_read_b128 v[194:197], v136 offset:1024
	ds_read_b128 v[198:201], v136 offset:2048
	ds_read_b128 v[202:205], v136 offset:3072
	s_add_u32 s46, s46, 0x80000
	s_addc_u32 s47, s47, 0
	s_mov_b32 m0, s69
	v_lshl_add_u64 v[244:245], s[46:47], 0, v[128:129]
	ds_read_b128 v[206:209], v168 offset:32768
	ds_read_b128 v[210:213], v168 offset:33792
	ds_read_b128 v[214:217], v168 offset:34816
	ds_read_b128 v[218:221], v168 offset:35840
	ds_read_b128 v[222:225], v168 offset:36864
	ds_read_b128 v[226:229], v168 offset:37888
	ds_read_b128 v[230:233], v168 offset:38912
	ds_read_b128 v[234:237], v168 offset:39936
	global_load_lds_dwordx4 v[244:245], off
	v_lshl_add_u64 v[244:245], s[46:47], 0, v[132:133]
	s_mov_b32 m0, s70
	s_nop 0
	global_load_lds_dwordx4 v[244:245], off
	s_waitcnt vmcnt(8)
	s_barrier
	s_setprio 1
	s_waitcnt lgkmcnt(0)
	v_mfma_f32_16x16x32_bf16 v[124:127], v[152:155], v[206:209], v[124:127]
	v_mfma_f32_16x16x32_bf16 v[120:123], v[182:185], v[206:209], v[120:123]
	v_mfma_f32_16x16x32_bf16 v[108:111], v[152:155], v[214:217], v[108:111]
	v_mfma_f32_16x16x32_bf16 v[104:107], v[182:185], v[214:217], v[104:107]
	v_mfma_f32_16x16x32_bf16 v[92:95], v[152:155], v[222:225], v[92:95]
	v_mfma_f32_16x16x32_bf16 v[88:91], v[182:185], v[222:225], v[88:91]
	v_mfma_f32_16x16x32_bf16 v[76:79], v[152:155], v[230:233], v[76:79]
	v_mfma_f32_16x16x32_bf16 v[72:75], v[182:185], v[230:233], v[72:75]
	v_mfma_f32_16x16x32_bf16 v[124:127], v[174:177], v[210:213], v[124:127]
	v_mfma_f32_16x16x32_bf16 v[120:123], v[186:189], v[210:213], v[120:123]
	v_mfma_f32_16x16x32_bf16 v[108:111], v[174:177], v[218:221], v[108:111]
	v_mfma_f32_16x16x32_bf16 v[104:107], v[186:189], v[218:221], v[104:107]
	v_mfma_f32_16x16x32_bf16 v[92:95], v[174:177], v[226:229], v[92:95]
	v_mfma_f32_16x16x32_bf16 v[88:91], v[186:189], v[226:229], v[88:91]
	v_mfma_f32_16x16x32_bf16 v[76:79], v[174:177], v[234:237], v[76:79]
	v_mfma_f32_16x16x32_bf16 v[72:75], v[186:189], v[234:237], v[72:75]
	s_setprio 0
	s_cmp_eq_u32 s14, 16
	s_cbranch_scc1 .Lp1_skipb1_2
	s_setprio 1
	v_mfma_f32_16x16x32_bf16 v[116:119], v[190:193], v[206:209], v[116:119]
	v_mfma_f32_16x16x32_bf16 v[112:115], v[198:201], v[206:209], v[112:115]
	v_mfma_f32_16x16x32_bf16 v[100:103], v[190:193], v[214:217], v[100:103]
	v_mfma_f32_16x16x32_bf16 v[96:99], v[198:201], v[214:217], v[96:99]
	v_mfma_f32_16x16x32_bf16 v[84:87], v[190:193], v[222:225], v[84:87]
	v_mfma_f32_16x16x32_bf16 v[80:83], v[198:201], v[222:225], v[80:83]
	v_mfma_f32_16x16x32_bf16 v[68:71], v[190:193], v[230:233], v[68:71]
	v_mfma_f32_16x16x32_bf16 v[64:67], v[198:201], v[230:233], v[64:67]
	v_mfma_f32_16x16x32_bf16 v[116:119], v[194:197], v[210:213], v[116:119]
	v_mfma_f32_16x16x32_bf16 v[112:115], v[202:205], v[210:213], v[112:115]
	v_mfma_f32_16x16x32_bf16 v[100:103], v[194:197], v[218:221], v[100:103]
	v_mfma_f32_16x16x32_bf16 v[96:99], v[202:205], v[218:221], v[96:99]
	v_mfma_f32_16x16x32_bf16 v[84:87], v[194:197], v[226:229], v[84:87]
	v_mfma_f32_16x16x32_bf16 v[80:83], v[202:205], v[226:229], v[80:83]
	v_mfma_f32_16x16x32_bf16 v[68:71], v[194:197], v[234:237], v[68:71]
	v_mfma_f32_16x16x32_bf16 v[64:67], v[202:205], v[234:237], v[64:67]
	s_setprio 0
; #define PG8_STAGE(bufoff, gbase, voff) do { _Pragma("unroll") for (int _i = 0; _i < 2; ++_i) \
;         __builtin_amdgcn_global_load_lds((const unsigned*)((const char*)(gbase) + (voff)[_i]), (PG8_LAS unsigned*)(lds + (bufoff) + ldsw + _i * 8192), 16, 0, 0); } while (0)
; #define PG8_LDA(dst, b, h) do { _Pragma("unroll") for (int m = 0; m < 4; ++m) _Pragma("unroll") for (int k = 0; k < 2; ++k) dst[m][k] = *(const PG8_LAS bf16x8*)(lds + PG8_SA(b, h) + aoff + m * 2048 + k * 1024); } while (0)
; #define PG8_MMA(ai, bj, At, Bt) do { __builtin_amdgcn_s_setprio(1); _Pragma("unroll") for (int m = 0; m < 4; ++m) _Pragma("unroll") for (int n = 0; n < 2; ++n) _Pragma("unroll") for (int k = 0; k < 2; ++k) \
;         acc[ai][bj][m][n] = __builtin_amdgcn_mfma_f32_16x16x32_bf16(Bt[n][k], At[m][k], acc[ai][bj][m][n], 0, 0, 0); __builtin_amdgcn_s_setprio(0); } while (0)
; #define PG8_WAIT_V(n) asm volatile("s_waitcnt vmcnt(" #n ")" ::: "memory")
; #define PG8_WAIT_L(n) asm volatile("s_waitcnt lgkmcnt(" #n ")" ::: "memory")
; #define PG8_BAR __builtin_amdgcn_s_barrier()
; #define PG8_SCHED __builtin_amdgcn_sched_barrier(0)
; template <class Epi, class Sched, bool ALIGN_EPI = false, bool SP2 = false>
; __device__ __forceinline__ void gemm_phase(PG8_LAS unsigned char* lds, const Gemm g, const Sched& S, const Epi& E) {
;     ...
;             PG8_WAIT_V(8); PG8_WAIT_L(0); PG8_BAR; PG8_MMA(0, 0, At, B0); PG8_MMA(0, 1, At, B1); PG8_BAR; PG8_SCHED;
;             PG8_LDA(At, 1, 1); PG8_STAGE(PG8_SB(1, 0), b3, voffB); PG8_STAGE(PG8_SB(1, 1), b3 + hstep, voffB); PG8_STAGE(PG8_SA(1, 0), a3, voffA);
;             PG8_WAIT_V(8); PG8_WAIT_L(0); PG8_BAR; PG8_MMA(1, 0, At, B0); PG8_MMA(1, 1, At, B1); PG8_BAR; PG8_SCHED;
.Lp1_skipb1_2:
	s_barrier
	s_add_i32 s46, s50, s66
	v_lshl_add_u64 v[156:157], v[156:157], 0, s[26:27]
	s_mov_b32 m0, s46
	ds_read_b128 v[206:209], v168 offset:49152
	ds_read_b128 v[210:213], v168 offset:50176
	ds_read_b128 v[214:217], v168 offset:51200
	ds_read_b128 v[218:221], v168 offset:52224
	ds_read_b128 v[222:225], v168 offset:53248
	ds_read_b128 v[226:229], v168 offset:54272
	ds_read_b128 v[230:233], v168 offset:55296
	ds_read_b128 v[234:237], v168 offset:56320
	global_load_lds_dwordx4 v[156:157], off
	s_add_i32 m0, s46, 0x2000
	s_add_u32 s12, s12, 0x80080
	v_lshl_add_u64 v[156:157], v[238:239], 0, s[26:27]
	s_addc_u32 s13, s13, 0
	s_add_i32 s46, s51, s66
	global_load_lds_dwordx4 v[156:157], off
	v_lshl_add_u64 v[156:157], s[12:13], 0, v[130:131]
	s_mov_b32 m0, s46
	s_nop 0
	global_load_lds_dwordx4 v[156:157], off
	v_lshl_add_u64 v[156:157], s[12:13], 0, v[134:135]
	s_add_i32 m0, s46, 0x2000
	s_nop 0
	global_load_lds_dwordx4 v[156:157], off
	v_lshl_add_u64 v[156:157], v[240:241], 0, s[26:27]
	s_mov_b32 m0, s95
	s_nop 0
	global_load_lds_dwordx4 v[156:157], off
	v_lshl_add_u64 v[156:157], v[242:243], 0, s[26:27]
	s_mov_b32 m0, s96
	s_nop 0
	global_load_lds_dwordx4 v[156:157], off
	s_waitcnt vmcnt(8)
	s_barrier
	s_setprio 1
	s_waitcnt lgkmcnt(0)
	v_mfma_f32_16x16x32_bf16 v[60:63], v[152:155], v[206:209], v[60:63]
	v_mfma_f32_16x16x32_bf16 v[56:59], v[182:185], v[206:209], v[56:59]
	v_mfma_f32_16x16x32_bf16 v[44:47], v[152:155], v[214:217], v[44:47]
	v_mfma_f32_16x16x32_bf16 v[40:43], v[182:185], v[214:217], v[40:43]
	v_mfma_f32_16x16x32_bf16 v[28:31], v[152:155], v[222:225], v[28:31]
	v_mfma_f32_16x16x32_bf16 v[24:27], v[182:185], v[222:225], v[24:27]
	v_mfma_f32_16x16x32_bf16 v[12:15], v[152:155], v[230:233], v[12:15]
	v_mfma_f32_16x16x32_bf16 v[8:11], v[182:185], v[230:233], v[8:11]
	v_mfma_f32_16x16x32_bf16 v[60:63], v[174:177], v[210:213], v[60:63]
	v_mfma_f32_16x16x32_bf16 v[56:59], v[186:189], v[210:213], v[56:59]
	v_mfma_f32_16x16x32_bf16 v[44:47], v[174:177], v[218:221], v[44:47]
	v_mfma_f32_16x16x32_bf16 v[40:43], v[186:189], v[218:221], v[40:43]
	v_mfma_f32_16x16x32_bf16 v[28:31], v[174:177], v[226:229], v[28:31]
	v_mfma_f32_16x16x32_bf16 v[24:27], v[186:189], v[226:229], v[24:27]
	v_mfma_f32_16x16x32_bf16 v[12:15], v[174:177], v[234:237], v[12:15]
	v_mfma_f32_16x16x32_bf16 v[8:11], v[186:189], v[234:237], v[8:11]
	s_setprio 0
	s_cmp_eq_u32 s14, 16
	s_cbranch_scc1 .Lp1_skipb1_3
	s_setprio 1
	v_mfma_f32_16x16x32_bf16 v[52:55], v[190:193], v[206:209], v[52:55]
	v_mfma_f32_16x16x32_bf16 v[48:51], v[198:201], v[206:209], v[48:51]
	v_mfma_f32_16x16x32_bf16 v[36:39], v[190:193], v[214:217], v[36:39]
	v_mfma_f32_16x16x32_bf16 v[32:35], v[198:201], v[214:217], v[32:35]
	v_mfma_f32_16x16x32_bf16 v[20:23], v[190:193], v[222:225], v[20:23]
	v_mfma_f32_16x16x32_bf16 v[16:19], v[198:201], v[222:225], v[16:19]
	v_mfma_f32_16x16x32_bf16 v[4:7], v[190:193], v[230:233], v[4:7]
	v_mfma_f32_16x16x32_bf16 v[0:3], v[198:201], v[230:233], v[0:3]
	v_mfma_f32_16x16x32_bf16 v[52:55], v[194:197], v[210:213], v[52:55]
	v_mfma_f32_16x16x32_bf16 v[48:51], v[202:205], v[210:213], v[48:51]
	v_mfma_f32_16x16x32_bf16 v[36:39], v[194:197], v[218:221], v[36:39]
	v_mfma_f32_16x16x32_bf16 v[32:35], v[202:205], v[218:221], v[32:35]
	v_mfma_f32_16x16x32_bf16 v[20:23], v[194:197], v[226:229], v[20:23]
	v_mfma_f32_16x16x32_bf16 v[16:19], v[202:205], v[226:229], v[16:19]
	v_mfma_f32_16x16x32_bf16 v[4:7], v[194:197], v[234:237], v[4:7]
	v_mfma_f32_16x16x32_bf16 v[0:3], v[202:205], v[234:237], v[0:3]
	s_setprio 0

; #define PG8_STAGE(bufoff, gbase, voff) do { _Pragma("unroll") for (int _i = 0; _i < 2; ++_i) \
;         __builtin_amdgcn_global_load_lds((const unsigned*)((const char*)(gbase) + (voff)[_i]), (PG8_LAS unsigned*)(lds + (bufoff) + ldsw + _i * 8192), 16, 0, 0); } while (0)
; #define PG8_LDA(dst, b, h) do { _Pragma("unroll") for (int m = 0; m < 4; ++m) _Pragma("unroll") for (int k = 0; k < 2; ++k) dst[m][k] = *(const PG8_LAS bf16x8*)(lds + PG8_SA(b, h) + aoff + m * 2048 + k * 1024); } while (0)
; #define PG8_LDB(dst, b, h) do { _Pragma("unroll") for (int n = 0; n < 2; ++n) _Pragma("unroll") for (int k = 0; k < 2; ++k) dst[n][k] = *(const PG8_LAS bf16x8*)(lds + PG8_SB(b, h) + boff + n * 2048 + k * 1024); } while (0)
; #define PG8_MMA(ai, bj, At, Bt) do { __builtin_amdgcn_s_setprio(1); _Pragma("unroll") for (int m = 0; m < 4; ++m) _Pragma("unroll") for (int n = 0; n < 2; ++n) _Pragma("unroll") for (int k = 0; k < 2; ++k) \
;         acc[ai][bj][m][n] = __builtin_amdgcn_mfma_f32_16x16x32_bf16(Bt[n][k], At[m][k], acc[ai][bj][m][n], 0, 0, 0); __builtin_amdgcn_s_setprio(0); } while (0)
; #define PG8_WAIT_V(n) asm volatile("s_waitcnt vmcnt(" #n ")" ::: "memory")
; #define PG8_WAIT_L(n) asm volatile("s_waitcnt lgkmcnt(" #n ")" ::: "memory")
; #define PG8_BAR __builtin_amdgcn_s_barrier()
; #define PG8_SCHED __builtin_amdgcn_sched_barrier(0)
; template <class Epi, class Sched, bool ALIGN_EPI = false, bool SP2 = false>
; __device__ __forceinline__ void gemm_phase(PG8_LAS unsigned char* lds, const Gemm g, const Sched& S, const Epi& E) {
;     ...
;             PG8_LDB(B0, 0, 0); PG8_LDB(B1, 0, 1); PG8_SCHED; PG8_LDA(At, 0, 0); PG8_STAGE(PG8_SA(1, 1), a1 + hstep, voffA);
;             PG8_WAIT_V(8); PG8_WAIT_L(0); PG8_BAR; PG8_MMA(0, 0, At, B0); PG8_MMA(0, 1, At, B1); PG8_BAR; PG8_SCHED;
;             PG8_LDA(At, 0, 1); PG8_STAGE(PG8_SB(0, 0), b2, voffB); PG8_STAGE(PG8_SB(0, 1), b2 + hstep, voffB); PG8_STAGE(PG8_SA(0, 0), a2, voffA);
;             PG8_WAIT_V(8); PG8_WAIT_L(0); PG8_BAR; PG8_MMA(1, 0, At, B0); PG8_MMA(1, 1, At, B1); PG8_BAR; PG8_SCHED;
.LBB0_567:
	ds_read_b128 v[144:147], v158
	ds_read_b128 v[148:151], v158 offset:1024
	ds_read_b128 v[162:165], v158 offset:2048
	ds_read_b128 v[168:171], v158 offset:3072
	ds_read_b128 v[172:175], v159
	ds_read_b128 v[182:185], v159 offset:1024
	ds_read_b128 v[186:189], v159 offset:2048
	ds_read_b128 v[190:193], v159 offset:3072
	s_add_u32 s36, s34, 0xfffe0080
	s_addc_u32 s37, s35, -1
	s_cmp_eq_u32 s66, 4
	s_cselect_b32 s39, s7, s37
	s_cselect_b32 s38, s25, s36
	s_cselect_b32 s37, s23, s65
	s_cselect_b32 s36, s31, s33
	v_lshl_add_u64 v[154:155], s[34:35], 0, v[136:137]
	s_add_i32 m0, s45, 0xc000
	ds_read_b128 v[194:197], v160
	ds_read_b128 v[198:201], v160 offset:1024
	ds_read_b128 v[202:205], v160 offset:2048
	ds_read_b128 v[206:209], v160 offset:3072
	ds_read_b128 v[210:213], v160 offset:4096
	ds_read_b128 v[214:217], v160 offset:5120
	ds_read_b128 v[218:221], v160 offset:6144
	ds_read_b128 v[222:225], v160 offset:7168
	global_load_lds_dwordx4 v[154:155], off
	v_lshl_add_u64 v[154:155], s[34:35], 0, v[138:139]
	s_add_i32 m0, s45, 0xe000
	s_nop 0
	global_load_lds_dwordx4 v[154:155], off
	s_waitcnt vmcnt(8)
	s_barrier
	s_setprio 1
	s_waitcnt lgkmcnt(0)
	v_mfma_f32_16x16x32_bf16 v[124:127], v[144:147], v[194:197], v[124:127]
	v_mfma_f32_16x16x32_bf16 v[120:123], v[162:165], v[194:197], v[120:123]
	v_mfma_f32_16x16x32_bf16 v[108:111], v[144:147], v[202:205], v[108:111]
	v_mfma_f32_16x16x32_bf16 v[104:107], v[162:165], v[202:205], v[104:107]
	v_mfma_f32_16x16x32_bf16 v[92:95], v[144:147], v[210:213], v[92:95]
	v_mfma_f32_16x16x32_bf16 v[88:91], v[162:165], v[210:213], v[88:91]
	v_mfma_f32_16x16x32_bf16 v[76:79], v[144:147], v[218:221], v[76:79]
	v_mfma_f32_16x16x32_bf16 v[72:75], v[162:165], v[218:221], v[72:75]
	v_mfma_f32_16x16x32_bf16 v[124:127], v[148:151], v[198:201], v[124:127]
	v_mfma_f32_16x16x32_bf16 v[120:123], v[168:171], v[198:201], v[120:123]
	v_mfma_f32_16x16x32_bf16 v[108:111], v[148:151], v[206:209], v[108:111]
	v_mfma_f32_16x16x32_bf16 v[104:107], v[168:171], v[206:209], v[104:107]
	v_mfma_f32_16x16x32_bf16 v[92:95], v[148:151], v[214:217], v[92:95]
	v_mfma_f32_16x16x32_bf16 v[88:91], v[168:171], v[214:217], v[88:91]
	v_mfma_f32_16x16x32_bf16 v[76:79], v[148:151], v[222:225], v[76:79]
	v_mfma_f32_16x16x32_bf16 v[72:75], v[168:171], v[222:225], v[72:75]
	s_setprio 0
	s_setprio 1
	v_mfma_f32_16x16x32_bf16 v[116:119], v[172:175], v[194:197], v[116:119]
	v_mfma_f32_16x16x32_bf16 v[112:115], v[186:189], v[194:197], v[112:115]
	v_mfma_f32_16x16x32_bf16 v[100:103], v[172:175], v[202:205], v[100:103]
	v_mfma_f32_16x16x32_bf16 v[96:99], v[186:189], v[202:205], v[96:99]
	v_mfma_f32_16x16x32_bf16 v[84:87], v[172:175], v[210:213], v[84:87]
	v_mfma_f32_16x16x32_bf16 v[80:83], v[186:189], v[210:213], v[80:83]
	v_mfma_f32_16x16x32_bf16 v[68:71], v[172:175], v[218:221], v[68:71]
	v_mfma_f32_16x16x32_bf16 v[64:67], v[186:189], v[218:221], v[64:67]
	v_mfma_f32_16x16x32_bf16 v[116:119], v[182:185], v[198:201], v[116:119]
	v_mfma_f32_16x16x32_bf16 v[112:115], v[190:193], v[198:201], v[112:115]
	v_mfma_f32_16x16x32_bf16 v[100:103], v[182:185], v[206:209], v[100:103]
	v_mfma_f32_16x16x32_bf16 v[96:99], v[190:193], v[206:209], v[96:99]
	v_mfma_f32_16x16x32_bf16 v[84:87], v[182:185], v[214:217], v[84:87]
	v_mfma_f32_16x16x32_bf16 v[80:83], v[190:193], v[214:217], v[80:83]
	v_mfma_f32_16x16x32_bf16 v[68:71], v[182:185], v[222:225], v[68:71]
	v_mfma_f32_16x16x32_bf16 v[64:67], v[190:193], v[222:225], v[64:67]
	s_setprio 0
	s_barrier
	s_add_i32 s67, s57, s44
	v_lshl_add_u64 v[154:155], s[36:37], 0, v[130:131]
	s_mov_b32 m0, s67
	ds_read_b128 v[194:197], v160 offset:16384
	ds_read_b128 v[198:201], v160 offset:17408
	ds_read_b128 v[202:205], v160 offset:18432
	ds_read_b128 v[206:209], v160 offset:19456
	ds_read_b128 v[210:213], v160 offset:20480
	ds_read_b128 v[214:217], v160 offset:21504
	ds_read_b128 v[218:221], v160 offset:22528
	ds_read_b128 v[222:225], v160 offset:23552
	global_load_lds_dwordx4 v[154:155], off
	s_add_i32 m0, s67, 0x2000
	s_add_u32 s68, s36, 0x20000
	v_lshl_add_u64 v[176:177], s[36:37], 0, v[134:135]
	s_addc_u32 s69, s37, 0
	s_add_i32 s67, s58, s44
	global_load_lds_dwordx4 v[176:177], off
	v_lshl_add_u64 v[226:227], s[68:69], 0, v[130:131]
	s_mov_b32 m0, s67
	v_lshl_add_u64 v[228:229], s[38:39], 0, v[132:133]
	global_load_lds_dwordx4 v[226:227], off
	v_lshl_add_u64 v[226:227], s[68:69], 0, v[134:135]
	s_add_i32 m0, s67, 0x2000
	s_nop 0
	global_load_lds_dwordx4 v[226:227], off
	v_lshl_add_u64 v[226:227], s[38:39], 0, v[128:129]
	s_mov_b32 m0, s45
	s_nop 0
	global_load_lds_dwordx4 v[226:227], off
	s_mov_b32 m0, s46
	s_nop 0
	global_load_lds_dwordx4 v[228:229], off
	s_waitcnt vmcnt(8)
	s_barrier
; #define PG8_STAGE(bufoff, gbase, voff) do { _Pragma("unroll") for (int _i = 0; _i < 2; ++_i) \
;         __builtin_amdgcn_global_load_lds((const unsigned*)((const char*)(gbase) + (voff)[_i]), (PG8_LAS unsigned*)(lds + (bufoff) + ldsw + _i * 8192), 16, 0, 0); } while (0)
; #define PG8_LDA(dst, b, h) do { _Pragma("unroll") for (int m = 0; m < 4; ++m) _Pragma("unroll") for (int k = 0; k < 2; ++k) dst[m][k] = *(const PG8_LAS bf16x8*)(lds + PG8_SA(b, h) + aoff + m * 2048 + k * 1024); } while (0)
; #define PG8_LDB(dst, b, h) do { _Pragma("unroll") for (int n = 0; n < 2; ++n) _Pragma("unroll") for (int k = 0; k < 2; ++k) dst[n][k] = *(const PG8_LAS bf16x8*)(lds + PG8_SB(b, h) + boff + n * 2048 + k * 1024); } while (0)
; #define PG8_MMA(ai, bj, At, Bt) do { __builtin_amdgcn_s_setprio(1); _Pragma("unroll") for (int m = 0; m < 4; ++m) _Pragma("unroll") for (int n = 0; n < 2; ++n) _Pragma("unroll") for (int k = 0; k < 2; ++k) \
;         acc[ai][bj][m][n] = __builtin_amdgcn_mfma_f32_16x16x32_bf16(Bt[n][k], At[m][k], acc[ai][bj][m][n], 0, 0, 0); __builtin_amdgcn_s_setprio(0); } while (0)
; #define PG8_WAIT_V(n) asm volatile("s_waitcnt vmcnt(" #n ")" ::: "memory")
; #define PG8_WAIT_L(n) asm volatile("s_waitcnt lgkmcnt(" #n ")" ::: "memory")
; #define PG8_BAR __builtin_amdgcn_s_barrier()
; #define PG8_SCHED __builtin_amdgcn_sched_barrier(0)
; template <class Epi, class Sched, bool ALIGN_EPI = false, bool SP2 = false>
; __device__ __forceinline__ void gemm_phase(PG8_LAS unsigned char* lds, const Gemm g, const Sched& S, const Epi& E) {
;     ...
;             PG8_WAIT_V(8); PG8_WAIT_L(0); PG8_BAR; PG8_MMA(1, 0, At, B0); PG8_MMA(1, 1, At, B1); PG8_BAR; PG8_SCHED;
;             PG8_LDB(B0, 1, 0); PG8_LDB(B1, 1, 1); PG8_SCHED; PG8_LDA(At, 1, 0); PG8_STAGE(PG8_SA(0, 1), a2 + hstep, voffA);
;             PG8_WAIT_V(8); PG8_WAIT_L(0); PG8_BAR; PG8_MMA(0, 0, At, B0); PG8_MMA(0, 1, At, B1); PG8_BAR; PG8_SCHED;
;             PG8_LDA(At, 1, 1); PG8_STAGE(PG8_SB(1, 0), b3, voffB); PG8_STAGE(PG8_SB(1, 1), b3 + hstep, voffB); PG8_STAGE(PG8_SA(1, 0), a3, voffA);
	s_setprio 1
	s_waitcnt lgkmcnt(0)
	v_mfma_f32_16x16x32_bf16 v[60:63], v[144:147], v[194:197], v[60:63]
	v_mfma_f32_16x16x32_bf16 v[56:59], v[162:165], v[194:197], v[56:59]
	v_mfma_f32_16x16x32_bf16 v[44:47], v[144:147], v[202:205], v[44:47]
	v_mfma_f32_16x16x32_bf16 v[40:43], v[162:165], v[202:205], v[40:43]
	v_mfma_f32_16x16x32_bf16 v[28:31], v[144:147], v[210:213], v[28:31]
	v_mfma_f32_16x16x32_bf16 v[24:27], v[162:165], v[210:213], v[24:27]
	v_mfma_f32_16x16x32_bf16 v[12:15], v[144:147], v[218:221], v[12:15]
	v_mfma_f32_16x16x32_bf16 v[8:11], v[162:165], v[218:221], v[8:11]
	v_mfma_f32_16x16x32_bf16 v[60:63], v[148:151], v[198:201], v[60:63]
	v_mfma_f32_16x16x32_bf16 v[56:59], v[168:171], v[198:201], v[56:59]
	v_mfma_f32_16x16x32_bf16 v[44:47], v[148:151], v[206:209], v[44:47]
	v_mfma_f32_16x16x32_bf16 v[40:43], v[168:171], v[206:209], v[40:43]
	v_mfma_f32_16x16x32_bf16 v[28:31], v[148:151], v[214:217], v[28:31]
	v_mfma_f32_16x16x32_bf16 v[24:27], v[168:171], v[214:217], v[24:27]
	v_mfma_f32_16x16x32_bf16 v[12:15], v[148:151], v[222:225], v[12:15]
	v_mfma_f32_16x16x32_bf16 v[8:11], v[168:171], v[222:225], v[8:11]
	s_setprio 0
	s_setprio 1
	v_mfma_f32_16x16x32_bf16 v[52:55], v[172:175], v[194:197], v[52:55]
	v_mfma_f32_16x16x32_bf16 v[48:51], v[186:189], v[194:197], v[48:51]
	v_mfma_f32_16x16x32_bf16 v[36:39], v[172:175], v[202:205], v[36:39]
	v_mfma_f32_16x16x32_bf16 v[32:35], v[186:189], v[202:205], v[32:35]
	v_mfma_f32_16x16x32_bf16 v[20:23], v[172:175], v[210:213], v[20:23]
	v_mfma_f32_16x16x32_bf16 v[16:19], v[186:189], v[210:213], v[16:19]
	v_mfma_f32_16x16x32_bf16 v[4:7], v[172:175], v[218:221], v[4:7]
	v_mfma_f32_16x16x32_bf16 v[0:3], v[186:189], v[218:221], v[0:3]
	v_mfma_f32_16x16x32_bf16 v[52:55], v[182:185], v[198:201], v[52:55]
	v_mfma_f32_16x16x32_bf16 v[48:51], v[190:193], v[198:201], v[48:51]
	v_mfma_f32_16x16x32_bf16 v[36:39], v[182:185], v[206:209], v[36:39]
	v_mfma_f32_16x16x32_bf16 v[32:35], v[190:193], v[206:209], v[32:35]
	v_mfma_f32_16x16x32_bf16 v[20:23], v[182:185], v[214:217], v[20:23]
	v_mfma_f32_16x16x32_bf16 v[16:19], v[190:193], v[214:217], v[16:19]
	v_mfma_f32_16x16x32_bf16 v[4:7], v[182:185], v[222:225], v[4:7]
	v_mfma_f32_16x16x32_bf16 v[0:3], v[190:193], v[222:225], v[0:3]
	s_setprio 0
	s_barrier
	s_add_i32 s67, 0, 0x18000
	v_add_u32_e32 v152, s67, v156
	s_add_i32 s68, 0, 0x1c000
	ds_read_b128 v[144:147], v152
	ds_read_b128 v[148:151], v152 offset:1024
	ds_read_b128 v[162:165], v152 offset:2048
	ds_read_b128 v[168:171], v152 offset:3072
	v_add_u32_e32 v152, s68, v156
	ds_read_b128 v[172:175], v152
	ds_read_b128 v[182:185], v152 offset:1024
	ds_read_b128 v[186:189], v152 offset:2048
	ds_read_b128 v[190:193], v152 offset:3072
	s_add_u32 s38, s38, 0x20000
	s_addc_u32 s39, s39, 0
	s_mov_b32 m0, s47
	v_lshl_add_u64 v[230:231], s[38:39], 0, v[128:129]
	ds_read_b128 v[194:197], v160 offset:32768
	ds_read_b128 v[198:201], v160 offset:33792
	ds_read_b128 v[202:205], v160 offset:34816
	ds_read_b128 v[206:209], v160 offset:35840
	ds_read_b128 v[210:213], v160 offset:36864
	ds_read_b128 v[214:217], v160 offset:37888
	ds_read_b128 v[218:221], v160 offset:38912
	ds_read_b128 v[222:225], v160 offset:39936
	global_load_lds_dwordx4 v[230:231], off
	v_lshl_add_u64 v[230:231], s[38:39], 0, v[132:133]
	s_mov_b32 m0, s48
	s_nop 0
	global_load_lds_dwordx4 v[230:231], off
	s_waitcnt vmcnt(8)
	s_barrier
	s_setprio 1
	s_waitcnt lgkmcnt(0)
	v_mfma_f32_16x16x32_bf16 v[124:127], v[144:147], v[194:197], v[124:127]
	v_mfma_f32_16x16x32_bf16 v[120:123], v[162:165], v[194:197], v[120:123]
	v_mfma_f32_16x16x32_bf16 v[108:111], v[144:147], v[202:205], v[108:111]
	v_mfma_f32_16x16x32_bf16 v[104:107], v[162:165], v[202:205], v[104:107]
	v_mfma_f32_16x16x32_bf16 v[92:95], v[144:147], v[210:213], v[92:95]
	v_mfma_f32_16x16x32_bf16 v[88:91], v[162:165], v[210:213], v[88:91]
	v_mfma_f32_16x16x32_bf16 v[76:79], v[144:147], v[218:221], v[76:79]
	v_mfma_f32_16x16x32_bf16 v[72:75], v[162:165], v[218:221], v[72:75]
	v_mfma_f32_16x16x32_bf16 v[124:127], v[148:151], v[198:201], v[124:127]
	v_mfma_f32_16x16x32_bf16 v[120:123], v[168:171], v[198:201], v[120:123]
	v_mfma_f32_16x16x32_bf16 v[108:111], v[148:151], v[206:209], v[108:111]
	v_mfma_f32_16x16x32_bf16 v[104:107], v[168:171], v[206:209], v[104:107]
	v_mfma_f32_16x16x32_bf16 v[92:95], v[148:151], v[214:217], v[92:95]
	v_mfma_f32_16x16x32_bf16 v[88:91], v[168:171], v[214:217], v[88:91]
	v_mfma_f32_16x16x32_bf16 v[76:79], v[148:151], v[222:225], v[76:79]
	v_mfma_f32_16x16x32_bf16 v[72:75], v[168:171], v[222:225], v[72:75]
	s_setprio 0
	s_setprio 1
	v_mfma_f32_16x16x32_bf16 v[116:119], v[172:175], v[194:197], v[116:119]
	v_mfma_f32_16x16x32_bf16 v[112:115], v[186:189], v[194:197], v[112:115]
	v_mfma_f32_16x16x32_bf16 v[100:103], v[172:175], v[202:205], v[100:103]
	v_mfma_f32_16x16x32_bf16 v[96:99], v[186:189], v[202:205], v[96:99]
	v_mfma_f32_16x16x32_bf16 v[84:87], v[172:175], v[210:213], v[84:87]
	v_mfma_f32_16x16x32_bf16 v[80:83], v[186:189], v[210:213], v[80:83]
	v_mfma_f32_16x16x32_bf16 v[68:71], v[172:175], v[218:221], v[68:71]
	v_mfma_f32_16x16x32_bf16 v[64:67], v[186:189], v[218:221], v[64:67]
	v_mfma_f32_16x16x32_bf16 v[116:119], v[182:185], v[198:201], v[116:119]
	v_mfma_f32_16x16x32_bf16 v[112:115], v[190:193], v[198:201], v[112:115]
	v_mfma_f32_16x16x32_bf16 v[100:103], v[182:185], v[206:209], v[100:103]
	v_mfma_f32_16x16x32_bf16 v[96:99], v[190:193], v[206:209], v[96:99]
	v_mfma_f32_16x16x32_bf16 v[84:87], v[182:185], v[214:217], v[84:87]
	v_mfma_f32_16x16x32_bf16 v[80:83], v[190:193], v[214:217], v[80:83]
	v_mfma_f32_16x16x32_bf16 v[68:71], v[182:185], v[222:225], v[68:71]
	v_mfma_f32_16x16x32_bf16 v[64:67], v[190:193], v[222:225], v[64:67]
	s_setprio 0
	s_barrier
; #define PG8_STAGE(bufoff, gbase, voff) do { _Pragma("unroll") for (int _i = 0; _i < 2; ++_i) \
;         __builtin_amdgcn_global_load_lds((const unsigned*)((const char*)(gbase) + (voff)[_i]), (PG8_LAS unsigned*)(lds + (bufoff) + ldsw + _i * 8192), 16, 0, 0); } while (0)
; #define PG8_LDA(dst, b, h) do { _Pragma("unroll") for (int m = 0; m < 4; ++m) _Pragma("unroll") for (int k = 0; k < 2; ++k) dst[m][k] = *(const PG8_LAS bf16x8*)(lds + PG8_SA(b, h) + aoff + m * 2048 + k * 1024); } while (0)
; #define PG8_MMA(ai, bj, At, Bt) do { __builtin_amdgcn_s_setprio(1); _Pragma("unroll") for (int m = 0; m < 4; ++m) _Pragma("unroll") for (int n = 0; n < 2; ++n) _Pragma("unroll") for (int k = 0; k < 2; ++k) \
;         acc[ai][bj][m][n] = __builtin_amdgcn_mfma_f32_16x16x32_bf16(Bt[n][k], At[m][k], acc[ai][bj][m][n], 0, 0, 0); __builtin_amdgcn_s_setprio(0); } while (0)
; #define PG8_WAIT_V(n) asm volatile("s_waitcnt vmcnt(" #n ")" ::: "memory")
; #define PG8_WAIT_L(n) asm volatile("s_waitcnt lgkmcnt(" #n ")" ::: "memory")
; #define PG8_BAR __builtin_amdgcn_s_barrier()
; #define PG8_SCHED __builtin_amdgcn_sched_barrier(0)
; template <class Epi, class Sched, bool ALIGN_EPI = false, bool SP2 = false>
; __device__ __forceinline__ void gemm_phase(PG8_LAS unsigned char* lds, const Gemm g, const Sched& S, const Epi& E) {
;     ...
;             PG8_LDA(At, 1, 1); PG8_STAGE(PG8_SB(1, 0), b3, voffB); PG8_STAGE(PG8_SB(1, 1), b3 + hstep, voffB); PG8_STAGE(PG8_SA(1, 0), a3, voffA);
;             PG8_WAIT_V(8); PG8_WAIT_L(0); PG8_BAR; PG8_MMA(1, 0, At, B0); PG8_MMA(1, 1, At, B1); PG8_BAR; PG8_SCHED;
;     ...
;         if constexpr (ALIGN_EPI) { if (wr == 0) PG8_BAR; }
	s_add_i32 s38, s67, s44
	v_lshl_add_u64 v[154:155], v[154:155], 0, s[16:17]
	s_mov_b32 m0, s38
	ds_read_b128 v[194:197], v160 offset:49152
	ds_read_b128 v[198:201], v160 offset:50176
	ds_read_b128 v[202:205], v160 offset:51200
	ds_read_b128 v[206:209], v160 offset:52224
	ds_read_b128 v[210:213], v160 offset:53248
	ds_read_b128 v[214:217], v160 offset:54272
	ds_read_b128 v[218:221], v160 offset:55296
	ds_read_b128 v[222:225], v160 offset:56320
	global_load_lds_dwordx4 v[154:155], off
	s_add_i32 m0, s38, 0x2000
	s_add_u32 s36, s36, 0x20080
	v_lshl_add_u64 v[154:155], v[176:177], 0, s[16:17]
	s_addc_u32 s37, s37, 0
	s_add_i32 s38, s68, s44
	global_load_lds_dwordx4 v[154:155], off
	v_lshl_add_u64 v[154:155], s[36:37], 0, v[130:131]
	s_mov_b32 m0, s38
	s_nop 0
	global_load_lds_dwordx4 v[154:155], off
	v_lshl_add_u64 v[154:155], s[36:37], 0, v[134:135]
	s_add_i32 m0, s38, 0x2000
	s_nop 0
	global_load_lds_dwordx4 v[154:155], off
	v_lshl_add_u64 v[154:155], v[226:227], 0, s[16:17]
	s_mov_b32 m0, s51
	s_nop 0
	global_load_lds_dwordx4 v[154:155], off
	v_lshl_add_u64 v[154:155], v[228:229], 0, s[16:17]
	s_mov_b32 m0, s52
	s_nop 0
	global_load_lds_dwordx4 v[154:155], off
	s_waitcnt vmcnt(8)
	s_barrier
	s_setprio 1
	s_waitcnt lgkmcnt(0)
	v_mfma_f32_16x16x32_bf16 v[60:63], v[144:147], v[194:197], v[60:63]
	v_mfma_f32_16x16x32_bf16 v[56:59], v[162:165], v[194:197], v[56:59]
	v_mfma_f32_16x16x32_bf16 v[44:47], v[144:147], v[202:205], v[44:47]
	v_mfma_f32_16x16x32_bf16 v[40:43], v[162:165], v[202:205], v[40:43]
	v_mfma_f32_16x16x32_bf16 v[28:31], v[144:147], v[210:213], v[28:31]
	v_mfma_f32_16x16x32_bf16 v[24:27], v[162:165], v[210:213], v[24:27]
	v_mfma_f32_16x16x32_bf16 v[12:15], v[144:147], v[218:221], v[12:15]
	v_mfma_f32_16x16x32_bf16 v[8:11], v[162:165], v[218:221], v[8:11]
	v_mfma_f32_16x16x32_bf16 v[60:63], v[148:151], v[198:201], v[60:63]
	v_mfma_f32_16x16x32_bf16 v[56:59], v[168:171], v[198:201], v[56:59]
	v_mfma_f32_16x16x32_bf16 v[44:47], v[148:151], v[206:209], v[44:47]
	v_mfma_f32_16x16x32_bf16 v[40:43], v[168:171], v[206:209], v[40:43]
	v_mfma_f32_16x16x32_bf16 v[28:31], v[148:151], v[214:217], v[28:31]
	v_mfma_f32_16x16x32_bf16 v[24:27], v[168:171], v[214:217], v[24:27]
	v_mfma_f32_16x16x32_bf16 v[12:15], v[148:151], v[222:225], v[12:15]
	v_mfma_f32_16x16x32_bf16 v[8:11], v[168:171], v[222:225], v[8:11]
	s_setprio 0
	s_setprio 1
	v_mfma_f32_16x16x32_bf16 v[52:55], v[172:175], v[194:197], v[52:55]
	v_mfma_f32_16x16x32_bf16 v[48:51], v[186:189], v[194:197], v[48:51]
	v_mfma_f32_16x16x32_bf16 v[36:39], v[172:175], v[202:205], v[36:39]
	v_mfma_f32_16x16x32_bf16 v[32:35], v[186:189], v[202:205], v[32:35]
	v_mfma_f32_16x16x32_bf16 v[20:23], v[172:175], v[210:213], v[20:23]
	v_mfma_f32_16x16x32_bf16 v[16:19], v[186:189], v[210:213], v[16:19]
	v_mfma_f32_16x16x32_bf16 v[4:7], v[172:175], v[218:221], v[4:7]
	v_mfma_f32_16x16x32_bf16 v[0:3], v[186:189], v[218:221], v[0:3]
	v_mfma_f32_16x16x32_bf16 v[52:55], v[182:185], v[198:201], v[52:55]
	v_mfma_f32_16x16x32_bf16 v[48:51], v[190:193], v[198:201], v[48:51]
	v_mfma_f32_16x16x32_bf16 v[36:39], v[182:185], v[206:209], v[36:39]
	v_mfma_f32_16x16x32_bf16 v[32:35], v[190:193], v[206:209], v[32:35]
	v_mfma_f32_16x16x32_bf16 v[20:23], v[182:185], v[214:217], v[20:23]
	v_mfma_f32_16x16x32_bf16 v[16:19], v[190:193], v[214:217], v[16:19]
	v_mfma_f32_16x16x32_bf16 v[4:7], v[182:185], v[222:225], v[4:7]
	v_mfma_f32_16x16x32_bf16 v[0:3], v[190:193], v[222:225], v[0:3]
	s_setprio 0
	s_barrier
	s_add_i32 s66, s66, 2
	s_add_u32 s34, s34, 0x100
	s_addc_u32 s35, s35, 0
	s_add_u32 s33, s33, 0x100
	s_addc_u32 s65, s65, 0
	s_cmp_gt_u32 s66, 5
	s_cbranch_scc0 .LBB0_567
	s_and_b64 vcc, exec, s[18:19]
	s_cbranch_vccz .LBB0_570
	s_barrier

; #define PG8_STAGE(bufoff, gbase, voff) do { _Pragma("unroll") for (int _i = 0; _i < 2; ++_i) \
;         __builtin_amdgcn_global_load_lds((const unsigned*)((const char*)(gbase) + (voff)[_i]), (PG8_LAS unsigned*)(lds + (bufoff) + ldsw + _i * 8192), 16, 0, 0); } while (0)
; #define PG8_LDA(dst, b, h) do { _Pragma("unroll") for (int m = 0; m < 4; ++m) _Pragma("unroll") for (int k = 0; k < 2; ++k) dst[m][k] = *(const PG8_LAS bf16x8*)(lds + PG8_SA(b, h) + aoff + m * 2048 + k * 1024); } while (0)
; #define PG8_LDB(dst, b, h) do { _Pragma("unroll") for (int n = 0; n < 2; ++n) _Pragma("unroll") for (int k = 0; k < 2; ++k) dst[n][k] = *(const PG8_LAS bf16x8*)(lds + PG8_SB(b, h) + boff + n * 2048 + k * 1024); } while (0)
; #define PG8_MMA(ai, bj, At, Bt) do { __builtin_amdgcn_s_setprio(1); _Pragma("unroll") for (int m = 0; m < 4; ++m) _Pragma("unroll") for (int n = 0; n < 2; ++n) _Pragma("unroll") for (int k = 0; k < 2; ++k) \
;         acc[ai][bj][m][n] = __builtin_amdgcn_mfma_f32_16x16x32_bf16(Bt[n][k], At[m][k], acc[ai][bj][m][n], 0, 0, 0); __builtin_amdgcn_s_setprio(0); } while (0)
; #define PG8_WAIT_V(n) asm volatile("s_waitcnt vmcnt(" #n ")" ::: "memory")
; #define PG8_WAIT_L(n) asm volatile("s_waitcnt lgkmcnt(" #n ")" ::: "memory")
; #define PG8_BAR __builtin_amdgcn_s_barrier()
; #define PG8_SCHED __builtin_amdgcn_sched_barrier(0)
; template <class Epi, class Sched, bool ALIGN_EPI = false, bool SP2 = false>
; __device__ __forceinline__ void gemm_phase(PG8_LAS unsigned char* lds, const Gemm g, const Sched& S, const Epi& E) {
;     ...
;             PG8_LDB(B0, 0, 0); PG8_LDB(B1, 0, 1); PG8_SCHED; PG8_LDA(At, 0, 0); PG8_STAGE(PG8_SA(1, 1), a1 + hstep, voffA);
;             PG8_WAIT_V(8); PG8_WAIT_L(0); PG8_BAR; PG8_MMA(0, 0, At, B0); PG8_MMA(0, 1, At, B1); PG8_BAR; PG8_SCHED;
;             PG8_LDA(At, 0, 1); PG8_STAGE(PG8_SB(0, 0), b2, voffB); PG8_STAGE(PG8_SB(0, 1), b2 + hstep, voffB); PG8_STAGE(PG8_SA(0, 0), a2, voffA);
;             PG8_WAIT_V(8); PG8_WAIT_L(0); PG8_BAR; PG8_MMA(1, 0, At, B0); PG8_MMA(1, 1, At, B1); PG8_BAR; PG8_SCHED;
.LBB0_623:
	ds_read_b128 v[158:161], v152
	ds_read_b128 v[162:165], v152 offset:1024
	ds_read_b128 v[168:171], v152 offset:2048
	ds_read_b128 v[172:175], v152 offset:3072
	ds_read_b128 v[182:185], v153
	ds_read_b128 v[186:189], v153 offset:1024
	ds_read_b128 v[190:193], v153 offset:2048
	ds_read_b128 v[194:197], v153 offset:3072
	s_add_u32 s26, s24, 0xfffe0080
	s_addc_u32 s27, s25, -1
	s_cmp_eq_u32 s55, 4
	s_cselect_b32 s29, s17, s27
	s_cselect_b32 s28, s51, s26
	s_cselect_b32 s27, s15, s54
	s_cselect_b32 s26, s52, s53
	v_lshl_add_u64 v[148:149], s[24:25], 0, v[140:141]
	s_add_i32 m0, s23, 0xc000
	ds_read_b128 v[198:201], v154
	ds_read_b128 v[202:205], v154 offset:1024
	ds_read_b128 v[206:209], v154 offset:2048
	ds_read_b128 v[210:213], v154 offset:3072
	ds_read_b128 v[214:217], v154 offset:4096
	ds_read_b128 v[218:221], v154 offset:5120
	ds_read_b128 v[222:225], v154 offset:6144
	ds_read_b128 v[226:229], v154 offset:7168
	global_load_lds_dwordx4 v[148:149], off
	v_lshl_add_u64 v[148:149], s[24:25], 0, v[142:143]
	s_add_i32 m0, s23, 0xe000
	s_nop 0
	global_load_lds_dwordx4 v[148:149], off
	s_waitcnt vmcnt(8)
	s_barrier
	s_setprio 1
	s_waitcnt lgkmcnt(0)
	v_mfma_f32_16x16x32_bf16 v[124:127], v[158:161], v[198:201], v[124:127]
	v_mfma_f32_16x16x32_bf16 v[120:123], v[168:171], v[198:201], v[120:123]
	v_mfma_f32_16x16x32_bf16 v[108:111], v[158:161], v[206:209], v[108:111]
	v_mfma_f32_16x16x32_bf16 v[104:107], v[168:171], v[206:209], v[104:107]
	v_mfma_f32_16x16x32_bf16 v[92:95], v[158:161], v[214:217], v[92:95]
	v_mfma_f32_16x16x32_bf16 v[88:91], v[168:171], v[214:217], v[88:91]
	v_mfma_f32_16x16x32_bf16 v[76:79], v[158:161], v[222:225], v[76:79]
	v_mfma_f32_16x16x32_bf16 v[72:75], v[168:171], v[222:225], v[72:75]
	v_mfma_f32_16x16x32_bf16 v[124:127], v[162:165], v[202:205], v[124:127]
	v_mfma_f32_16x16x32_bf16 v[120:123], v[172:175], v[202:205], v[120:123]
	v_mfma_f32_16x16x32_bf16 v[108:111], v[162:165], v[210:213], v[108:111]
	v_mfma_f32_16x16x32_bf16 v[104:107], v[172:175], v[210:213], v[104:107]
	v_mfma_f32_16x16x32_bf16 v[92:95], v[162:165], v[218:221], v[92:95]
	v_mfma_f32_16x16x32_bf16 v[88:91], v[172:175], v[218:221], v[88:91]
	v_mfma_f32_16x16x32_bf16 v[76:79], v[162:165], v[226:229], v[76:79]
	v_mfma_f32_16x16x32_bf16 v[72:75], v[172:175], v[226:229], v[72:75]
	s_setprio 0
	s_setprio 1
	v_mfma_f32_16x16x32_bf16 v[116:119], v[182:185], v[198:201], v[116:119]
	v_mfma_f32_16x16x32_bf16 v[112:115], v[190:193], v[198:201], v[112:115]
	v_mfma_f32_16x16x32_bf16 v[100:103], v[182:185], v[206:209], v[100:103]
	v_mfma_f32_16x16x32_bf16 v[96:99], v[190:193], v[206:209], v[96:99]
	v_mfma_f32_16x16x32_bf16 v[84:87], v[182:185], v[214:217], v[84:87]
	v_mfma_f32_16x16x32_bf16 v[80:83], v[190:193], v[214:217], v[80:83]
	v_mfma_f32_16x16x32_bf16 v[68:71], v[182:185], v[222:225], v[68:71]
	v_mfma_f32_16x16x32_bf16 v[64:67], v[190:193], v[222:225], v[64:67]
	v_mfma_f32_16x16x32_bf16 v[116:119], v[186:189], v[202:205], v[116:119]
	v_mfma_f32_16x16x32_bf16 v[112:115], v[194:197], v[202:205], v[112:115]
	v_mfma_f32_16x16x32_bf16 v[100:103], v[186:189], v[210:213], v[100:103]
	v_mfma_f32_16x16x32_bf16 v[96:99], v[194:197], v[210:213], v[96:99]
	v_mfma_f32_16x16x32_bf16 v[84:87], v[186:189], v[218:221], v[84:87]
	v_mfma_f32_16x16x32_bf16 v[80:83], v[194:197], v[218:221], v[80:83]
	v_mfma_f32_16x16x32_bf16 v[68:71], v[186:189], v[226:229], v[68:71]
	v_mfma_f32_16x16x32_bf16 v[64:67], v[194:197], v[226:229], v[64:67]
	s_setprio 0
	s_barrier
	s_add_i32 s56, s45, s36
	v_lshl_add_u64 v[148:149], s[26:27], 0, v[130:131]
	s_mov_b32 m0, s56
	ds_read_b128 v[198:201], v154 offset:16384
	ds_read_b128 v[202:205], v154 offset:17408
	ds_read_b128 v[206:209], v154 offset:18432
	ds_read_b128 v[210:213], v154 offset:19456
	ds_read_b128 v[214:217], v154 offset:20480
	ds_read_b128 v[218:221], v154 offset:21504
	ds_read_b128 v[222:225], v154 offset:22528
	ds_read_b128 v[226:229], v154 offset:23552
	global_load_lds_dwordx4 v[148:149], off
	s_add_i32 m0, s56, 0x2000
	s_add_u32 s56, s26, 0x20000
	v_lshl_add_u64 v[176:177], s[26:27], 0, v[134:135]
	s_addc_u32 s57, s27, 0
	s_add_i32 s58, s46, s36
	global_load_lds_dwordx4 v[176:177], off
	v_lshl_add_u64 v[230:231], s[56:57], 0, v[130:131]
	s_mov_b32 m0, s58
	v_lshl_add_u64 v[232:233], s[28:29], 0, v[132:133]
	global_load_lds_dwordx4 v[230:231], off
	v_lshl_add_u64 v[230:231], s[56:57], 0, v[134:135]
	s_add_i32 m0, s58, 0x2000
	s_nop 0
	global_load_lds_dwordx4 v[230:231], off
	v_lshl_add_u64 v[230:231], s[28:29], 0, v[128:129]
	s_mov_b32 m0, s23
	s_nop 0
	global_load_lds_dwordx4 v[230:231], off
	s_mov_b32 m0, s37
	s_nop 0
	global_load_lds_dwordx4 v[232:233], off
	s_waitcnt vmcnt(8)
	s_barrier
; #define PG8_STAGE(bufoff, gbase, voff) do { _Pragma("unroll") for (int _i = 0; _i < 2; ++_i) \
;         __builtin_amdgcn_global_load_lds((const unsigned*)((const char*)(gbase) + (voff)[_i]), (PG8_LAS unsigned*)(lds + (bufoff) + ldsw + _i * 8192), 16, 0, 0); } while (0)
; #define PG8_LDA(dst, b, h) do { _Pragma("unroll") for (int m = 0; m < 4; ++m) _Pragma("unroll") for (int k = 0; k < 2; ++k) dst[m][k] = *(const PG8_LAS bf16x8*)(lds + PG8_SA(b, h) + aoff + m * 2048 + k * 1024); } while (0)
; #define PG8_LDB(dst, b, h) do { _Pragma("unroll") for (int n = 0; n < 2; ++n) _Pragma("unroll") for (int k = 0; k < 2; ++k) dst[n][k] = *(const PG8_LAS bf16x8*)(lds + PG8_SB(b, h) + boff + n * 2048 + k * 1024); } while (0)
; #define PG8_MMA(ai, bj, At, Bt) do { __builtin_amdgcn_s_setprio(1); _Pragma("unroll") for (int m = 0; m < 4; ++m) _Pragma("unroll") for (int n = 0; n < 2; ++n) _Pragma("unroll") for (int k = 0; k < 2; ++k) \
;         acc[ai][bj][m][n] = __builtin_amdgcn_mfma_f32_16x16x32_bf16(Bt[n][k], At[m][k], acc[ai][bj][m][n], 0, 0, 0); __builtin_amdgcn_s_setprio(0); } while (0)
; #define PG8_WAIT_V(n) asm volatile("s_waitcnt vmcnt(" #n ")" ::: "memory")
; #define PG8_WAIT_L(n) asm volatile("s_waitcnt lgkmcnt(" #n ")" ::: "memory")
; #define PG8_BAR __builtin_amdgcn_s_barrier()
; #define PG8_SCHED __builtin_amdgcn_sched_barrier(0)
; template <class Epi, class Sched, bool ALIGN_EPI = false, bool SP2 = false>
; __device__ __forceinline__ void gemm_phase(PG8_LAS unsigned char* lds, const Gemm g, const Sched& S, const Epi& E) {
;     ...
;             PG8_WAIT_V(8); PG8_WAIT_L(0); PG8_BAR; PG8_MMA(1, 0, At, B0); PG8_MMA(1, 1, At, B1); PG8_BAR; PG8_SCHED;
;             PG8_LDB(B0, 1, 0); PG8_LDB(B1, 1, 1); PG8_SCHED; PG8_LDA(At, 1, 0); PG8_STAGE(PG8_SA(0, 1), a2 + hstep, voffA);
;             PG8_WAIT_V(8); PG8_WAIT_L(0); PG8_BAR; PG8_MMA(0, 0, At, B0); PG8_MMA(0, 1, At, B1); PG8_BAR; PG8_SCHED;
	s_setprio 1
	s_waitcnt lgkmcnt(0)
	v_mfma_f32_16x16x32_bf16 v[60:63], v[158:161], v[198:201], v[60:63]
	v_mfma_f32_16x16x32_bf16 v[56:59], v[168:171], v[198:201], v[56:59]
	v_mfma_f32_16x16x32_bf16 v[44:47], v[158:161], v[206:209], v[44:47]
	v_mfma_f32_16x16x32_bf16 v[40:43], v[168:171], v[206:209], v[40:43]
	v_mfma_f32_16x16x32_bf16 v[28:31], v[158:161], v[214:217], v[28:31]
	v_mfma_f32_16x16x32_bf16 v[24:27], v[168:171], v[214:217], v[24:27]
	v_mfma_f32_16x16x32_bf16 v[12:15], v[158:161], v[222:225], v[12:15]
	v_mfma_f32_16x16x32_bf16 v[8:11], v[168:171], v[222:225], v[8:11]
	v_mfma_f32_16x16x32_bf16 v[60:63], v[162:165], v[202:205], v[60:63]
	v_mfma_f32_16x16x32_bf16 v[56:59], v[172:175], v[202:205], v[56:59]
	v_mfma_f32_16x16x32_bf16 v[44:47], v[162:165], v[210:213], v[44:47]
	v_mfma_f32_16x16x32_bf16 v[40:43], v[172:175], v[210:213], v[40:43]
	v_mfma_f32_16x16x32_bf16 v[28:31], v[162:165], v[218:221], v[28:31]
	v_mfma_f32_16x16x32_bf16 v[24:27], v[172:175], v[218:221], v[24:27]
	v_mfma_f32_16x16x32_bf16 v[12:15], v[162:165], v[226:229], v[12:15]
	v_mfma_f32_16x16x32_bf16 v[8:11], v[172:175], v[226:229], v[8:11]
	s_setprio 0
	s_setprio 1
	v_mfma_f32_16x16x32_bf16 v[52:55], v[182:185], v[198:201], v[52:55]
	v_mfma_f32_16x16x32_bf16 v[48:51], v[190:193], v[198:201], v[48:51]
	v_mfma_f32_16x16x32_bf16 v[36:39], v[182:185], v[206:209], v[36:39]
	v_mfma_f32_16x16x32_bf16 v[32:35], v[190:193], v[206:209], v[32:35]
	v_mfma_f32_16x16x32_bf16 v[20:23], v[182:185], v[214:217], v[20:23]
	v_mfma_f32_16x16x32_bf16 v[16:19], v[190:193], v[214:217], v[16:19]
	v_mfma_f32_16x16x32_bf16 v[4:7], v[182:185], v[222:225], v[4:7]
	v_mfma_f32_16x16x32_bf16 v[0:3], v[190:193], v[222:225], v[0:3]
	v_mfma_f32_16x16x32_bf16 v[52:55], v[186:189], v[202:205], v[52:55]
	v_mfma_f32_16x16x32_bf16 v[48:51], v[194:197], v[202:205], v[48:51]
	v_mfma_f32_16x16x32_bf16 v[36:39], v[186:189], v[210:213], v[36:39]
	v_mfma_f32_16x16x32_bf16 v[32:35], v[194:197], v[210:213], v[32:35]
	v_mfma_f32_16x16x32_bf16 v[20:23], v[186:189], v[218:221], v[20:23]
	v_mfma_f32_16x16x32_bf16 v[16:19], v[194:197], v[218:221], v[16:19]
	v_mfma_f32_16x16x32_bf16 v[4:7], v[186:189], v[226:229], v[4:7]
	v_mfma_f32_16x16x32_bf16 v[0:3], v[194:197], v[226:229], v[0:3]
	s_setprio 0
	s_barrier
	s_add_i32 s56, 0, 0x18000
	v_add_u32_e32 v157, s56, v151
	s_add_i32 s57, 0, 0x1c000
	ds_read_b128 v[158:161], v157
	ds_read_b128 v[162:165], v157 offset:1024
	ds_read_b128 v[168:171], v157 offset:2048
	ds_read_b128 v[172:175], v157 offset:3072
	v_add_u32_e32 v157, s57, v151
	ds_read_b128 v[182:185], v157
	ds_read_b128 v[186:189], v157 offset:1024
	ds_read_b128 v[190:193], v157 offset:2048
	ds_read_b128 v[194:197], v157 offset:3072
	s_add_u32 s28, s28, 0x20000
	s_addc_u32 s29, s29, 0
	s_mov_b32 m0, s38
	v_lshl_add_u64 v[234:235], s[28:29], 0, v[128:129]
	ds_read_b128 v[198:201], v154 offset:32768
	ds_read_b128 v[202:205], v154 offset:33792
	ds_read_b128 v[206:209], v154 offset:34816
	ds_read_b128 v[210:213], v154 offset:35840
	ds_read_b128 v[214:217], v154 offset:36864
	ds_read_b128 v[218:221], v154 offset:37888
	ds_read_b128 v[222:225], v154 offset:38912
	ds_read_b128 v[226:229], v154 offset:39936
	global_load_lds_dwordx4 v[234:235], off
	v_lshl_add_u64 v[234:235], s[28:29], 0, v[132:133]
	s_mov_b32 m0, s39
	s_nop 0
	global_load_lds_dwordx4 v[234:235], off
	s_waitcnt vmcnt(8)
	s_barrier
	s_setprio 1
	s_waitcnt lgkmcnt(0)
	v_mfma_f32_16x16x32_bf16 v[124:127], v[158:161], v[198:201], v[124:127]
	v_mfma_f32_16x16x32_bf16 v[120:123], v[168:171], v[198:201], v[120:123]
	v_mfma_f32_16x16x32_bf16 v[108:111], v[158:161], v[206:209], v[108:111]
	v_mfma_f32_16x16x32_bf16 v[104:107], v[168:171], v[206:209], v[104:107]
	v_mfma_f32_16x16x32_bf16 v[92:95], v[158:161], v[214:217], v[92:95]
	v_mfma_f32_16x16x32_bf16 v[88:91], v[168:171], v[214:217], v[88:91]
	v_mfma_f32_16x16x32_bf16 v[76:79], v[158:161], v[222:225], v[76:79]
	v_mfma_f32_16x16x32_bf16 v[72:75], v[168:171], v[222:225], v[72:75]
	v_mfma_f32_16x16x32_bf16 v[124:127], v[162:165], v[202:205], v[124:127]
	v_mfma_f32_16x16x32_bf16 v[120:123], v[172:175], v[202:205], v[120:123]
	v_mfma_f32_16x16x32_bf16 v[108:111], v[162:165], v[210:213], v[108:111]
	v_mfma_f32_16x16x32_bf16 v[104:107], v[172:175], v[210:213], v[104:107]
	v_mfma_f32_16x16x32_bf16 v[92:95], v[162:165], v[218:221], v[92:95]
	v_mfma_f32_16x16x32_bf16 v[88:91], v[172:175], v[218:221], v[88:91]
	v_mfma_f32_16x16x32_bf16 v[76:79], v[162:165], v[226:229], v[76:79]
	v_mfma_f32_16x16x32_bf16 v[72:75], v[172:175], v[226:229], v[72:75]
	s_setprio 0
	s_setprio 1
	v_mfma_f32_16x16x32_bf16 v[116:119], v[182:185], v[198:201], v[116:119]
	v_mfma_f32_16x16x32_bf16 v[112:115], v[190:193], v[198:201], v[112:115]
	v_mfma_f32_16x16x32_bf16 v[100:103], v[182:185], v[206:209], v[100:103]
	v_mfma_f32_16x16x32_bf16 v[96:99], v[190:193], v[206:209], v[96:99]
	v_mfma_f32_16x16x32_bf16 v[84:87], v[182:185], v[214:217], v[84:87]
	v_mfma_f32_16x16x32_bf16 v[80:83], v[190:193], v[214:217], v[80:83]
	v_mfma_f32_16x16x32_bf16 v[68:71], v[182:185], v[222:225], v[68:71]
	v_mfma_f32_16x16x32_bf16 v[64:67], v[190:193], v[222:225], v[64:67]
	v_mfma_f32_16x16x32_bf16 v[116:119], v[186:189], v[202:205], v[116:119]
	v_mfma_f32_16x16x32_bf16 v[112:115], v[194:197], v[202:205], v[112:115]
	v_mfma_f32_16x16x32_bf16 v[100:103], v[186:189], v[210:213], v[100:103]
	v_mfma_f32_16x16x32_bf16 v[96:99], v[194:197], v[210:213], v[96:99]
	v_mfma_f32_16x16x32_bf16 v[84:87], v[186:189], v[218:221], v[84:87]
	v_mfma_f32_16x16x32_bf16 v[80:83], v[194:197], v[218:221], v[80:83]
	v_mfma_f32_16x16x32_bf16 v[68:71], v[186:189], v[226:229], v[68:71]
	v_mfma_f32_16x16x32_bf16 v[64:67], v[194:197], v[226:229], v[64:67]
	s_setprio 0
	s_barrier
; #define PG8_STAGE(bufoff, gbase, voff) do { _Pragma("unroll") for (int _i = 0; _i < 2; ++_i) \
;         __builtin_amdgcn_global_load_lds((const unsigned*)((const char*)(gbase) + (voff)[_i]), (PG8_LAS unsigned*)(lds + (bufoff) + ldsw + _i * 8192), 16, 0, 0); } while (0)
; #define PG8_LDA(dst, b, h) do { _Pragma("unroll") for (int m = 0; m < 4; ++m) _Pragma("unroll") for (int k = 0; k < 2; ++k) dst[m][k] = *(const PG8_LAS bf16x8*)(lds + PG8_SA(b, h) + aoff + m * 2048 + k * 1024); } while (0)
; #define PG8_MMA(ai, bj, At, Bt) do { __builtin_amdgcn_s_setprio(1); _Pragma("unroll") for (int m = 0; m < 4; ++m) _Pragma("unroll") for (int n = 0; n < 2; ++n) _Pragma("unroll") for (int k = 0; k < 2; ++k) \
;         acc[ai][bj][m][n] = __builtin_amdgcn_mfma_f32_16x16x32_bf16(Bt[n][k], At[m][k], acc[ai][bj][m][n], 0, 0, 0); __builtin_amdgcn_s_setprio(0); } while (0)
; #define PG8_WAIT_V(n) asm volatile("s_waitcnt vmcnt(" #n ")" ::: "memory")
; #define PG8_WAIT_L(n) asm volatile("s_waitcnt lgkmcnt(" #n ")" ::: "memory")
; #define PG8_BAR __builtin_amdgcn_s_barrier()
; #define PG8_SCHED __builtin_amdgcn_sched_barrier(0)
; template <class Epi, class Sched, bool ALIGN_EPI = false, bool SP2 = false>
; __device__ __forceinline__ void gemm_phase(PG8_LAS unsigned char* lds, const Gemm g, const Sched& S, const Epi& E) {
;     ...
;             PG8_LDA(At, 1, 1); PG8_STAGE(PG8_SB(1, 0), b3, voffB); PG8_STAGE(PG8_SB(1, 1), b3 + hstep, voffB); PG8_STAGE(PG8_SA(1, 0), a3, voffA);
;             PG8_WAIT_V(8); PG8_WAIT_L(0); PG8_BAR; PG8_MMA(1, 0, At, B0); PG8_MMA(1, 1, At, B1); PG8_BAR; PG8_SCHED;
;     ...
;         if constexpr (ALIGN_EPI) { if (wr == 0) PG8_BAR; }
	s_add_i32 s28, s56, s36
	v_lshl_add_u64 v[148:149], v[148:149], 0, s[10:11]
	s_mov_b32 m0, s28
	ds_read_b128 v[198:201], v154 offset:49152
	ds_read_b128 v[202:205], v154 offset:50176
	ds_read_b128 v[206:209], v154 offset:51200
	ds_read_b128 v[210:213], v154 offset:52224
	ds_read_b128 v[214:217], v154 offset:53248
	ds_read_b128 v[218:221], v154 offset:54272
	ds_read_b128 v[222:225], v154 offset:55296
	ds_read_b128 v[226:229], v154 offset:56320
	global_load_lds_dwordx4 v[148:149], off
	s_add_i32 m0, s28, 0x2000
	s_add_u32 s26, s26, 0x20080
	v_lshl_add_u64 v[148:149], v[176:177], 0, s[10:11]
	s_addc_u32 s27, s27, 0
	s_add_i32 s28, s57, s36
	global_load_lds_dwordx4 v[148:149], off
	v_lshl_add_u64 v[148:149], s[26:27], 0, v[130:131]
	s_mov_b32 m0, s28
	s_nop 0
	global_load_lds_dwordx4 v[148:149], off
	v_lshl_add_u64 v[148:149], s[26:27], 0, v[134:135]
	s_add_i32 m0, s28, 0x2000
	s_nop 0
	global_load_lds_dwordx4 v[148:149], off
	v_lshl_add_u64 v[148:149], v[230:231], 0, s[10:11]
	s_mov_b32 m0, s42
	s_nop 0
	global_load_lds_dwordx4 v[148:149], off
	v_lshl_add_u64 v[148:149], v[232:233], 0, s[10:11]
	s_mov_b32 m0, s43
	s_nop 0
	global_load_lds_dwordx4 v[148:149], off
	s_waitcnt vmcnt(8)
	s_barrier
	s_setprio 1
	s_waitcnt lgkmcnt(0)
	v_mfma_f32_16x16x32_bf16 v[60:63], v[158:161], v[198:201], v[60:63]
	v_mfma_f32_16x16x32_bf16 v[56:59], v[168:171], v[198:201], v[56:59]
	v_mfma_f32_16x16x32_bf16 v[44:47], v[158:161], v[206:209], v[44:47]
	v_mfma_f32_16x16x32_bf16 v[40:43], v[168:171], v[206:209], v[40:43]
	v_mfma_f32_16x16x32_bf16 v[28:31], v[158:161], v[214:217], v[28:31]
	v_mfma_f32_16x16x32_bf16 v[24:27], v[168:171], v[214:217], v[24:27]
	v_mfma_f32_16x16x32_bf16 v[12:15], v[158:161], v[222:225], v[12:15]
	v_mfma_f32_16x16x32_bf16 v[8:11], v[168:171], v[222:225], v[8:11]
	v_mfma_f32_16x16x32_bf16 v[60:63], v[162:165], v[202:205], v[60:63]
	v_mfma_f32_16x16x32_bf16 v[56:59], v[172:175], v[202:205], v[56:59]
	v_mfma_f32_16x16x32_bf16 v[44:47], v[162:165], v[210:213], v[44:47]
	v_mfma_f32_16x16x32_bf16 v[40:43], v[172:175], v[210:213], v[40:43]
	v_mfma_f32_16x16x32_bf16 v[28:31], v[162:165], v[218:221], v[28:31]
	v_mfma_f32_16x16x32_bf16 v[24:27], v[172:175], v[218:221], v[24:27]
	v_mfma_f32_16x16x32_bf16 v[12:15], v[162:165], v[226:229], v[12:15]
	v_mfma_f32_16x16x32_bf16 v[8:11], v[172:175], v[226:229], v[8:11]
	s_setprio 0
	s_setprio 1
	v_mfma_f32_16x16x32_bf16 v[52:55], v[182:185], v[198:201], v[52:55]
	v_mfma_f32_16x16x32_bf16 v[48:51], v[190:193], v[198:201], v[48:51]
	v_mfma_f32_16x16x32_bf16 v[36:39], v[182:185], v[206:209], v[36:39]
	v_mfma_f32_16x16x32_bf16 v[32:35], v[190:193], v[206:209], v[32:35]
	v_mfma_f32_16x16x32_bf16 v[20:23], v[182:185], v[214:217], v[20:23]
	v_mfma_f32_16x16x32_bf16 v[16:19], v[190:193], v[214:217], v[16:19]
	v_mfma_f32_16x16x32_bf16 v[4:7], v[182:185], v[222:225], v[4:7]
	v_mfma_f32_16x16x32_bf16 v[0:3], v[190:193], v[222:225], v[0:3]
	v_mfma_f32_16x16x32_bf16 v[52:55], v[186:189], v[202:205], v[52:55]
	v_mfma_f32_16x16x32_bf16 v[48:51], v[194:197], v[202:205], v[48:51]
	v_mfma_f32_16x16x32_bf16 v[36:39], v[186:189], v[210:213], v[36:39]
	v_mfma_f32_16x16x32_bf16 v[32:35], v[194:197], v[210:213], v[32:35]
	v_mfma_f32_16x16x32_bf16 v[20:23], v[186:189], v[218:221], v[20:23]
	v_mfma_f32_16x16x32_bf16 v[16:19], v[194:197], v[218:221], v[16:19]
	v_mfma_f32_16x16x32_bf16 v[4:7], v[186:189], v[226:229], v[4:7]
	v_mfma_f32_16x16x32_bf16 v[0:3], v[194:197], v[226:229], v[0:3]
	s_setprio 0
	s_barrier
	s_add_i32 s55, s55, 2
	s_add_u32 s24, s24, 0x100
	s_addc_u32 s25, s25, 0
	s_add_u32 s53, s53, 0x100
	s_addc_u32 s54, s54, 0
	s_cmp_gt_u32 s55, 5
	s_cbranch_scc0 .LBB0_623
	s_and_b64 vcc, exec, s[12:13]
	s_cbranch_vccz .LBB0_626
	s_barrier

; #define PG8_STAGE(bufoff, gbase, voff) do { _Pragma("unroll") for (int _i = 0; _i < 2; ++_i) \
;         __builtin_amdgcn_global_load_lds((const unsigned*)((const char*)(gbase) + (voff)[_i]), (PG8_LAS unsigned*)(lds + (bufoff) + ldsw + _i * 8192), 16, 0, 0); } while (0)
; #define PG8_LDA(dst, b, h) do { _Pragma("unroll") for (int m = 0; m < 4; ++m) _Pragma("unroll") for (int k = 0; k < 2; ++k) dst[m][k] = *(const PG8_LAS bf16x8*)(lds + PG8_SA(b, h) + aoff + m * 2048 + k * 1024); } while (0)
; #define PG8_LDB(dst, b, h) do { _Pragma("unroll") for (int n = 0; n < 2; ++n) _Pragma("unroll") for (int k = 0; k < 2; ++k) dst[n][k] = *(const PG8_LAS bf16x8*)(lds + PG8_SB(b, h) + boff + n * 2048 + k * 1024); } while (0)
; #define PG8_MMA(ai, bj, At, Bt) do { __builtin_amdgcn_s_setprio(1); _Pragma("unroll") for (int m = 0; m < 4; ++m) _Pragma("unroll") for (int n = 0; n < 2; ++n) _Pragma("unroll") for (int k = 0; k < 2; ++k) \
;         acc[ai][bj][m][n] = __builtin_amdgcn_mfma_f32_16x16x32_bf16(Bt[n][k], At[m][k], acc[ai][bj][m][n], 0, 0, 0); __builtin_amdgcn_s_setprio(0); } while (0)
; #define PG8_WAIT_V(n) asm volatile("s_waitcnt vmcnt(" #n ")" ::: "memory")
; #define PG8_WAIT_L(n) asm volatile("s_waitcnt lgkmcnt(" #n ")" ::: "memory")
; #define PG8_BAR __builtin_amdgcn_s_barrier()
; #define PG8_SCHED __builtin_amdgcn_sched_barrier(0)
; template <class Epi, class Sched, bool ALIGN_EPI = false, bool SP2 = false>
; __device__ __forceinline__ void gemm_phase(PG8_LAS unsigned char* lds, const Gemm g, const Sched& S, const Epi& E) {
;     ...
;             const char* a2 = last ? nA : cA + (size_t)(t + 2) * kstep; const char* b2 = last ? nB : cB + (size_t)(t + 2) * kstep;
;             const char* a3 = a2 + kstep; const char* b3 = b2 + kstep;
;             if (last && has_next) S.a_ready(nxt);
;             if constexpr (SP2) {
;             PG8_LDB(B0, 0, 0); PG8_LDB(B1, 0, 1); PG8_SCHED; PG8_LDA(At, 0, 0); PG8_STAGE(PG8_SA(1, 1), a1 + hstep, voffA);
;             PG8_WAIT_V(8); PG8_WAIT_L(0); PG8_BAR; PG8_MMA(0, 0, At, B0); PG8_MMA(0, 1, At, B1); PG8_BAR; PG8_SCHED;
;             PG8_LDA(At, 0, 1); PG8_STAGE(PG8_SB(0, 0), b2, voffB); PG8_STAGE(PG8_SB(0, 1), b2 + hstep, voffB); PG8_STAGE(PG8_SA(0, 0), a2, voffA);
.LBB0_1049:
	ds_read_b128 v[154:157], v150
	ds_read_b128 v[158:161], v150 offset:1024
	ds_read_b128 v[162:165], v150 offset:2048
	ds_read_b128 v[168:171], v150 offset:3072
	ds_read_b128 v[172:175], v151
	ds_read_b128 v[182:185], v151 offset:1024
	ds_read_b128 v[186:189], v151 offset:2048
	ds_read_b128 v[190:193], v151 offset:3072
	s_add_u32 s30, s28, 0xfffc0080
	s_addc_u32 s31, s29, -1
	s_cmp_eq_u32 s54, 12
	s_cselect_b32 s35, s21, s31
	s_cselect_b32 s34, s50, s30
	s_cselect_b32 s31, s19, s53
	s_cselect_b32 s30, s51, s52
	v_lshl_add_u64 v[148:149], s[28:29], 0, v[140:141]
	s_add_i32 m0, s41, 0xc000
	ds_read_b128 v[194:197], v152
	ds_read_b128 v[198:201], v152 offset:1024
	ds_read_b128 v[202:205], v152 offset:2048
	ds_read_b128 v[206:209], v152 offset:3072
	ds_read_b128 v[210:213], v152 offset:4096
	ds_read_b128 v[214:217], v152 offset:5120
	ds_read_b128 v[218:221], v152 offset:6144
	ds_read_b128 v[222:225], v152 offset:7168
	global_load_lds_dwordx4 v[148:149], off
	v_lshl_add_u64 v[148:149], s[28:29], 0, v[142:143]
	s_add_i32 m0, s41, 0xe000
	s_nop 0
	global_load_lds_dwordx4 v[148:149], off
	s_waitcnt vmcnt(8)
	s_barrier
	s_setprio 1
	s_waitcnt lgkmcnt(0)
	v_mfma_f32_16x16x32_bf16 v[124:127], v[154:157], v[194:197], v[124:127]
	v_mfma_f32_16x16x32_bf16 v[120:123], v[162:165], v[194:197], v[120:123]
	v_mfma_f32_16x16x32_bf16 v[108:111], v[154:157], v[202:205], v[108:111]
	v_mfma_f32_16x16x32_bf16 v[104:107], v[162:165], v[202:205], v[104:107]
	v_mfma_f32_16x16x32_bf16 v[92:95], v[154:157], v[210:213], v[92:95]
	v_mfma_f32_16x16x32_bf16 v[88:91], v[162:165], v[210:213], v[88:91]
	v_mfma_f32_16x16x32_bf16 v[76:79], v[154:157], v[218:221], v[76:79]
	v_mfma_f32_16x16x32_bf16 v[72:75], v[162:165], v[218:221], v[72:75]
	v_mfma_f32_16x16x32_bf16 v[124:127], v[158:161], v[198:201], v[124:127]
	v_mfma_f32_16x16x32_bf16 v[120:123], v[168:171], v[198:201], v[120:123]
	v_mfma_f32_16x16x32_bf16 v[108:111], v[158:161], v[206:209], v[108:111]
	v_mfma_f32_16x16x32_bf16 v[104:107], v[168:171], v[206:209], v[104:107]
	v_mfma_f32_16x16x32_bf16 v[92:95], v[158:161], v[214:217], v[92:95]
	v_mfma_f32_16x16x32_bf16 v[88:91], v[168:171], v[214:217], v[88:91]
	v_mfma_f32_16x16x32_bf16 v[76:79], v[158:161], v[222:225], v[76:79]
	v_mfma_f32_16x16x32_bf16 v[72:75], v[168:171], v[222:225], v[72:75]
	s_setprio 0
	s_setprio 1
	v_mfma_f32_16x16x32_bf16 v[116:119], v[172:175], v[194:197], v[116:119]
	v_mfma_f32_16x16x32_bf16 v[112:115], v[186:189], v[194:197], v[112:115]
	v_mfma_f32_16x16x32_bf16 v[100:103], v[172:175], v[202:205], v[100:103]
	v_mfma_f32_16x16x32_bf16 v[96:99], v[186:189], v[202:205], v[96:99]
	v_mfma_f32_16x16x32_bf16 v[84:87], v[172:175], v[210:213], v[84:87]
	v_mfma_f32_16x16x32_bf16 v[80:83], v[186:189], v[210:213], v[80:83]
	v_mfma_f32_16x16x32_bf16 v[68:71], v[172:175], v[218:221], v[68:71]
	v_mfma_f32_16x16x32_bf16 v[64:67], v[186:189], v[218:221], v[64:67]
	v_mfma_f32_16x16x32_bf16 v[116:119], v[182:185], v[198:201], v[116:119]
	v_mfma_f32_16x16x32_bf16 v[112:115], v[190:193], v[198:201], v[112:115]
	v_mfma_f32_16x16x32_bf16 v[100:103], v[182:185], v[206:209], v[100:103]
	v_mfma_f32_16x16x32_bf16 v[96:99], v[190:193], v[206:209], v[96:99]
	v_mfma_f32_16x16x32_bf16 v[84:87], v[182:185], v[214:217], v[84:87]
	v_mfma_f32_16x16x32_bf16 v[80:83], v[190:193], v[214:217], v[80:83]
	v_mfma_f32_16x16x32_bf16 v[68:71], v[182:185], v[222:225], v[68:71]
	v_mfma_f32_16x16x32_bf16 v[64:67], v[190:193], v[222:225], v[64:67]
	s_setprio 0
	s_barrier
	s_add_i32 s55, s33, s40
	v_lshl_add_u64 v[148:149], s[30:31], 0, v[130:131]
	s_mov_b32 m0, s55
	ds_read_b128 v[194:197], v152 offset:16384
	ds_read_b128 v[198:201], v152 offset:17408
	ds_read_b128 v[202:205], v152 offset:18432
	ds_read_b128 v[206:209], v152 offset:19456
	ds_read_b128 v[210:213], v152 offset:20480
	ds_read_b128 v[214:217], v152 offset:21504
	ds_read_b128 v[218:221], v152 offset:22528
	ds_read_b128 v[222:225], v152 offset:23552
	global_load_lds_dwordx4 v[148:149], off
	s_add_i32 m0, s55, 0x2000
	s_add_u32 s56, s30, 0x40000
	v_lshl_add_u64 v[176:177], s[30:31], 0, v[134:135]
	s_addc_u32 s57, s31, 0
	s_add_i32 s55, s49, s40
	global_load_lds_dwordx4 v[176:177], off
	v_lshl_add_u64 v[226:227], s[56:57], 0, v[130:131]
	s_mov_b32 m0, s55
	v_lshl_add_u64 v[228:229], s[34:35], 0, v[132:133]
	global_load_lds_dwordx4 v[226:227], off
	v_lshl_add_u64 v[226:227], s[56:57], 0, v[134:135]
	s_add_i32 m0, s55, 0x2000
	s_nop 0
	global_load_lds_dwordx4 v[226:227], off
	v_lshl_add_u64 v[226:227], s[34:35], 0, v[128:129]
	s_mov_b32 m0, s41
	s_nop 0
	global_load_lds_dwordx4 v[226:227], off
	s_mov_b32 m0, s42
	s_nop 0
	global_load_lds_dwordx4 v[228:229], off
	s_waitcnt vmcnt(8)
	s_barrier
; #define PG8_STAGE(bufoff, gbase, voff) do { _Pragma("unroll") for (int _i = 0; _i < 2; ++_i) \
;         __builtin_amdgcn_global_load_lds((const unsigned*)((const char*)(gbase) + (voff)[_i]), (PG8_LAS unsigned*)(lds + (bufoff) + ldsw + _i * 8192), 16, 0, 0); } while (0)
; #define PG8_LDA(dst, b, h) do { _Pragma("unroll") for (int m = 0; m < 4; ++m) _Pragma("unroll") for (int k = 0; k < 2; ++k) dst[m][k] = *(const PG8_LAS bf16x8*)(lds + PG8_SA(b, h) + aoff + m * 2048 + k * 1024); } while (0)
; #define PG8_LDB(dst, b, h) do { _Pragma("unroll") for (int n = 0; n < 2; ++n) _Pragma("unroll") for (int k = 0; k < 2; ++k) dst[n][k] = *(const PG8_LAS bf16x8*)(lds + PG8_SB(b, h) + boff + n * 2048 + k * 1024); } while (0)
; #define PG8_MMA(ai, bj, At, Bt) do { __builtin_amdgcn_s_setprio(1); _Pragma("unroll") for (int m = 0; m < 4; ++m) _Pragma("unroll") for (int n = 0; n < 2; ++n) _Pragma("unroll") for (int k = 0; k < 2; ++k) \
;         acc[ai][bj][m][n] = __builtin_amdgcn_mfma_f32_16x16x32_bf16(Bt[n][k], At[m][k], acc[ai][bj][m][n], 0, 0, 0); __builtin_amdgcn_s_setprio(0); } while (0)
; #define PG8_WAIT_V(n) asm volatile("s_waitcnt vmcnt(" #n ")" ::: "memory")
; #define PG8_WAIT_L(n) asm volatile("s_waitcnt lgkmcnt(" #n ")" ::: "memory")
; #define PG8_BAR __builtin_amdgcn_s_barrier()
; #define PG8_SCHED __builtin_amdgcn_sched_barrier(0)
; template <class Epi, class Sched, bool ALIGN_EPI = false, bool SP2 = false>
; __device__ __forceinline__ void gemm_phase(PG8_LAS unsigned char* lds, const Gemm g, const Sched& S, const Epi& E) {
;     ...
;             PG8_WAIT_V(8); PG8_WAIT_L(0); PG8_BAR; PG8_MMA(1, 0, At, B0); PG8_MMA(1, 1, At, B1); PG8_BAR; PG8_SCHED;
;             PG8_LDB(B0, 1, 0); PG8_LDB(B1, 1, 1); PG8_SCHED; PG8_LDA(At, 1, 0); PG8_STAGE(PG8_SA(0, 1), a2 + hstep, voffA);
;             PG8_WAIT_V(8); PG8_WAIT_L(0); PG8_BAR; PG8_MMA(0, 0, At, B0); PG8_MMA(0, 1, At, B1); PG8_BAR; PG8_SCHED;
	s_setprio 1
	s_waitcnt lgkmcnt(0)
	v_mfma_f32_16x16x32_bf16 v[60:63], v[154:157], v[194:197], v[60:63]
	v_mfma_f32_16x16x32_bf16 v[56:59], v[162:165], v[194:197], v[56:59]
	v_mfma_f32_16x16x32_bf16 v[44:47], v[154:157], v[202:205], v[44:47]
	v_mfma_f32_16x16x32_bf16 v[40:43], v[162:165], v[202:205], v[40:43]
	v_mfma_f32_16x16x32_bf16 v[28:31], v[154:157], v[210:213], v[28:31]
	v_mfma_f32_16x16x32_bf16 v[24:27], v[162:165], v[210:213], v[24:27]
	v_mfma_f32_16x16x32_bf16 v[12:15], v[154:157], v[218:221], v[12:15]
	v_mfma_f32_16x16x32_bf16 v[8:11], v[162:165], v[218:221], v[8:11]
	v_mfma_f32_16x16x32_bf16 v[60:63], v[158:161], v[198:201], v[60:63]
	v_mfma_f32_16x16x32_bf16 v[56:59], v[168:171], v[198:201], v[56:59]
	v_mfma_f32_16x16x32_bf16 v[44:47], v[158:161], v[206:209], v[44:47]
	v_mfma_f32_16x16x32_bf16 v[40:43], v[168:171], v[206:209], v[40:43]
	v_mfma_f32_16x16x32_bf16 v[28:31], v[158:161], v[214:217], v[28:31]
	v_mfma_f32_16x16x32_bf16 v[24:27], v[168:171], v[214:217], v[24:27]
	v_mfma_f32_16x16x32_bf16 v[12:15], v[158:161], v[222:225], v[12:15]
	v_mfma_f32_16x16x32_bf16 v[8:11], v[168:171], v[222:225], v[8:11]
	s_setprio 0
	s_setprio 1
	v_mfma_f32_16x16x32_bf16 v[52:55], v[172:175], v[194:197], v[52:55]
	v_mfma_f32_16x16x32_bf16 v[48:51], v[186:189], v[194:197], v[48:51]
	v_mfma_f32_16x16x32_bf16 v[36:39], v[172:175], v[202:205], v[36:39]
	v_mfma_f32_16x16x32_bf16 v[32:35], v[186:189], v[202:205], v[32:35]
	v_mfma_f32_16x16x32_bf16 v[20:23], v[172:175], v[210:213], v[20:23]
	v_mfma_f32_16x16x32_bf16 v[16:19], v[186:189], v[210:213], v[16:19]
	v_mfma_f32_16x16x32_bf16 v[4:7], v[172:175], v[218:221], v[4:7]
	v_mfma_f32_16x16x32_bf16 v[0:3], v[186:189], v[218:221], v[0:3]
	v_mfma_f32_16x16x32_bf16 v[52:55], v[182:185], v[198:201], v[52:55]
	v_mfma_f32_16x16x32_bf16 v[48:51], v[190:193], v[198:201], v[48:51]
	v_mfma_f32_16x16x32_bf16 v[36:39], v[182:185], v[206:209], v[36:39]
	v_mfma_f32_16x16x32_bf16 v[32:35], v[190:193], v[206:209], v[32:35]
	v_mfma_f32_16x16x32_bf16 v[20:23], v[182:185], v[214:217], v[20:23]
	v_mfma_f32_16x16x32_bf16 v[16:19], v[190:193], v[214:217], v[16:19]
	v_mfma_f32_16x16x32_bf16 v[4:7], v[182:185], v[222:225], v[4:7]
	v_mfma_f32_16x16x32_bf16 v[0:3], v[190:193], v[222:225], v[0:3]
	s_setprio 0
	s_barrier
	s_add_i32 s55, 0, 0x18000
	v_add_u32_e32 v153, s55, v139
	s_add_i32 s56, 0, 0x1c000
	ds_read_b128 v[154:157], v153
	ds_read_b128 v[158:161], v153 offset:1024
	ds_read_b128 v[162:165], v153 offset:2048
	ds_read_b128 v[168:171], v153 offset:3072
	v_add_u32_e32 v153, s56, v139
	ds_read_b128 v[172:175], v153
	ds_read_b128 v[182:185], v153 offset:1024
	ds_read_b128 v[186:189], v153 offset:2048
	ds_read_b128 v[190:193], v153 offset:3072
	s_add_u32 s34, s34, 0x40000
	s_addc_u32 s35, s35, 0
	s_mov_b32 m0, s43
	v_lshl_add_u64 v[230:231], s[34:35], 0, v[128:129]
	ds_read_b128 v[194:197], v152 offset:32768
	ds_read_b128 v[198:201], v152 offset:33792
	ds_read_b128 v[202:205], v152 offset:34816
	ds_read_b128 v[206:209], v152 offset:35840
	ds_read_b128 v[210:213], v152 offset:36864
	ds_read_b128 v[214:217], v152 offset:37888
	ds_read_b128 v[218:221], v152 offset:38912
	ds_read_b128 v[222:225], v152 offset:39936
	global_load_lds_dwordx4 v[230:231], off
	v_lshl_add_u64 v[230:231], s[34:35], 0, v[132:133]
	s_mov_b32 m0, s44
	s_nop 0
	global_load_lds_dwordx4 v[230:231], off
	s_waitcnt vmcnt(8)
	s_barrier
	s_setprio 1
	s_waitcnt lgkmcnt(0)
	v_mfma_f32_16x16x32_bf16 v[124:127], v[154:157], v[194:197], v[124:127]
	v_mfma_f32_16x16x32_bf16 v[120:123], v[162:165], v[194:197], v[120:123]
	v_mfma_f32_16x16x32_bf16 v[108:111], v[154:157], v[202:205], v[108:111]
	v_mfma_f32_16x16x32_bf16 v[104:107], v[162:165], v[202:205], v[104:107]
	v_mfma_f32_16x16x32_bf16 v[92:95], v[154:157], v[210:213], v[92:95]
	v_mfma_f32_16x16x32_bf16 v[88:91], v[162:165], v[210:213], v[88:91]
	v_mfma_f32_16x16x32_bf16 v[76:79], v[154:157], v[218:221], v[76:79]
	v_mfma_f32_16x16x32_bf16 v[72:75], v[162:165], v[218:221], v[72:75]
	v_mfma_f32_16x16x32_bf16 v[124:127], v[158:161], v[198:201], v[124:127]
	v_mfma_f32_16x16x32_bf16 v[120:123], v[168:171], v[198:201], v[120:123]
	v_mfma_f32_16x16x32_bf16 v[108:111], v[158:161], v[206:209], v[108:111]
	v_mfma_f32_16x16x32_bf16 v[104:107], v[168:171], v[206:209], v[104:107]
	v_mfma_f32_16x16x32_bf16 v[92:95], v[158:161], v[214:217], v[92:95]
	v_mfma_f32_16x16x32_bf16 v[88:91], v[168:171], v[214:217], v[88:91]
	v_mfma_f32_16x16x32_bf16 v[76:79], v[158:161], v[222:225], v[76:79]
	v_mfma_f32_16x16x32_bf16 v[72:75], v[168:171], v[222:225], v[72:75]
	s_setprio 0
	s_setprio 1
	v_mfma_f32_16x16x32_bf16 v[116:119], v[172:175], v[194:197], v[116:119]
	v_mfma_f32_16x16x32_bf16 v[112:115], v[186:189], v[194:197], v[112:115]
	v_mfma_f32_16x16x32_bf16 v[100:103], v[172:175], v[202:205], v[100:103]
	v_mfma_f32_16x16x32_bf16 v[96:99], v[186:189], v[202:205], v[96:99]
	v_mfma_f32_16x16x32_bf16 v[84:87], v[172:175], v[210:213], v[84:87]
	v_mfma_f32_16x16x32_bf16 v[80:83], v[186:189], v[210:213], v[80:83]
	v_mfma_f32_16x16x32_bf16 v[68:71], v[172:175], v[218:221], v[68:71]
	v_mfma_f32_16x16x32_bf16 v[64:67], v[186:189], v[218:221], v[64:67]
	v_mfma_f32_16x16x32_bf16 v[116:119], v[182:185], v[198:201], v[116:119]
	v_mfma_f32_16x16x32_bf16 v[112:115], v[190:193], v[198:201], v[112:115]
	v_mfma_f32_16x16x32_bf16 v[100:103], v[182:185], v[206:209], v[100:103]
	v_mfma_f32_16x16x32_bf16 v[96:99], v[190:193], v[206:209], v[96:99]
	v_mfma_f32_16x16x32_bf16 v[84:87], v[182:185], v[214:217], v[84:87]
	v_mfma_f32_16x16x32_bf16 v[80:83], v[190:193], v[214:217], v[80:83]
	v_mfma_f32_16x16x32_bf16 v[68:71], v[182:185], v[222:225], v[68:71]
	v_mfma_f32_16x16x32_bf16 v[64:67], v[190:193], v[222:225], v[64:67]
	s_setprio 0
	s_barrier
; #define PG8_STAGE(bufoff, gbase, voff) do { _Pragma("unroll") for (int _i = 0; _i < 2; ++_i) \
;         __builtin_amdgcn_global_load_lds((const unsigned*)((const char*)(gbase) + (voff)[_i]), (PG8_LAS unsigned*)(lds + (bufoff) + ldsw + _i * 8192), 16, 0, 0); } while (0)
; #define PG8_LDA(dst, b, h) do { _Pragma("unroll") for (int m = 0; m < 4; ++m) _Pragma("unroll") for (int k = 0; k < 2; ++k) dst[m][k] = *(const PG8_LAS bf16x8*)(lds + PG8_SA(b, h) + aoff + m * 2048 + k * 1024); } while (0)
; #define PG8_MMA(ai, bj, At, Bt) do { __builtin_amdgcn_s_setprio(1); _Pragma("unroll") for (int m = 0; m < 4; ++m) _Pragma("unroll") for (int n = 0; n < 2; ++n) _Pragma("unroll") for (int k = 0; k < 2; ++k) \
;         acc[ai][bj][m][n] = __builtin_amdgcn_mfma_f32_16x16x32_bf16(Bt[n][k], At[m][k], acc[ai][bj][m][n], 0, 0, 0); __builtin_amdgcn_s_setprio(0); } while (0)
; #define PG8_WAIT_V(n) asm volatile("s_waitcnt vmcnt(" #n ")" ::: "memory")
; #define PG8_WAIT_L(n) asm volatile("s_waitcnt lgkmcnt(" #n ")" ::: "memory")
; #define PG8_BAR __builtin_amdgcn_s_barrier()
; #define PG8_SCHED __builtin_amdgcn_sched_barrier(0)
; template <class Epi, class Sched, bool ALIGN_EPI = false, bool SP2 = false>
; __device__ __forceinline__ void gemm_phase(PG8_LAS unsigned char* lds, const Gemm g, const Sched& S, const Epi& E) {
;     ...
;             PG8_LDA(At, 1, 1); PG8_STAGE(PG8_SB(1, 0), b3, voffB); PG8_STAGE(PG8_SB(1, 1), b3 + hstep, voffB); PG8_STAGE(PG8_SA(1, 0), a3, voffA);
;             PG8_WAIT_V(8); PG8_WAIT_L(0); PG8_BAR; PG8_MMA(1, 0, At, B0); PG8_MMA(1, 1, At, B1); PG8_BAR; PG8_SCHED;
	s_add_i32 s34, s55, s40
	v_lshl_add_u64 v[148:149], v[148:149], 0, s[14:15]
	s_mov_b32 m0, s34
	ds_read_b128 v[194:197], v152 offset:49152
	ds_read_b128 v[198:201], v152 offset:50176
	ds_read_b128 v[202:205], v152 offset:51200
	ds_read_b128 v[206:209], v152 offset:52224
	ds_read_b128 v[210:213], v152 offset:53248
	ds_read_b128 v[214:217], v152 offset:54272
	ds_read_b128 v[218:221], v152 offset:55296
	ds_read_b128 v[222:225], v152 offset:56320
	global_load_lds_dwordx4 v[148:149], off
	s_add_i32 m0, s34, 0x2000
	s_add_u32 s30, s30, 0x40080
	v_lshl_add_u64 v[148:149], v[176:177], 0, s[14:15]
	s_addc_u32 s31, s31, 0
	s_add_i32 s34, s56, s40
	global_load_lds_dwordx4 v[148:149], off
	v_lshl_add_u64 v[148:149], s[30:31], 0, v[130:131]
	s_mov_b32 m0, s34
	s_nop 0
	global_load_lds_dwordx4 v[148:149], off
	v_lshl_add_u64 v[148:149], s[30:31], 0, v[134:135]
	s_add_i32 m0, s34, 0x2000
	s_nop 0
	global_load_lds_dwordx4 v[148:149], off
	v_lshl_add_u64 v[148:149], v[226:227], 0, s[14:15]
	s_mov_b32 m0, s46
	s_nop 0
	global_load_lds_dwordx4 v[148:149], off
	v_lshl_add_u64 v[148:149], v[228:229], 0, s[14:15]
	s_mov_b32 m0, s47
	s_nop 0
	global_load_lds_dwordx4 v[148:149], off
	s_waitcnt vmcnt(8)
	s_barrier
	s_setprio 1
	s_waitcnt lgkmcnt(0)
	v_mfma_f32_16x16x32_bf16 v[60:63], v[154:157], v[194:197], v[60:63]
	v_mfma_f32_16x16x32_bf16 v[56:59], v[162:165], v[194:197], v[56:59]
	v_mfma_f32_16x16x32_bf16 v[44:47], v[154:157], v[202:205], v[44:47]
	v_mfma_f32_16x16x32_bf16 v[40:43], v[162:165], v[202:205], v[40:43]
	v_mfma_f32_16x16x32_bf16 v[28:31], v[154:157], v[210:213], v[28:31]
	v_mfma_f32_16x16x32_bf16 v[24:27], v[162:165], v[210:213], v[24:27]
	v_mfma_f32_16x16x32_bf16 v[12:15], v[154:157], v[218:221], v[12:15]
	v_mfma_f32_16x16x32_bf16 v[8:11], v[162:165], v[218:221], v[8:11]
	v_mfma_f32_16x16x32_bf16 v[60:63], v[158:161], v[198:201], v[60:63]
	v_mfma_f32_16x16x32_bf16 v[56:59], v[168:171], v[198:201], v[56:59]
	v_mfma_f32_16x16x32_bf16 v[44:47], v[158:161], v[206:209], v[44:47]
	v_mfma_f32_16x16x32_bf16 v[40:43], v[168:171], v[206:209], v[40:43]
	v_mfma_f32_16x16x32_bf16 v[28:31], v[158:161], v[214:217], v[28:31]
	v_mfma_f32_16x16x32_bf16 v[24:27], v[168:171], v[214:217], v[24:27]
	v_mfma_f32_16x16x32_bf16 v[12:15], v[158:161], v[222:225], v[12:15]
	v_mfma_f32_16x16x32_bf16 v[8:11], v[168:171], v[222:225], v[8:11]
	s_setprio 0
	s_setprio 1
	v_mfma_f32_16x16x32_bf16 v[52:55], v[172:175], v[194:197], v[52:55]
	v_mfma_f32_16x16x32_bf16 v[48:51], v[186:189], v[194:197], v[48:51]
	v_mfma_f32_16x16x32_bf16 v[36:39], v[172:175], v[202:205], v[36:39]
	v_mfma_f32_16x16x32_bf16 v[32:35], v[186:189], v[202:205], v[32:35]
	v_mfma_f32_16x16x32_bf16 v[20:23], v[172:175], v[210:213], v[20:23]
	v_mfma_f32_16x16x32_bf16 v[16:19], v[186:189], v[210:213], v[16:19]
	v_mfma_f32_16x16x32_bf16 v[4:7], v[172:175], v[218:221], v[4:7]
	v_mfma_f32_16x16x32_bf16 v[0:3], v[186:189], v[218:221], v[0:3]
	v_mfma_f32_16x16x32_bf16 v[52:55], v[182:185], v[198:201], v[52:55]
	v_mfma_f32_16x16x32_bf16 v[48:51], v[190:193], v[198:201], v[48:51]
	v_mfma_f32_16x16x32_bf16 v[36:39], v[182:185], v[206:209], v[36:39]
	v_mfma_f32_16x16x32_bf16 v[32:35], v[190:193], v[206:209], v[32:35]
	v_mfma_f32_16x16x32_bf16 v[20:23], v[182:185], v[214:217], v[20:23]
	v_mfma_f32_16x16x32_bf16 v[16:19], v[190:193], v[214:217], v[16:19]
	v_mfma_f32_16x16x32_bf16 v[4:7], v[182:185], v[222:225], v[4:7]
	v_mfma_f32_16x16x32_bf16 v[0:3], v[190:193], v[222:225], v[0:3]
	s_setprio 0
	s_barrier
	s_add_i32 s54, s54, 2
	s_add_u32 s28, s28, 0x100
	s_addc_u32 s29, s29, 0
	s_add_u32 s52, s52, 0x100
	s_addc_u32 s53, s53, 0
	s_cmp_gt_u32 s54, 13
	s_cbranch_scc0 .LBB0_1049
	s_and_b64 vcc, exec, s[16:17]
	s_cbranch_vccz .LBB0_1052
	s_barrier

; #define PG8_STAGE(bufoff, gbase, voff) do { _Pragma("unroll") for (int _i = 0; _i < 2; ++_i) \
;         __builtin_amdgcn_global_load_lds((const unsigned*)((const char*)(gbase) + (voff)[_i]), (PG8_LAS unsigned*)(lds + (bufoff) + ldsw + _i * 8192), 16, 0, 0); } while (0)
; #define PG8_LDA(dst, b, h) do { _Pragma("unroll") for (int m = 0; m < 4; ++m) _Pragma("unroll") for (int k = 0; k < 2; ++k) dst[m][k] = *(const PG8_LAS bf16x8*)(lds + PG8_SA(b, h) + aoff + m * 2048 + k * 1024); } while (0)
; #define PG8_LDB(dst, b, h) do { _Pragma("unroll") for (int n = 0; n < 2; ++n) _Pragma("unroll") for (int k = 0; k < 2; ++k) dst[n][k] = *(const PG8_LAS bf16x8*)(lds + PG8_SB(b, h) + boff + n * 2048 + k * 1024); } while (0)
; #define PG8_MMA(ai, bj, At, Bt) do { __builtin_amdgcn_s_setprio(1); _Pragma("unroll") for (int m = 0; m < 4; ++m) _Pragma("unroll") for (int n = 0; n < 2; ++n) _Pragma("unroll") for (int k = 0; k < 2; ++k) \
;         acc[ai][bj][m][n] = __builtin_amdgcn_mfma_f32_16x16x32_bf16(Bt[n][k], At[m][k], acc[ai][bj][m][n], 0, 0, 0); __builtin_amdgcn_s_setprio(0); } while (0)
; #define PG8_WAIT_V(n) asm volatile("s_waitcnt vmcnt(" #n ")" ::: "memory")
; #define PG8_WAIT_L(n) asm volatile("s_waitcnt lgkmcnt(" #n ")" ::: "memory")
; #define PG8_BAR __builtin_amdgcn_s_barrier()
; #define PG8_SCHED __builtin_amdgcn_sched_barrier(0)
; template <class Epi, class Sched, bool ALIGN_EPI = false, bool SP2 = false>
; __device__ __forceinline__ void gemm_phase(PG8_LAS unsigned char* lds, const Gemm g, const Sched& S, const Epi& E) {
;     ...
;             const char* a2 = last ? nA : cA + (size_t)(t + 2) * kstep; const char* b2 = last ? nB : cB + (size_t)(t + 2) * kstep;
;             const char* a3 = a2 + kstep; const char* b3 = b2 + kstep;
;             if (last && has_next) S.a_ready(nxt);
;             if constexpr (SP2) {
;             PG8_LDB(B0, 0, 0); PG8_LDB(B1, 0, 1); PG8_SCHED; PG8_LDA(At, 0, 0); PG8_STAGE(PG8_SA(1, 1), a1 + hstep, voffA);
;             PG8_WAIT_V(8); PG8_WAIT_L(0); PG8_BAR; PG8_MMA(0, 0, At, B0); PG8_MMA(0, 1, At, B1); PG8_BAR; PG8_SCHED;
;             PG8_LDA(At, 0, 1); PG8_STAGE(PG8_SB(0, 0), b2, voffB); PG8_STAGE(PG8_SB(0, 1), b2 + hstep, voffB); PG8_STAGE(PG8_SA(0, 0), a2, voffA);
.LBB0_1073:
	ds_read_b128 v[154:157], v150
	ds_read_b128 v[158:161], v150 offset:1024
	ds_read_b128 v[162:165], v150 offset:2048
	ds_read_b128 v[168:171], v150 offset:3072
	ds_read_b128 v[172:175], v151
	ds_read_b128 v[182:185], v151 offset:1024
	ds_read_b128 v[186:189], v151 offset:2048
	ds_read_b128 v[190:193], v151 offset:3072
	s_add_u32 s30, s28, 0xfffc0080
	s_addc_u32 s31, s29, -1
	s_cmp_eq_u32 s54, 12
	s_cselect_b32 s35, s21, s31
	s_cselect_b32 s34, s33, s30
	s_cselect_b32 s31, s19, s53
	s_cselect_b32 s30, s51, s52
	v_lshl_add_u64 v[148:149], s[28:29], 0, v[140:141]
	s_add_i32 m0, s41, 0xc000
	ds_read_b128 v[194:197], v152
	ds_read_b128 v[198:201], v152 offset:1024
	ds_read_b128 v[202:205], v152 offset:2048
	ds_read_b128 v[206:209], v152 offset:3072
	ds_read_b128 v[210:213], v152 offset:4096
	ds_read_b128 v[214:217], v152 offset:5120
	ds_read_b128 v[218:221], v152 offset:6144
	ds_read_b128 v[222:225], v152 offset:7168
	global_load_lds_dwordx4 v[148:149], off
	v_lshl_add_u64 v[148:149], s[28:29], 0, v[142:143]
	s_add_i32 m0, s41, 0xe000
	s_nop 0
	global_load_lds_dwordx4 v[148:149], off
	s_waitcnt vmcnt(8)
	s_barrier
	s_setprio 1
	s_waitcnt lgkmcnt(0)
	v_mfma_f32_16x16x32_bf16 v[124:127], v[154:157], v[194:197], v[124:127]
	v_mfma_f32_16x16x32_bf16 v[120:123], v[162:165], v[194:197], v[120:123]
	v_mfma_f32_16x16x32_bf16 v[108:111], v[154:157], v[202:205], v[108:111]
	v_mfma_f32_16x16x32_bf16 v[104:107], v[162:165], v[202:205], v[104:107]
	v_mfma_f32_16x16x32_bf16 v[92:95], v[154:157], v[210:213], v[92:95]
	v_mfma_f32_16x16x32_bf16 v[88:91], v[162:165], v[210:213], v[88:91]
	v_mfma_f32_16x16x32_bf16 v[76:79], v[154:157], v[218:221], v[76:79]
	v_mfma_f32_16x16x32_bf16 v[72:75], v[162:165], v[218:221], v[72:75]
	v_mfma_f32_16x16x32_bf16 v[124:127], v[158:161], v[198:201], v[124:127]
	v_mfma_f32_16x16x32_bf16 v[120:123], v[168:171], v[198:201], v[120:123]
	v_mfma_f32_16x16x32_bf16 v[108:111], v[158:161], v[206:209], v[108:111]
	v_mfma_f32_16x16x32_bf16 v[104:107], v[168:171], v[206:209], v[104:107]
	v_mfma_f32_16x16x32_bf16 v[92:95], v[158:161], v[214:217], v[92:95]
	v_mfma_f32_16x16x32_bf16 v[88:91], v[168:171], v[214:217], v[88:91]
	v_mfma_f32_16x16x32_bf16 v[76:79], v[158:161], v[222:225], v[76:79]
	v_mfma_f32_16x16x32_bf16 v[72:75], v[168:171], v[222:225], v[72:75]
	s_setprio 0
	s_setprio 1
	v_mfma_f32_16x16x32_bf16 v[116:119], v[172:175], v[194:197], v[116:119]
	v_mfma_f32_16x16x32_bf16 v[112:115], v[186:189], v[194:197], v[112:115]
	v_mfma_f32_16x16x32_bf16 v[100:103], v[172:175], v[202:205], v[100:103]
	v_mfma_f32_16x16x32_bf16 v[96:99], v[186:189], v[202:205], v[96:99]
	v_mfma_f32_16x16x32_bf16 v[84:87], v[172:175], v[210:213], v[84:87]
	v_mfma_f32_16x16x32_bf16 v[80:83], v[186:189], v[210:213], v[80:83]
	v_mfma_f32_16x16x32_bf16 v[68:71], v[172:175], v[218:221], v[68:71]
	v_mfma_f32_16x16x32_bf16 v[64:67], v[186:189], v[218:221], v[64:67]
	v_mfma_f32_16x16x32_bf16 v[116:119], v[182:185], v[198:201], v[116:119]
	v_mfma_f32_16x16x32_bf16 v[112:115], v[190:193], v[198:201], v[112:115]
	v_mfma_f32_16x16x32_bf16 v[100:103], v[182:185], v[206:209], v[100:103]
	v_mfma_f32_16x16x32_bf16 v[96:99], v[190:193], v[206:209], v[96:99]
	v_mfma_f32_16x16x32_bf16 v[84:87], v[182:185], v[214:217], v[84:87]
	v_mfma_f32_16x16x32_bf16 v[80:83], v[190:193], v[214:217], v[80:83]
	v_mfma_f32_16x16x32_bf16 v[68:71], v[182:185], v[222:225], v[68:71]
	v_mfma_f32_16x16x32_bf16 v[64:67], v[190:193], v[222:225], v[64:67]
	s_setprio 0
	s_barrier
	s_add_i32 s55, s49, s40
	v_lshl_add_u64 v[148:149], s[30:31], 0, v[130:131]
	s_mov_b32 m0, s55
	ds_read_b128 v[194:197], v152 offset:16384
	ds_read_b128 v[198:201], v152 offset:17408
	ds_read_b128 v[202:205], v152 offset:18432
	ds_read_b128 v[206:209], v152 offset:19456
	ds_read_b128 v[210:213], v152 offset:20480
	ds_read_b128 v[214:217], v152 offset:21504
	ds_read_b128 v[218:221], v152 offset:22528
	ds_read_b128 v[222:225], v152 offset:23552
	global_load_lds_dwordx4 v[148:149], off
	s_add_i32 m0, s55, 0x2000
	s_add_u32 s56, s30, 0x40000
	v_lshl_add_u64 v[176:177], s[30:31], 0, v[134:135]
	s_addc_u32 s57, s31, 0
	s_add_i32 s55, s50, s40
	global_load_lds_dwordx4 v[176:177], off
	v_lshl_add_u64 v[226:227], s[56:57], 0, v[130:131]
	s_mov_b32 m0, s55
	v_lshl_add_u64 v[228:229], s[34:35], 0, v[132:133]
	global_load_lds_dwordx4 v[226:227], off
	v_lshl_add_u64 v[226:227], s[56:57], 0, v[134:135]
	s_add_i32 m0, s55, 0x2000
	s_nop 0
	global_load_lds_dwordx4 v[226:227], off
	v_lshl_add_u64 v[226:227], s[34:35], 0, v[128:129]
	s_mov_b32 m0, s41
	s_nop 0
	global_load_lds_dwordx4 v[226:227], off
	s_mov_b32 m0, s42
	s_nop 0
	global_load_lds_dwordx4 v[228:229], off
	s_waitcnt vmcnt(8)
	s_barrier
; #define PG8_STAGE(bufoff, gbase, voff) do { _Pragma("unroll") for (int _i = 0; _i < 2; ++_i) \
;         __builtin_amdgcn_global_load_lds((const unsigned*)((const char*)(gbase) + (voff)[_i]), (PG8_LAS unsigned*)(lds + (bufoff) + ldsw + _i * 8192), 16, 0, 0); } while (0)
; #define PG8_LDA(dst, b, h) do { _Pragma("unroll") for (int m = 0; m < 4; ++m) _Pragma("unroll") for (int k = 0; k < 2; ++k) dst[m][k] = *(const PG8_LAS bf16x8*)(lds + PG8_SA(b, h) + aoff + m * 2048 + k * 1024); } while (0)
; #define PG8_LDB(dst, b, h) do { _Pragma("unroll") for (int n = 0; n < 2; ++n) _Pragma("unroll") for (int k = 0; k < 2; ++k) dst[n][k] = *(const PG8_LAS bf16x8*)(lds + PG8_SB(b, h) + boff + n * 2048 + k * 1024); } while (0)
; #define PG8_MMA(ai, bj, At, Bt) do { __builtin_amdgcn_s_setprio(1); _Pragma("unroll") for (int m = 0; m < 4; ++m) _Pragma("unroll") for (int n = 0; n < 2; ++n) _Pragma("unroll") for (int k = 0; k < 2; ++k) \
;         acc[ai][bj][m][n] = __builtin_amdgcn_mfma_f32_16x16x32_bf16(Bt[n][k], At[m][k], acc[ai][bj][m][n], 0, 0, 0); __builtin_amdgcn_s_setprio(0); } while (0)
; #define PG8_WAIT_V(n) asm volatile("s_waitcnt vmcnt(" #n ")" ::: "memory")
; #define PG8_WAIT_L(n) asm volatile("s_waitcnt lgkmcnt(" #n ")" ::: "memory")
; #define PG8_BAR __builtin_amdgcn_s_barrier()
; #define PG8_SCHED __builtin_amdgcn_sched_barrier(0)
; template <class Epi, class Sched, bool ALIGN_EPI = false, bool SP2 = false>
; __device__ __forceinline__ void gemm_phase(PG8_LAS unsigned char* lds, const Gemm g, const Sched& S, const Epi& E) {
;     ...
;             PG8_WAIT_V(8); PG8_WAIT_L(0); PG8_BAR; PG8_MMA(1, 0, At, B0); PG8_MMA(1, 1, At, B1); PG8_BAR; PG8_SCHED;
;             PG8_LDB(B0, 1, 0); PG8_LDB(B1, 1, 1); PG8_SCHED; PG8_LDA(At, 1, 0); PG8_STAGE(PG8_SA(0, 1), a2 + hstep, voffA);
;             PG8_WAIT_V(8); PG8_WAIT_L(0); PG8_BAR; PG8_MMA(0, 0, At, B0); PG8_MMA(0, 1, At, B1); PG8_BAR; PG8_SCHED;
	s_setprio 1
	s_waitcnt lgkmcnt(0)
	v_mfma_f32_16x16x32_bf16 v[60:63], v[154:157], v[194:197], v[60:63]
	v_mfma_f32_16x16x32_bf16 v[56:59], v[162:165], v[194:197], v[56:59]
	v_mfma_f32_16x16x32_bf16 v[44:47], v[154:157], v[202:205], v[44:47]
	v_mfma_f32_16x16x32_bf16 v[40:43], v[162:165], v[202:205], v[40:43]
	v_mfma_f32_16x16x32_bf16 v[28:31], v[154:157], v[210:213], v[28:31]
	v_mfma_f32_16x16x32_bf16 v[24:27], v[162:165], v[210:213], v[24:27]
	v_mfma_f32_16x16x32_bf16 v[12:15], v[154:157], v[218:221], v[12:15]
	v_mfma_f32_16x16x32_bf16 v[8:11], v[162:165], v[218:221], v[8:11]
	v_mfma_f32_16x16x32_bf16 v[60:63], v[158:161], v[198:201], v[60:63]
	v_mfma_f32_16x16x32_bf16 v[56:59], v[168:171], v[198:201], v[56:59]
	v_mfma_f32_16x16x32_bf16 v[44:47], v[158:161], v[206:209], v[44:47]
	v_mfma_f32_16x16x32_bf16 v[40:43], v[168:171], v[206:209], v[40:43]
	v_mfma_f32_16x16x32_bf16 v[28:31], v[158:161], v[214:217], v[28:31]
	v_mfma_f32_16x16x32_bf16 v[24:27], v[168:171], v[214:217], v[24:27]
	v_mfma_f32_16x16x32_bf16 v[12:15], v[158:161], v[222:225], v[12:15]
	v_mfma_f32_16x16x32_bf16 v[8:11], v[168:171], v[222:225], v[8:11]
	s_setprio 0
	s_setprio 1
	v_mfma_f32_16x16x32_bf16 v[52:55], v[172:175], v[194:197], v[52:55]
	v_mfma_f32_16x16x32_bf16 v[48:51], v[186:189], v[194:197], v[48:51]
	v_mfma_f32_16x16x32_bf16 v[36:39], v[172:175], v[202:205], v[36:39]
	v_mfma_f32_16x16x32_bf16 v[32:35], v[186:189], v[202:205], v[32:35]
	v_mfma_f32_16x16x32_bf16 v[20:23], v[172:175], v[210:213], v[20:23]
	v_mfma_f32_16x16x32_bf16 v[16:19], v[186:189], v[210:213], v[16:19]
	v_mfma_f32_16x16x32_bf16 v[4:7], v[172:175], v[218:221], v[4:7]
	v_mfma_f32_16x16x32_bf16 v[0:3], v[186:189], v[218:221], v[0:3]
	v_mfma_f32_16x16x32_bf16 v[52:55], v[182:185], v[198:201], v[52:55]
	v_mfma_f32_16x16x32_bf16 v[48:51], v[190:193], v[198:201], v[48:51]
	v_mfma_f32_16x16x32_bf16 v[36:39], v[182:185], v[206:209], v[36:39]
	v_mfma_f32_16x16x32_bf16 v[32:35], v[190:193], v[206:209], v[32:35]
	v_mfma_f32_16x16x32_bf16 v[20:23], v[182:185], v[214:217], v[20:23]
	v_mfma_f32_16x16x32_bf16 v[16:19], v[190:193], v[214:217], v[16:19]
	v_mfma_f32_16x16x32_bf16 v[4:7], v[182:185], v[222:225], v[4:7]
	v_mfma_f32_16x16x32_bf16 v[0:3], v[190:193], v[222:225], v[0:3]
	s_setprio 0
	s_barrier
	s_add_i32 s55, 0, 0x18000
	v_add_u32_e32 v153, s55, v139
	s_add_i32 s56, 0, 0x1c000
	ds_read_b128 v[154:157], v153
	ds_read_b128 v[158:161], v153 offset:1024
	ds_read_b128 v[162:165], v153 offset:2048
	ds_read_b128 v[168:171], v153 offset:3072
	v_add_u32_e32 v153, s56, v139
	ds_read_b128 v[172:175], v153
	ds_read_b128 v[182:185], v153 offset:1024
	ds_read_b128 v[186:189], v153 offset:2048
	ds_read_b128 v[190:193], v153 offset:3072
	s_add_u32 s34, s34, 0x40000
	s_addc_u32 s35, s35, 0
	s_mov_b32 m0, s43
	v_lshl_add_u64 v[230:231], s[34:35], 0, v[128:129]
	ds_read_b128 v[194:197], v152 offset:32768
	ds_read_b128 v[198:201], v152 offset:33792
	ds_read_b128 v[202:205], v152 offset:34816
	ds_read_b128 v[206:209], v152 offset:35840
	ds_read_b128 v[210:213], v152 offset:36864
	ds_read_b128 v[214:217], v152 offset:37888
	ds_read_b128 v[218:221], v152 offset:38912
	ds_read_b128 v[222:225], v152 offset:39936
	global_load_lds_dwordx4 v[230:231], off
	v_lshl_add_u64 v[230:231], s[34:35], 0, v[132:133]
	s_mov_b32 m0, s44
	s_nop 0
	global_load_lds_dwordx4 v[230:231], off
	s_waitcnt vmcnt(8)
	s_barrier
	s_setprio 1
	s_waitcnt lgkmcnt(0)
	v_mfma_f32_16x16x32_bf16 v[124:127], v[154:157], v[194:197], v[124:127]
	v_mfma_f32_16x16x32_bf16 v[120:123], v[162:165], v[194:197], v[120:123]
	v_mfma_f32_16x16x32_bf16 v[108:111], v[154:157], v[202:205], v[108:111]
	v_mfma_f32_16x16x32_bf16 v[104:107], v[162:165], v[202:205], v[104:107]
	v_mfma_f32_16x16x32_bf16 v[92:95], v[154:157], v[210:213], v[92:95]
	v_mfma_f32_16x16x32_bf16 v[88:91], v[162:165], v[210:213], v[88:91]
	v_mfma_f32_16x16x32_bf16 v[76:79], v[154:157], v[218:221], v[76:79]
	v_mfma_f32_16x16x32_bf16 v[72:75], v[162:165], v[218:221], v[72:75]
	v_mfma_f32_16x16x32_bf16 v[124:127], v[158:161], v[198:201], v[124:127]
	v_mfma_f32_16x16x32_bf16 v[120:123], v[168:171], v[198:201], v[120:123]
	v_mfma_f32_16x16x32_bf16 v[108:111], v[158:161], v[206:209], v[108:111]
	v_mfma_f32_16x16x32_bf16 v[104:107], v[168:171], v[206:209], v[104:107]
	v_mfma_f32_16x16x32_bf16 v[92:95], v[158:161], v[214:217], v[92:95]
	v_mfma_f32_16x16x32_bf16 v[88:91], v[168:171], v[214:217], v[88:91]
	v_mfma_f32_16x16x32_bf16 v[76:79], v[158:161], v[222:225], v[76:79]
	v_mfma_f32_16x16x32_bf16 v[72:75], v[168:171], v[222:225], v[72:75]
	s_setprio 0
	s_setprio 1
	v_mfma_f32_16x16x32_bf16 v[116:119], v[172:175], v[194:197], v[116:119]
	v_mfma_f32_16x16x32_bf16 v[112:115], v[186:189], v[194:197], v[112:115]
	v_mfma_f32_16x16x32_bf16 v[100:103], v[172:175], v[202:205], v[100:103]
	v_mfma_f32_16x16x32_bf16 v[96:99], v[186:189], v[202:205], v[96:99]
	v_mfma_f32_16x16x32_bf16 v[84:87], v[172:175], v[210:213], v[84:87]
	v_mfma_f32_16x16x32_bf16 v[80:83], v[186:189], v[210:213], v[80:83]
	v_mfma_f32_16x16x32_bf16 v[68:71], v[172:175], v[218:221], v[68:71]
	v_mfma_f32_16x16x32_bf16 v[64:67], v[186:189], v[218:221], v[64:67]
	v_mfma_f32_16x16x32_bf16 v[116:119], v[182:185], v[198:201], v[116:119]
	v_mfma_f32_16x16x32_bf16 v[112:115], v[190:193], v[198:201], v[112:115]
	v_mfma_f32_16x16x32_bf16 v[100:103], v[182:185], v[206:209], v[100:103]
	v_mfma_f32_16x16x32_bf16 v[96:99], v[190:193], v[206:209], v[96:99]
	v_mfma_f32_16x16x32_bf16 v[84:87], v[182:185], v[214:217], v[84:87]
	v_mfma_f32_16x16x32_bf16 v[80:83], v[190:193], v[214:217], v[80:83]
	v_mfma_f32_16x16x32_bf16 v[68:71], v[182:185], v[222:225], v[68:71]
	v_mfma_f32_16x16x32_bf16 v[64:67], v[190:193], v[222:225], v[64:67]
	s_setprio 0
	s_barrier
; #define PG8_STAGE(bufoff, gbase, voff) do { _Pragma("unroll") for (int _i = 0; _i < 2; ++_i) \
;         __builtin_amdgcn_global_load_lds((const unsigned*)((const char*)(gbase) + (voff)[_i]), (PG8_LAS unsigned*)(lds + (bufoff) + ldsw + _i * 8192), 16, 0, 0); } while (0)
; #define PG8_LDA(dst, b, h) do { _Pragma("unroll") for (int m = 0; m < 4; ++m) _Pragma("unroll") for (int k = 0; k < 2; ++k) dst[m][k] = *(const PG8_LAS bf16x8*)(lds + PG8_SA(b, h) + aoff + m * 2048 + k * 1024); } while (0)
; #define PG8_MMA(ai, bj, At, Bt) do { __builtin_amdgcn_s_setprio(1); _Pragma("unroll") for (int m = 0; m < 4; ++m) _Pragma("unroll") for (int n = 0; n < 2; ++n) _Pragma("unroll") for (int k = 0; k < 2; ++k) \
;         acc[ai][bj][m][n] = __builtin_amdgcn_mfma_f32_16x16x32_bf16(Bt[n][k], At[m][k], acc[ai][bj][m][n], 0, 0, 0); __builtin_amdgcn_s_setprio(0); } while (0)
; #define PG8_WAIT_V(n) asm volatile("s_waitcnt vmcnt(" #n ")" ::: "memory")
; #define PG8_WAIT_L(n) asm volatile("s_waitcnt lgkmcnt(" #n ")" ::: "memory")
; #define PG8_BAR __builtin_amdgcn_s_barrier()
; #define PG8_SCHED __builtin_amdgcn_sched_barrier(0)
; template <class Epi, class Sched, bool ALIGN_EPI = false, bool SP2 = false>
; __device__ __forceinline__ void gemm_phase(PG8_LAS unsigned char* lds, const Gemm g, const Sched& S, const Epi& E) {
;     ...
;             PG8_LDA(At, 1, 1); PG8_STAGE(PG8_SB(1, 0), b3, voffB); PG8_STAGE(PG8_SB(1, 1), b3 + hstep, voffB); PG8_STAGE(PG8_SA(1, 0), a3, voffA);
;             PG8_WAIT_V(8); PG8_WAIT_L(0); PG8_BAR; PG8_MMA(1, 0, At, B0); PG8_MMA(1, 1, At, B1); PG8_BAR; PG8_SCHED;
	s_add_i32 s34, s55, s40
	v_lshl_add_u64 v[148:149], v[148:149], 0, s[14:15]
	s_mov_b32 m0, s34
	ds_read_b128 v[194:197], v152 offset:49152
	ds_read_b128 v[198:201], v152 offset:50176
	ds_read_b128 v[202:205], v152 offset:51200
	ds_read_b128 v[206:209], v152 offset:52224
	ds_read_b128 v[210:213], v152 offset:53248
	ds_read_b128 v[214:217], v152 offset:54272
	ds_read_b128 v[218:221], v152 offset:55296
	ds_read_b128 v[222:225], v152 offset:56320
	global_load_lds_dwordx4 v[148:149], off
	s_add_i32 m0, s34, 0x2000
	s_add_u32 s30, s30, 0x40080
	v_lshl_add_u64 v[148:149], v[176:177], 0, s[14:15]
	s_addc_u32 s31, s31, 0
	s_add_i32 s34, s56, s40
	global_load_lds_dwordx4 v[148:149], off
	v_lshl_add_u64 v[148:149], s[30:31], 0, v[130:131]
	s_mov_b32 m0, s34
	s_nop 0
	global_load_lds_dwordx4 v[148:149], off
	v_lshl_add_u64 v[148:149], s[30:31], 0, v[134:135]
	s_add_i32 m0, s34, 0x2000
	s_nop 0
	global_load_lds_dwordx4 v[148:149], off
	v_lshl_add_u64 v[148:149], v[226:227], 0, s[14:15]
	s_mov_b32 m0, s46
	s_nop 0
	global_load_lds_dwordx4 v[148:149], off
	v_lshl_add_u64 v[148:149], v[228:229], 0, s[14:15]
	s_mov_b32 m0, s47
	s_nop 0
	global_load_lds_dwordx4 v[148:149], off
	s_waitcnt vmcnt(8)
	s_barrier
	s_setprio 1
	s_waitcnt lgkmcnt(0)
	v_mfma_f32_16x16x32_bf16 v[60:63], v[154:157], v[194:197], v[60:63]
	v_mfma_f32_16x16x32_bf16 v[56:59], v[162:165], v[194:197], v[56:59]
	v_mfma_f32_16x16x32_bf16 v[44:47], v[154:157], v[202:205], v[44:47]
	v_mfma_f32_16x16x32_bf16 v[40:43], v[162:165], v[202:205], v[40:43]
	v_mfma_f32_16x16x32_bf16 v[28:31], v[154:157], v[210:213], v[28:31]
	v_mfma_f32_16x16x32_bf16 v[24:27], v[162:165], v[210:213], v[24:27]
	v_mfma_f32_16x16x32_bf16 v[12:15], v[154:157], v[218:221], v[12:15]
	v_mfma_f32_16x16x32_bf16 v[8:11], v[162:165], v[218:221], v[8:11]
	v_mfma_f32_16x16x32_bf16 v[60:63], v[158:161], v[198:201], v[60:63]
	v_mfma_f32_16x16x32_bf16 v[56:59], v[168:171], v[198:201], v[56:59]
	v_mfma_f32_16x16x32_bf16 v[44:47], v[158:161], v[206:209], v[44:47]
	v_mfma_f32_16x16x32_bf16 v[40:43], v[168:171], v[206:209], v[40:43]
	v_mfma_f32_16x16x32_bf16 v[28:31], v[158:161], v[214:217], v[28:31]
	v_mfma_f32_16x16x32_bf16 v[24:27], v[168:171], v[214:217], v[24:27]
	v_mfma_f32_16x16x32_bf16 v[12:15], v[158:161], v[222:225], v[12:15]
	v_mfma_f32_16x16x32_bf16 v[8:11], v[168:171], v[222:225], v[8:11]
	s_setprio 0
	s_setprio 1
	v_mfma_f32_16x16x32_bf16 v[52:55], v[172:175], v[194:197], v[52:55]
	v_mfma_f32_16x16x32_bf16 v[48:51], v[186:189], v[194:197], v[48:51]
	v_mfma_f32_16x16x32_bf16 v[36:39], v[172:175], v[202:205], v[36:39]
	v_mfma_f32_16x16x32_bf16 v[32:35], v[186:189], v[202:205], v[32:35]
	v_mfma_f32_16x16x32_bf16 v[20:23], v[172:175], v[210:213], v[20:23]
	v_mfma_f32_16x16x32_bf16 v[16:19], v[186:189], v[210:213], v[16:19]
	v_mfma_f32_16x16x32_bf16 v[4:7], v[172:175], v[218:221], v[4:7]
	v_mfma_f32_16x16x32_bf16 v[0:3], v[186:189], v[218:221], v[0:3]
	v_mfma_f32_16x16x32_bf16 v[52:55], v[182:185], v[198:201], v[52:55]
	v_mfma_f32_16x16x32_bf16 v[48:51], v[190:193], v[198:201], v[48:51]
	v_mfma_f32_16x16x32_bf16 v[36:39], v[182:185], v[206:209], v[36:39]
	v_mfma_f32_16x16x32_bf16 v[32:35], v[190:193], v[206:209], v[32:35]
	v_mfma_f32_16x16x32_bf16 v[20:23], v[182:185], v[214:217], v[20:23]
	v_mfma_f32_16x16x32_bf16 v[16:19], v[190:193], v[214:217], v[16:19]
	v_mfma_f32_16x16x32_bf16 v[4:7], v[182:185], v[222:225], v[4:7]
	v_mfma_f32_16x16x32_bf16 v[0:3], v[190:193], v[222:225], v[0:3]
	s_setprio 0
	s_barrier
	s_add_i32 s54, s54, 2
	s_add_u32 s28, s28, 0x100
	s_addc_u32 s29, s29, 0
	s_add_u32 s52, s52, 0x100
	s_addc_u32 s53, s53, 0
	s_cmp_gt_u32 s54, 13
	s_cbranch_scc0 .LBB0_1073
	s_and_b64 vcc, exec, s[16:17]
	s_cbranch_vccz .LBB0_1076
	s_barrier

; #define PG8_STAGE(bufoff, gbase, voff) do { _Pragma("unroll") for (int _i = 0; _i < 2; ++_i) \
;         __builtin_amdgcn_global_load_lds((const unsigned*)((const char*)(gbase) + (voff)[_i]), (PG8_LAS unsigned*)(lds + (bufoff) + ldsw + _i * 8192), 16, 0, 0); } while (0)
; #define PG8_LDA(dst, b, h) do { _Pragma("unroll") for (int m = 0; m < 4; ++m) _Pragma("unroll") for (int k = 0; k < 2; ++k) dst[m][k] = *(const PG8_LAS bf16x8*)(lds + PG8_SA(b, h) + aoff + m * 2048 + k * 1024); } while (0)
; #define PG8_LDB(dst, b, h) do { _Pragma("unroll") for (int n = 0; n < 2; ++n) _Pragma("unroll") for (int k = 0; k < 2; ++k) dst[n][k] = *(const PG8_LAS bf16x8*)(lds + PG8_SB(b, h) + boff + n * 2048 + k * 1024); } while (0)
; #define PG8_MMA(ai, bj, At, Bt) do { __builtin_amdgcn_s_setprio(1); _Pragma("unroll") for (int m = 0; m < 4; ++m) _Pragma("unroll") for (int n = 0; n < 2; ++n) _Pragma("unroll") for (int k = 0; k < 2; ++k) \
;         acc[ai][bj][m][n] = __builtin_amdgcn_mfma_f32_16x16x32_bf16(Bt[n][k], At[m][k], acc[ai][bj][m][n], 0, 0, 0); __builtin_amdgcn_s_setprio(0); } while (0)
; #define PG8_WAIT_V(n) asm volatile("s_waitcnt vmcnt(" #n ")" ::: "memory")
; #define PG8_WAIT_L(n) asm volatile("s_waitcnt lgkmcnt(" #n ")" ::: "memory")
; #define PG8_BAR __builtin_amdgcn_s_barrier()
; #define PG8_SCHED __builtin_amdgcn_sched_barrier(0)
; template <class Epi, class Sched, bool ALIGN_EPI = false, bool SP2 = false>
; __device__ __forceinline__ void gemm_phase(PG8_LAS unsigned char* lds, const Gemm g, const Sched& S, const Epi& E) {
;     ...
;             const char* a2 = last ? nA : cA + (size_t)(t + 2) * kstep; const char* b2 = last ? nB : cB + (size_t)(t + 2) * kstep;
;             const char* a3 = a2 + kstep; const char* b3 = b2 + kstep;
;             if (last && has_next) S.a_ready(nxt);
;             if constexpr (SP2) {
;             PG8_LDB(B0, 0, 0); PG8_LDB(B1, 0, 1); PG8_SCHED; PG8_LDA(At, 0, 0); PG8_STAGE(PG8_SA(1, 1), a1 + hstep, voffA);
;             PG8_WAIT_V(8); PG8_WAIT_L(0); PG8_BAR; PG8_MMA(0, 0, At, B0); PG8_MMA(0, 1, At, B1); PG8_BAR; PG8_SCHED;
;             PG8_LDA(At, 0, 1); PG8_STAGE(PG8_SB(0, 0), b2, voffB); PG8_STAGE(PG8_SB(0, 1), b2 + hstep, voffB); PG8_STAGE(PG8_SA(0, 0), a2, voffA);
.LBB0_1151:
	ds_read_b128 v[154:157], v150
	ds_read_b128 v[158:161], v150 offset:1024
	ds_read_b128 v[162:165], v150 offset:2048
	ds_read_b128 v[168:171], v150 offset:3072
	ds_read_b128 v[172:175], v151
	ds_read_b128 v[182:185], v151 offset:1024
	ds_read_b128 v[186:189], v151 offset:2048
	ds_read_b128 v[190:193], v151 offset:3072
	s_add_u32 s36, s34, 0xfff80080
	s_addc_u32 s37, s35, -1
	s_cmp_eq_u32 s56, 28
	s_cselect_b32 s39, s23, s37
	s_cselect_b32 s38, s29, s36
	s_cselect_b32 s37, s21, s55
	s_cselect_b32 s36, s31, s54
	v_lshl_add_u64 v[146:147], s[34:35], 0, v[138:139]
	s_add_i32 m0, s43, 0xc000
	ds_read_b128 v[194:197], v152
	ds_read_b128 v[198:201], v152 offset:1024
	ds_read_b128 v[202:205], v152 offset:2048
	ds_read_b128 v[206:209], v152 offset:3072
	ds_read_b128 v[210:213], v152 offset:4096
	ds_read_b128 v[214:217], v152 offset:5120
	ds_read_b128 v[218:221], v152 offset:6144
	ds_read_b128 v[222:225], v152 offset:7168
	global_load_lds_dwordx4 v[146:147], off
	v_lshl_add_u64 v[146:147], s[34:35], 0, v[140:141]
	s_add_i32 m0, s43, 0xe000
	s_nop 0
	global_load_lds_dwordx4 v[146:147], off
	s_waitcnt vmcnt(8)
	s_barrier
	s_setprio 1
	s_waitcnt lgkmcnt(0)
	v_mfma_f32_16x16x32_bf16 v[124:127], v[154:157], v[194:197], v[124:127]
	v_mfma_f32_16x16x32_bf16 v[120:123], v[162:165], v[194:197], v[120:123]
	v_mfma_f32_16x16x32_bf16 v[108:111], v[154:157], v[202:205], v[108:111]
	v_mfma_f32_16x16x32_bf16 v[104:107], v[162:165], v[202:205], v[104:107]
	v_mfma_f32_16x16x32_bf16 v[92:95], v[154:157], v[210:213], v[92:95]
	v_mfma_f32_16x16x32_bf16 v[88:91], v[162:165], v[210:213], v[88:91]
	v_mfma_f32_16x16x32_bf16 v[76:79], v[154:157], v[218:221], v[76:79]
	v_mfma_f32_16x16x32_bf16 v[72:75], v[162:165], v[218:221], v[72:75]
	v_mfma_f32_16x16x32_bf16 v[124:127], v[158:161], v[198:201], v[124:127]
	v_mfma_f32_16x16x32_bf16 v[120:123], v[168:171], v[198:201], v[120:123]
	v_mfma_f32_16x16x32_bf16 v[108:111], v[158:161], v[206:209], v[108:111]
	v_mfma_f32_16x16x32_bf16 v[104:107], v[168:171], v[206:209], v[104:107]
	v_mfma_f32_16x16x32_bf16 v[92:95], v[158:161], v[214:217], v[92:95]
	v_mfma_f32_16x16x32_bf16 v[88:91], v[168:171], v[214:217], v[88:91]
	v_mfma_f32_16x16x32_bf16 v[76:79], v[158:161], v[222:225], v[76:79]
	v_mfma_f32_16x16x32_bf16 v[72:75], v[168:171], v[222:225], v[72:75]
	s_setprio 0
	s_setprio 1
	v_mfma_f32_16x16x32_bf16 v[116:119], v[172:175], v[194:197], v[116:119]
	v_mfma_f32_16x16x32_bf16 v[112:115], v[186:189], v[194:197], v[112:115]
	v_mfma_f32_16x16x32_bf16 v[100:103], v[172:175], v[202:205], v[100:103]
	v_mfma_f32_16x16x32_bf16 v[96:99], v[186:189], v[202:205], v[96:99]
	v_mfma_f32_16x16x32_bf16 v[84:87], v[172:175], v[210:213], v[84:87]
	v_mfma_f32_16x16x32_bf16 v[80:83], v[186:189], v[210:213], v[80:83]
	v_mfma_f32_16x16x32_bf16 v[68:71], v[172:175], v[218:221], v[68:71]
	v_mfma_f32_16x16x32_bf16 v[64:67], v[186:189], v[218:221], v[64:67]
	v_mfma_f32_16x16x32_bf16 v[116:119], v[182:185], v[198:201], v[116:119]
	v_mfma_f32_16x16x32_bf16 v[112:115], v[190:193], v[198:201], v[112:115]
	v_mfma_f32_16x16x32_bf16 v[100:103], v[182:185], v[206:209], v[100:103]
	v_mfma_f32_16x16x32_bf16 v[96:99], v[190:193], v[206:209], v[96:99]
	v_mfma_f32_16x16x32_bf16 v[84:87], v[182:185], v[214:217], v[84:87]
	v_mfma_f32_16x16x32_bf16 v[80:83], v[190:193], v[214:217], v[80:83]
	v_mfma_f32_16x16x32_bf16 v[68:71], v[182:185], v[222:225], v[68:71]
	v_mfma_f32_16x16x32_bf16 v[64:67], v[190:193], v[222:225], v[64:67]
	s_setprio 0
	s_barrier
	s_add_i32 s57, s52, s42
	v_lshl_add_u64 v[146:147], s[36:37], 0, v[130:131]
	s_mov_b32 m0, s57
	ds_read_b128 v[194:197], v152 offset:16384
	ds_read_b128 v[198:201], v152 offset:17408
	ds_read_b128 v[202:205], v152 offset:18432
	ds_read_b128 v[206:209], v152 offset:19456
	ds_read_b128 v[210:213], v152 offset:20480
	ds_read_b128 v[214:217], v152 offset:21504
	ds_read_b128 v[218:221], v152 offset:22528
	ds_read_b128 v[222:225], v152 offset:23552
	global_load_lds_dwordx4 v[146:147], off
	s_add_i32 m0, s57, 0x2000
	s_add_u32 s58, s36, 0x80000
	v_lshl_add_u64 v[176:177], s[36:37], 0, v[134:135]
	s_addc_u32 s59, s37, 0
	s_add_i32 s57, s53, s42
	global_load_lds_dwordx4 v[176:177], off
	v_lshl_add_u64 v[226:227], s[58:59], 0, v[130:131]
	s_mov_b32 m0, s57
	v_lshl_add_u64 v[228:229], s[38:39], 0, v[132:133]
	global_load_lds_dwordx4 v[226:227], off
	v_lshl_add_u64 v[226:227], s[58:59], 0, v[134:135]
	s_add_i32 m0, s57, 0x2000
	s_nop 0
	global_load_lds_dwordx4 v[226:227], off
	v_lshl_add_u64 v[226:227], s[38:39], 0, v[128:129]
	s_mov_b32 m0, s43
	s_nop 0
	global_load_lds_dwordx4 v[226:227], off
	s_mov_b32 m0, s44
	s_nop 0
	global_load_lds_dwordx4 v[228:229], off
	s_waitcnt vmcnt(8)
	s_barrier
; #define PG8_STAGE(bufoff, gbase, voff) do { _Pragma("unroll") for (int _i = 0; _i < 2; ++_i) \
;         __builtin_amdgcn_global_load_lds((const unsigned*)((const char*)(gbase) + (voff)[_i]), (PG8_LAS unsigned*)(lds + (bufoff) + ldsw + _i * 8192), 16, 0, 0); } while (0)
; #define PG8_LDA(dst, b, h) do { _Pragma("unroll") for (int m = 0; m < 4; ++m) _Pragma("unroll") for (int k = 0; k < 2; ++k) dst[m][k] = *(const PG8_LAS bf16x8*)(lds + PG8_SA(b, h) + aoff + m * 2048 + k * 1024); } while (0)
; #define PG8_LDB(dst, b, h) do { _Pragma("unroll") for (int n = 0; n < 2; ++n) _Pragma("unroll") for (int k = 0; k < 2; ++k) dst[n][k] = *(const PG8_LAS bf16x8*)(lds + PG8_SB(b, h) + boff + n * 2048 + k * 1024); } while (0)
; #define PG8_MMA(ai, bj, At, Bt) do { __builtin_amdgcn_s_setprio(1); _Pragma("unroll") for (int m = 0; m < 4; ++m) _Pragma("unroll") for (int n = 0; n < 2; ++n) _Pragma("unroll") for (int k = 0; k < 2; ++k) \
;         acc[ai][bj][m][n] = __builtin_amdgcn_mfma_f32_16x16x32_bf16(Bt[n][k], At[m][k], acc[ai][bj][m][n], 0, 0, 0); __builtin_amdgcn_s_setprio(0); } while (0)
; #define PG8_WAIT_V(n) asm volatile("s_waitcnt vmcnt(" #n ")" ::: "memory")
; #define PG8_WAIT_L(n) asm volatile("s_waitcnt lgkmcnt(" #n ")" ::: "memory")
; #define PG8_BAR __builtin_amdgcn_s_barrier()
; #define PG8_SCHED __builtin_amdgcn_sched_barrier(0)
; template <class Epi, class Sched, bool ALIGN_EPI = false, bool SP2 = false>
; __device__ __forceinline__ void gemm_phase(PG8_LAS unsigned char* lds, const Gemm g, const Sched& S, const Epi& E) {
;     ...
;             PG8_WAIT_V(8); PG8_WAIT_L(0); PG8_BAR; PG8_MMA(1, 0, At, B0); PG8_MMA(1, 1, At, B1); PG8_BAR; PG8_SCHED;
;             PG8_LDB(B0, 1, 0); PG8_LDB(B1, 1, 1); PG8_SCHED; PG8_LDA(At, 1, 0); PG8_STAGE(PG8_SA(0, 1), a2 + hstep, voffA);
;             PG8_WAIT_V(8); PG8_WAIT_L(0); PG8_BAR; PG8_MMA(0, 0, At, B0); PG8_MMA(0, 1, At, B1); PG8_BAR; PG8_SCHED;
	s_setprio 1
	s_waitcnt lgkmcnt(0)
	v_mfma_f32_16x16x32_bf16 v[60:63], v[154:157], v[194:197], v[60:63]
	v_mfma_f32_16x16x32_bf16 v[56:59], v[162:165], v[194:197], v[56:59]
	v_mfma_f32_16x16x32_bf16 v[44:47], v[154:157], v[202:205], v[44:47]
	v_mfma_f32_16x16x32_bf16 v[40:43], v[162:165], v[202:205], v[40:43]
	v_mfma_f32_16x16x32_bf16 v[28:31], v[154:157], v[210:213], v[28:31]
	v_mfma_f32_16x16x32_bf16 v[24:27], v[162:165], v[210:213], v[24:27]
	v_mfma_f32_16x16x32_bf16 v[12:15], v[154:157], v[218:221], v[12:15]
	v_mfma_f32_16x16x32_bf16 v[8:11], v[162:165], v[218:221], v[8:11]
	v_mfma_f32_16x16x32_bf16 v[60:63], v[158:161], v[198:201], v[60:63]
	v_mfma_f32_16x16x32_bf16 v[56:59], v[168:171], v[198:201], v[56:59]
	v_mfma_f32_16x16x32_bf16 v[44:47], v[158:161], v[206:209], v[44:47]
	v_mfma_f32_16x16x32_bf16 v[40:43], v[168:171], v[206:209], v[40:43]
	v_mfma_f32_16x16x32_bf16 v[28:31], v[158:161], v[214:217], v[28:31]
	v_mfma_f32_16x16x32_bf16 v[24:27], v[168:171], v[214:217], v[24:27]
	v_mfma_f32_16x16x32_bf16 v[12:15], v[158:161], v[222:225], v[12:15]
	v_mfma_f32_16x16x32_bf16 v[8:11], v[168:171], v[222:225], v[8:11]
	s_setprio 0
	s_setprio 1
	v_mfma_f32_16x16x32_bf16 v[52:55], v[172:175], v[194:197], v[52:55]
	v_mfma_f32_16x16x32_bf16 v[48:51], v[186:189], v[194:197], v[48:51]
	v_mfma_f32_16x16x32_bf16 v[36:39], v[172:175], v[202:205], v[36:39]
	v_mfma_f32_16x16x32_bf16 v[32:35], v[186:189], v[202:205], v[32:35]
	v_mfma_f32_16x16x32_bf16 v[20:23], v[172:175], v[210:213], v[20:23]
	v_mfma_f32_16x16x32_bf16 v[16:19], v[186:189], v[210:213], v[16:19]
	v_mfma_f32_16x16x32_bf16 v[4:7], v[172:175], v[218:221], v[4:7]
	v_mfma_f32_16x16x32_bf16 v[0:3], v[186:189], v[218:221], v[0:3]
	v_mfma_f32_16x16x32_bf16 v[52:55], v[182:185], v[198:201], v[52:55]
	v_mfma_f32_16x16x32_bf16 v[48:51], v[190:193], v[198:201], v[48:51]
	v_mfma_f32_16x16x32_bf16 v[36:39], v[182:185], v[206:209], v[36:39]
	v_mfma_f32_16x16x32_bf16 v[32:35], v[190:193], v[206:209], v[32:35]
	v_mfma_f32_16x16x32_bf16 v[20:23], v[182:185], v[214:217], v[20:23]
	v_mfma_f32_16x16x32_bf16 v[16:19], v[190:193], v[214:217], v[16:19]
	v_mfma_f32_16x16x32_bf16 v[4:7], v[182:185], v[222:225], v[4:7]
	v_mfma_f32_16x16x32_bf16 v[0:3], v[190:193], v[222:225], v[0:3]
	s_setprio 0
	s_barrier
	s_add_i32 s57, 0, 0x18000
	v_add_u32_e32 v167, s57, v149
	s_add_i32 s58, 0, 0x1c000
	ds_read_b128 v[154:157], v167
	ds_read_b128 v[158:161], v167 offset:1024
	ds_read_b128 v[162:165], v167 offset:2048
	ds_read_b128 v[168:171], v167 offset:3072
	v_add_u32_e32 v167, s58, v149
	ds_read_b128 v[172:175], v167
	ds_read_b128 v[182:185], v167 offset:1024
	ds_read_b128 v[186:189], v167 offset:2048
	ds_read_b128 v[190:193], v167 offset:3072
	s_add_u32 s38, s38, 0x80000
	s_addc_u32 s39, s39, 0
	s_mov_b32 m0, s45
	v_lshl_add_u64 v[230:231], s[38:39], 0, v[128:129]
	ds_read_b128 v[194:197], v152 offset:32768
	ds_read_b128 v[198:201], v152 offset:33792
	ds_read_b128 v[202:205], v152 offset:34816
	ds_read_b128 v[206:209], v152 offset:35840
	ds_read_b128 v[210:213], v152 offset:36864
	ds_read_b128 v[214:217], v152 offset:37888
	ds_read_b128 v[218:221], v152 offset:38912
	ds_read_b128 v[222:225], v152 offset:39936
	global_load_lds_dwordx4 v[230:231], off
	v_lshl_add_u64 v[230:231], s[38:39], 0, v[132:133]
	s_mov_b32 m0, s46
	s_nop 0
	global_load_lds_dwordx4 v[230:231], off
	s_waitcnt vmcnt(8)
	s_barrier
	s_setprio 1
	s_waitcnt lgkmcnt(0)
	v_mfma_f32_16x16x32_bf16 v[124:127], v[154:157], v[194:197], v[124:127]
	v_mfma_f32_16x16x32_bf16 v[120:123], v[162:165], v[194:197], v[120:123]
	v_mfma_f32_16x16x32_bf16 v[108:111], v[154:157], v[202:205], v[108:111]
	v_mfma_f32_16x16x32_bf16 v[104:107], v[162:165], v[202:205], v[104:107]
	v_mfma_f32_16x16x32_bf16 v[92:95], v[154:157], v[210:213], v[92:95]
	v_mfma_f32_16x16x32_bf16 v[88:91], v[162:165], v[210:213], v[88:91]
	v_mfma_f32_16x16x32_bf16 v[76:79], v[154:157], v[218:221], v[76:79]
	v_mfma_f32_16x16x32_bf16 v[72:75], v[162:165], v[218:221], v[72:75]
	v_mfma_f32_16x16x32_bf16 v[124:127], v[158:161], v[198:201], v[124:127]
	v_mfma_f32_16x16x32_bf16 v[120:123], v[168:171], v[198:201], v[120:123]
	v_mfma_f32_16x16x32_bf16 v[108:111], v[158:161], v[206:209], v[108:111]
	v_mfma_f32_16x16x32_bf16 v[104:107], v[168:171], v[206:209], v[104:107]
	v_mfma_f32_16x16x32_bf16 v[92:95], v[158:161], v[214:217], v[92:95]
	v_mfma_f32_16x16x32_bf16 v[88:91], v[168:171], v[214:217], v[88:91]
	v_mfma_f32_16x16x32_bf16 v[76:79], v[158:161], v[222:225], v[76:79]
	v_mfma_f32_16x16x32_bf16 v[72:75], v[168:171], v[222:225], v[72:75]
	s_setprio 0
	s_setprio 1
	v_mfma_f32_16x16x32_bf16 v[116:119], v[172:175], v[194:197], v[116:119]
	v_mfma_f32_16x16x32_bf16 v[112:115], v[186:189], v[194:197], v[112:115]
	v_mfma_f32_16x16x32_bf16 v[100:103], v[172:175], v[202:205], v[100:103]
	v_mfma_f32_16x16x32_bf16 v[96:99], v[186:189], v[202:205], v[96:99]
	v_mfma_f32_16x16x32_bf16 v[84:87], v[172:175], v[210:213], v[84:87]
	v_mfma_f32_16x16x32_bf16 v[80:83], v[186:189], v[210:213], v[80:83]
	v_mfma_f32_16x16x32_bf16 v[68:71], v[172:175], v[218:221], v[68:71]
	v_mfma_f32_16x16x32_bf16 v[64:67], v[186:189], v[218:221], v[64:67]
	v_mfma_f32_16x16x32_bf16 v[116:119], v[182:185], v[198:201], v[116:119]
	v_mfma_f32_16x16x32_bf16 v[112:115], v[190:193], v[198:201], v[112:115]
	v_mfma_f32_16x16x32_bf16 v[100:103], v[182:185], v[206:209], v[100:103]
	v_mfma_f32_16x16x32_bf16 v[96:99], v[190:193], v[206:209], v[96:99]
	v_mfma_f32_16x16x32_bf16 v[84:87], v[182:185], v[214:217], v[84:87]
	v_mfma_f32_16x16x32_bf16 v[80:83], v[190:193], v[214:217], v[80:83]
	v_mfma_f32_16x16x32_bf16 v[68:71], v[182:185], v[222:225], v[68:71]
	v_mfma_f32_16x16x32_bf16 v[64:67], v[190:193], v[222:225], v[64:67]
	s_setprio 0
	s_barrier
; #define PG8_STAGE(bufoff, gbase, voff) do { _Pragma("unroll") for (int _i = 0; _i < 2; ++_i) \
;         __builtin_amdgcn_global_load_lds((const unsigned*)((const char*)(gbase) + (voff)[_i]), (PG8_LAS unsigned*)(lds + (bufoff) + ldsw + _i * 8192), 16, 0, 0); } while (0)
; #define PG8_LDA(dst, b, h) do { _Pragma("unroll") for (int m = 0; m < 4; ++m) _Pragma("unroll") for (int k = 0; k < 2; ++k) dst[m][k] = *(const PG8_LAS bf16x8*)(lds + PG8_SA(b, h) + aoff + m * 2048 + k * 1024); } while (0)
; #define PG8_MMA(ai, bj, At, Bt) do { __builtin_amdgcn_s_setprio(1); _Pragma("unroll") for (int m = 0; m < 4; ++m) _Pragma("unroll") for (int n = 0; n < 2; ++n) _Pragma("unroll") for (int k = 0; k < 2; ++k) \
;         acc[ai][bj][m][n] = __builtin_amdgcn_mfma_f32_16x16x32_bf16(Bt[n][k], At[m][k], acc[ai][bj][m][n], 0, 0, 0); __builtin_amdgcn_s_setprio(0); } while (0)
; #define PG8_WAIT_V(n) asm volatile("s_waitcnt vmcnt(" #n ")" ::: "memory")
; #define PG8_WAIT_L(n) asm volatile("s_waitcnt lgkmcnt(" #n ")" ::: "memory")
; #define PG8_BAR __builtin_amdgcn_s_barrier()
; #define PG8_SCHED __builtin_amdgcn_sched_barrier(0)
; template <class Epi, class Sched, bool ALIGN_EPI = false, bool SP2 = false>
; __device__ __forceinline__ void gemm_phase(PG8_LAS unsigned char* lds, const Gemm g, const Sched& S, const Epi& E) {
;     ...
;             PG8_LDA(At, 1, 1); PG8_STAGE(PG8_SB(1, 0), b3, voffB); PG8_STAGE(PG8_SB(1, 1), b3 + hstep, voffB); PG8_STAGE(PG8_SA(1, 0), a3, voffA);
;             PG8_WAIT_V(8); PG8_WAIT_L(0); PG8_BAR; PG8_MMA(1, 0, At, B0); PG8_MMA(1, 1, At, B1); PG8_BAR; PG8_SCHED;
	s_add_i32 s38, s57, s42
	v_lshl_add_u64 v[146:147], v[146:147], 0, s[16:17]
	s_mov_b32 m0, s38
	ds_read_b128 v[194:197], v152 offset:49152
	ds_read_b128 v[198:201], v152 offset:50176
	ds_read_b128 v[202:205], v152 offset:51200
	ds_read_b128 v[206:209], v152 offset:52224
	ds_read_b128 v[210:213], v152 offset:53248
	ds_read_b128 v[214:217], v152 offset:54272
	ds_read_b128 v[218:221], v152 offset:55296
	ds_read_b128 v[222:225], v152 offset:56320
	global_load_lds_dwordx4 v[146:147], off
	s_add_i32 m0, s38, 0x2000
	s_add_u32 s36, s36, 0x80080
	v_lshl_add_u64 v[146:147], v[176:177], 0, s[16:17]
	s_addc_u32 s37, s37, 0
	s_add_i32 s38, s58, s42
	global_load_lds_dwordx4 v[146:147], off
	v_lshl_add_u64 v[146:147], s[36:37], 0, v[130:131]
	s_mov_b32 m0, s38
	s_nop 0
	global_load_lds_dwordx4 v[146:147], off
	v_lshl_add_u64 v[146:147], s[36:37], 0, v[134:135]
	s_add_i32 m0, s38, 0x2000
	s_nop 0
	global_load_lds_dwordx4 v[146:147], off
	v_lshl_add_u64 v[146:147], v[226:227], 0, s[16:17]
	s_mov_b32 m0, s48
	s_nop 0
	global_load_lds_dwordx4 v[146:147], off
	v_lshl_add_u64 v[146:147], v[228:229], 0, s[16:17]
	s_mov_b32 m0, s49
	s_nop 0
	global_load_lds_dwordx4 v[146:147], off
	s_waitcnt vmcnt(8)
	s_barrier
	s_setprio 1
	s_waitcnt lgkmcnt(0)
	v_mfma_f32_16x16x32_bf16 v[60:63], v[154:157], v[194:197], v[60:63]
	v_mfma_f32_16x16x32_bf16 v[56:59], v[162:165], v[194:197], v[56:59]
	v_mfma_f32_16x16x32_bf16 v[44:47], v[154:157], v[202:205], v[44:47]
	v_mfma_f32_16x16x32_bf16 v[40:43], v[162:165], v[202:205], v[40:43]
	v_mfma_f32_16x16x32_bf16 v[28:31], v[154:157], v[210:213], v[28:31]
	v_mfma_f32_16x16x32_bf16 v[24:27], v[162:165], v[210:213], v[24:27]
	v_mfma_f32_16x16x32_bf16 v[12:15], v[154:157], v[218:221], v[12:15]
	v_mfma_f32_16x16x32_bf16 v[8:11], v[162:165], v[218:221], v[8:11]
	v_mfma_f32_16x16x32_bf16 v[60:63], v[158:161], v[198:201], v[60:63]
	v_mfma_f32_16x16x32_bf16 v[56:59], v[168:171], v[198:201], v[56:59]
	v_mfma_f32_16x16x32_bf16 v[44:47], v[158:161], v[206:209], v[44:47]
	v_mfma_f32_16x16x32_bf16 v[40:43], v[168:171], v[206:209], v[40:43]
	v_mfma_f32_16x16x32_bf16 v[28:31], v[158:161], v[214:217], v[28:31]
	v_mfma_f32_16x16x32_bf16 v[24:27], v[168:171], v[214:217], v[24:27]
	v_mfma_f32_16x16x32_bf16 v[12:15], v[158:161], v[222:225], v[12:15]
	v_mfma_f32_16x16x32_bf16 v[8:11], v[168:171], v[222:225], v[8:11]
	s_setprio 0
	s_setprio 1
	v_mfma_f32_16x16x32_bf16 v[52:55], v[172:175], v[194:197], v[52:55]
	v_mfma_f32_16x16x32_bf16 v[48:51], v[186:189], v[194:197], v[48:51]
	v_mfma_f32_16x16x32_bf16 v[36:39], v[172:175], v[202:205], v[36:39]
	v_mfma_f32_16x16x32_bf16 v[32:35], v[186:189], v[202:205], v[32:35]
	v_mfma_f32_16x16x32_bf16 v[20:23], v[172:175], v[210:213], v[20:23]
	v_mfma_f32_16x16x32_bf16 v[16:19], v[186:189], v[210:213], v[16:19]
	v_mfma_f32_16x16x32_bf16 v[4:7], v[172:175], v[218:221], v[4:7]
	v_mfma_f32_16x16x32_bf16 v[0:3], v[186:189], v[218:221], v[0:3]
	v_mfma_f32_16x16x32_bf16 v[52:55], v[182:185], v[198:201], v[52:55]
	v_mfma_f32_16x16x32_bf16 v[48:51], v[190:193], v[198:201], v[48:51]
	v_mfma_f32_16x16x32_bf16 v[36:39], v[182:185], v[206:209], v[36:39]
	v_mfma_f32_16x16x32_bf16 v[32:35], v[190:193], v[206:209], v[32:35]
	v_mfma_f32_16x16x32_bf16 v[20:23], v[182:185], v[214:217], v[20:23]
	v_mfma_f32_16x16x32_bf16 v[16:19], v[190:193], v[214:217], v[16:19]
	v_mfma_f32_16x16x32_bf16 v[4:7], v[182:185], v[222:225], v[4:7]
	v_mfma_f32_16x16x32_bf16 v[0:3], v[190:193], v[222:225], v[0:3]
	s_setprio 0
	s_barrier
	s_add_i32 s56, s56, 2
	s_add_u32 s34, s34, 0x100
	s_addc_u32 s35, s35, 0
	s_add_u32 s54, s54, 0x100
	s_addc_u32 s55, s55, 0
	s_cmp_gt_u32 s56, 29
	s_cbranch_scc0 .LBB0_1151
	s_and_b64 vcc, exec, s[18:19]
	s_cbranch_vccz .LBB0_1154
	s_barrier

; #define PG8_STAGE(bufoff, gbase, voff) do { _Pragma("unroll") for (int _i = 0; _i < 2; ++_i) \
;         __builtin_amdgcn_global_load_lds((const unsigned*)((const char*)(gbase) + (voff)[_i]), (PG8_LAS unsigned*)(lds + (bufoff) + ldsw + _i * 8192), 16, 0, 0); } while (0)
; #define PG8_LDA(dst, b, h) do { _Pragma("unroll") for (int m = 0; m < 4; ++m) _Pragma("unroll") for (int k = 0; k < 2; ++k) dst[m][k] = *(const PG8_LAS bf16x8*)(lds + PG8_SA(b, h) + aoff + m * 2048 + k * 1024); } while (0)
; #define PG8_LDB(dst, b, h) do { _Pragma("unroll") for (int n = 0; n < 2; ++n) _Pragma("unroll") for (int k = 0; k < 2; ++k) dst[n][k] = *(const PG8_LAS bf16x8*)(lds + PG8_SB(b, h) + boff + n * 2048 + k * 1024); } while (0)
; #define PG8_MMA(ai, bj, At, Bt) do { __builtin_amdgcn_s_setprio(1); _Pragma("unroll") for (int m = 0; m < 4; ++m) _Pragma("unroll") for (int n = 0; n < 2; ++n) _Pragma("unroll") for (int k = 0; k < 2; ++k) \
;         acc[ai][bj][m][n] = __builtin_amdgcn_mfma_f32_16x16x32_bf16(Bt[n][k], At[m][k], acc[ai][bj][m][n], 0, 0, 0); __builtin_amdgcn_s_setprio(0); } while (0)
; #define PG8_WAIT_V(n) asm volatile("s_waitcnt vmcnt(" #n ")" ::: "memory")
; #define PG8_WAIT_L(n) asm volatile("s_waitcnt lgkmcnt(" #n ")" ::: "memory")
; #define PG8_BAR __builtin_amdgcn_s_barrier()
; #define PG8_SCHED __builtin_amdgcn_sched_barrier(0)
; template <class Epi, class Sched, bool ALIGN_EPI = false, bool SP2 = false>
; __device__ __forceinline__ void gemm_phase(PG8_LAS unsigned char* lds, const Gemm g, const Sched& S, const Epi& E) {
;     ...
;             const char* a2 = last ? nA : cA + (size_t)(t + 2) * kstep; const char* b2 = last ? nB : cB + (size_t)(t + 2) * kstep;
;             const char* a3 = a2 + kstep; const char* b3 = b2 + kstep;
;             if (last && has_next) S.a_ready(nxt);
;             if constexpr (SP2) {
;             PG8_LDB(B0, 0, 0); PG8_LDB(B1, 0, 1); PG8_SCHED; PG8_LDA(At, 0, 0); PG8_STAGE(PG8_SA(1, 1), a1 + hstep, voffA);
;             PG8_WAIT_V(8); PG8_WAIT_L(0); PG8_BAR; PG8_MMA(0, 0, At, B0); PG8_MMA(0, 1, At, B1); PG8_BAR; PG8_SCHED;
;             PG8_LDA(At, 0, 1); PG8_STAGE(PG8_SB(0, 0), b2, voffB); PG8_STAGE(PG8_SB(0, 1), b2 + hstep, voffB); PG8_STAGE(PG8_SA(0, 0), a2, voffA);
.LBB0_1294:
	ds_read_b128 v[154:157], v150
	ds_read_b128 v[158:161], v150 offset:1024
	ds_read_b128 v[162:165], v150 offset:2048
	ds_read_b128 v[168:171], v150 offset:3072
	ds_read_b128 v[172:175], v151
	ds_read_b128 v[182:185], v151 offset:1024
	ds_read_b128 v[186:189], v151 offset:2048
	ds_read_b128 v[190:193], v151 offset:3072
	s_add_u32 s30, s28, 0xfff80080
	s_addc_u32 s31, s29, -1
	s_cmp_eq_u32 s53, 28
	s_cselect_b32 s35, s21, s31
	s_cselect_b32 s34, s49, s30
	s_cselect_b32 s31, s19, s52
	s_cselect_b32 s30, s50, s51
	v_lshl_add_u64 v[146:147], s[28:29], 0, v[138:139]
	s_add_i32 m0, s40, 0xc000
	ds_read_b128 v[194:197], v152
	ds_read_b128 v[198:201], v152 offset:1024
	ds_read_b128 v[202:205], v152 offset:2048
	ds_read_b128 v[206:209], v152 offset:3072
	ds_read_b128 v[210:213], v152 offset:4096
	ds_read_b128 v[214:217], v152 offset:5120
	ds_read_b128 v[218:221], v152 offset:6144
	ds_read_b128 v[222:225], v152 offset:7168
	global_load_lds_dwordx4 v[146:147], off
	v_lshl_add_u64 v[146:147], s[28:29], 0, v[140:141]
	s_add_i32 m0, s40, 0xe000
	s_nop 0
	global_load_lds_dwordx4 v[146:147], off
	s_waitcnt vmcnt(8)
	s_barrier
	s_setprio 1
	s_waitcnt lgkmcnt(0)
	v_mfma_f32_16x16x32_bf16 v[124:127], v[154:157], v[194:197], v[124:127]
	v_mfma_f32_16x16x32_bf16 v[120:123], v[162:165], v[194:197], v[120:123]
	v_mfma_f32_16x16x32_bf16 v[112:115], v[154:157], v[202:205], v[112:115]
	v_mfma_f32_16x16x32_bf16 v[104:107], v[162:165], v[202:205], v[104:107]
	v_mfma_f32_16x16x32_bf16 v[96:99], v[154:157], v[210:213], v[96:99]
	v_mfma_f32_16x16x32_bf16 v[88:91], v[162:165], v[210:213], v[88:91]
	v_mfma_f32_16x16x32_bf16 v[80:83], v[154:157], v[218:221], v[80:83]
	v_mfma_f32_16x16x32_bf16 v[72:75], v[162:165], v[218:221], v[72:75]
	v_mfma_f32_16x16x32_bf16 v[124:127], v[158:161], v[198:201], v[124:127]
	v_mfma_f32_16x16x32_bf16 v[120:123], v[168:171], v[198:201], v[120:123]
	v_mfma_f32_16x16x32_bf16 v[112:115], v[158:161], v[206:209], v[112:115]
	v_mfma_f32_16x16x32_bf16 v[104:107], v[168:171], v[206:209], v[104:107]
	v_mfma_f32_16x16x32_bf16 v[96:99], v[158:161], v[214:217], v[96:99]
	v_mfma_f32_16x16x32_bf16 v[88:91], v[168:171], v[214:217], v[88:91]
	v_mfma_f32_16x16x32_bf16 v[80:83], v[158:161], v[222:225], v[80:83]
	v_mfma_f32_16x16x32_bf16 v[72:75], v[168:171], v[222:225], v[72:75]
	s_setprio 0
	s_setprio 1
	v_mfma_f32_16x16x32_bf16 v[116:119], v[172:175], v[194:197], v[116:119]
	v_mfma_f32_16x16x32_bf16 v[108:111], v[186:189], v[194:197], v[108:111]
	v_mfma_f32_16x16x32_bf16 v[100:103], v[172:175], v[202:205], v[100:103]
	v_mfma_f32_16x16x32_bf16 v[92:95], v[186:189], v[202:205], v[92:95]
	v_mfma_f32_16x16x32_bf16 v[84:87], v[172:175], v[210:213], v[84:87]
	v_mfma_f32_16x16x32_bf16 v[76:79], v[186:189], v[210:213], v[76:79]
	v_mfma_f32_16x16x32_bf16 v[68:71], v[172:175], v[218:221], v[68:71]
	v_mfma_f32_16x16x32_bf16 v[64:67], v[186:189], v[218:221], v[64:67]
	v_mfma_f32_16x16x32_bf16 v[116:119], v[182:185], v[198:201], v[116:119]
	v_mfma_f32_16x16x32_bf16 v[108:111], v[190:193], v[198:201], v[108:111]
	v_mfma_f32_16x16x32_bf16 v[100:103], v[182:185], v[206:209], v[100:103]
	v_mfma_f32_16x16x32_bf16 v[92:95], v[190:193], v[206:209], v[92:95]
	v_mfma_f32_16x16x32_bf16 v[84:87], v[182:185], v[214:217], v[84:87]
	v_mfma_f32_16x16x32_bf16 v[76:79], v[190:193], v[214:217], v[76:79]
	v_mfma_f32_16x16x32_bf16 v[68:71], v[182:185], v[222:225], v[68:71]
	v_mfma_f32_16x16x32_bf16 v[64:67], v[190:193], v[222:225], v[64:67]
	s_setprio 0
	s_barrier
	s_add_i32 s55, s47, s39
	v_lshl_add_u64 v[146:147], s[30:31], 0, v[132:133]
	s_mov_b32 m0, s55
	ds_read_b128 v[194:197], v152 offset:16384
	ds_read_b128 v[198:201], v152 offset:17408
	ds_read_b128 v[202:205], v152 offset:18432
	ds_read_b128 v[206:209], v152 offset:19456
	ds_read_b128 v[210:213], v152 offset:20480
	ds_read_b128 v[214:217], v152 offset:21504
	ds_read_b128 v[218:221], v152 offset:22528
	ds_read_b128 v[222:225], v152 offset:23552
	global_load_lds_dwordx4 v[146:147], off
	s_add_i32 m0, s55, 0x2000
	s_add_u32 s56, s30, 0x80000
	v_lshl_add_u64 v[176:177], s[30:31], 0, v[128:129]
	s_addc_u32 s57, s31, 0
	s_add_i32 s55, s48, s39
	global_load_lds_dwordx4 v[176:177], off
	v_lshl_add_u64 v[226:227], s[56:57], 0, v[132:133]
	s_mov_b32 m0, s55
	v_lshl_add_u64 v[228:229], s[34:35], 0, v[130:131]
	global_load_lds_dwordx4 v[226:227], off
	v_lshl_add_u64 v[226:227], s[56:57], 0, v[128:129]
	s_add_i32 m0, s55, 0x2000
	s_nop 0
	global_load_lds_dwordx4 v[226:227], off
	v_lshl_add_u64 v[226:227], s[34:35], 0, v[134:135]
	s_mov_b32 m0, s40
	s_nop 0
	global_load_lds_dwordx4 v[226:227], off
	s_mov_b32 m0, s41
	s_nop 0
	global_load_lds_dwordx4 v[228:229], off
	s_waitcnt vmcnt(8)
	s_barrier
; #define PG8_STAGE(bufoff, gbase, voff) do { _Pragma("unroll") for (int _i = 0; _i < 2; ++_i) \
;         __builtin_amdgcn_global_load_lds((const unsigned*)((const char*)(gbase) + (voff)[_i]), (PG8_LAS unsigned*)(lds + (bufoff) + ldsw + _i * 8192), 16, 0, 0); } while (0)
; #define PG8_LDA(dst, b, h) do { _Pragma("unroll") for (int m = 0; m < 4; ++m) _Pragma("unroll") for (int k = 0; k < 2; ++k) dst[m][k] = *(const PG8_LAS bf16x8*)(lds + PG8_SA(b, h) + aoff + m * 2048 + k * 1024); } while (0)
; #define PG8_LDB(dst, b, h) do { _Pragma("unroll") for (int n = 0; n < 2; ++n) _Pragma("unroll") for (int k = 0; k < 2; ++k) dst[n][k] = *(const PG8_LAS bf16x8*)(lds + PG8_SB(b, h) + boff + n * 2048 + k * 1024); } while (0)
; #define PG8_MMA(ai, bj, At, Bt) do { __builtin_amdgcn_s_setprio(1); _Pragma("unroll") for (int m = 0; m < 4; ++m) _Pragma("unroll") for (int n = 0; n < 2; ++n) _Pragma("unroll") for (int k = 0; k < 2; ++k) \
;         acc[ai][bj][m][n] = __builtin_amdgcn_mfma_f32_16x16x32_bf16(Bt[n][k], At[m][k], acc[ai][bj][m][n], 0, 0, 0); __builtin_amdgcn_s_setprio(0); } while (0)
; #define PG8_WAIT_V(n) asm volatile("s_waitcnt vmcnt(" #n ")" ::: "memory")
; #define PG8_WAIT_L(n) asm volatile("s_waitcnt lgkmcnt(" #n ")" ::: "memory")
; #define PG8_BAR __builtin_amdgcn_s_barrier()
; #define PG8_SCHED __builtin_amdgcn_sched_barrier(0)
; template <class Epi, class Sched, bool ALIGN_EPI = false, bool SP2 = false>
; __device__ __forceinline__ void gemm_phase(PG8_LAS unsigned char* lds, const Gemm g, const Sched& S, const Epi& E) {
;     ...
;             PG8_WAIT_V(8); PG8_WAIT_L(0); PG8_BAR; PG8_MMA(1, 0, At, B0); PG8_MMA(1, 1, At, B1); PG8_BAR; PG8_SCHED;
;             PG8_LDB(B0, 1, 0); PG8_LDB(B1, 1, 1); PG8_SCHED; PG8_LDA(At, 1, 0); PG8_STAGE(PG8_SA(0, 1), a2 + hstep, voffA);
;             PG8_WAIT_V(8); PG8_WAIT_L(0); PG8_BAR; PG8_MMA(0, 0, At, B0); PG8_MMA(0, 1, At, B1); PG8_BAR; PG8_SCHED;
	s_setprio 1
	s_waitcnt lgkmcnt(0)
	v_mfma_f32_16x16x32_bf16 v[60:63], v[154:157], v[194:197], v[60:63]
	v_mfma_f32_16x16x32_bf16 v[56:59], v[162:165], v[194:197], v[56:59]
	v_mfma_f32_16x16x32_bf16 v[48:51], v[154:157], v[202:205], v[48:51]
	v_mfma_f32_16x16x32_bf16 v[40:43], v[162:165], v[202:205], v[40:43]
	v_mfma_f32_16x16x32_bf16 v[32:35], v[154:157], v[210:213], v[32:35]
	v_mfma_f32_16x16x32_bf16 v[24:27], v[162:165], v[210:213], v[24:27]
	v_mfma_f32_16x16x32_bf16 v[16:19], v[154:157], v[218:221], v[16:19]
	v_mfma_f32_16x16x32_bf16 v[8:11], v[162:165], v[218:221], v[8:11]
	v_mfma_f32_16x16x32_bf16 v[60:63], v[158:161], v[198:201], v[60:63]
	v_mfma_f32_16x16x32_bf16 v[56:59], v[168:171], v[198:201], v[56:59]
	v_mfma_f32_16x16x32_bf16 v[48:51], v[158:161], v[206:209], v[48:51]
	v_mfma_f32_16x16x32_bf16 v[40:43], v[168:171], v[206:209], v[40:43]
	v_mfma_f32_16x16x32_bf16 v[32:35], v[158:161], v[214:217], v[32:35]
	v_mfma_f32_16x16x32_bf16 v[24:27], v[168:171], v[214:217], v[24:27]
	v_mfma_f32_16x16x32_bf16 v[16:19], v[158:161], v[222:225], v[16:19]
	v_mfma_f32_16x16x32_bf16 v[8:11], v[168:171], v[222:225], v[8:11]
	s_setprio 0
	s_setprio 1
	v_mfma_f32_16x16x32_bf16 v[52:55], v[172:175], v[194:197], v[52:55]
	v_mfma_f32_16x16x32_bf16 v[44:47], v[186:189], v[194:197], v[44:47]
	v_mfma_f32_16x16x32_bf16 v[36:39], v[172:175], v[202:205], v[36:39]
	v_mfma_f32_16x16x32_bf16 v[28:31], v[186:189], v[202:205], v[28:31]
	v_mfma_f32_16x16x32_bf16 v[20:23], v[172:175], v[210:213], v[20:23]
	v_mfma_f32_16x16x32_bf16 v[12:15], v[186:189], v[210:213], v[12:15]
	v_mfma_f32_16x16x32_bf16 v[4:7], v[172:175], v[218:221], v[4:7]
	v_mfma_f32_16x16x32_bf16 v[0:3], v[186:189], v[218:221], v[0:3]
	v_mfma_f32_16x16x32_bf16 v[52:55], v[182:185], v[198:201], v[52:55]
	v_mfma_f32_16x16x32_bf16 v[44:47], v[190:193], v[198:201], v[44:47]
	v_mfma_f32_16x16x32_bf16 v[36:39], v[182:185], v[206:209], v[36:39]
	v_mfma_f32_16x16x32_bf16 v[28:31], v[190:193], v[206:209], v[28:31]
	v_mfma_f32_16x16x32_bf16 v[20:23], v[182:185], v[214:217], v[20:23]
	v_mfma_f32_16x16x32_bf16 v[12:15], v[190:193], v[214:217], v[12:15]
	v_mfma_f32_16x16x32_bf16 v[4:7], v[182:185], v[222:225], v[4:7]
	v_mfma_f32_16x16x32_bf16 v[0:3], v[190:193], v[222:225], v[0:3]
	s_setprio 0
	s_barrier
	s_add_i32 s55, 0, 0x18000
	v_add_u32_e32 v153, s55, v149
	s_add_i32 s56, 0, 0x1c000
	ds_read_b128 v[154:157], v153
	ds_read_b128 v[158:161], v153 offset:1024
	ds_read_b128 v[162:165], v153 offset:2048
	ds_read_b128 v[168:171], v153 offset:3072
	v_add_u32_e32 v153, s56, v149
	ds_read_b128 v[172:175], v153
	ds_read_b128 v[182:185], v153 offset:1024
	ds_read_b128 v[186:189], v153 offset:2048
	ds_read_b128 v[190:193], v153 offset:3072
	s_add_u32 s34, s34, 0x80000
	s_addc_u32 s35, s35, 0
	s_mov_b32 m0, s42
	v_lshl_add_u64 v[230:231], s[34:35], 0, v[134:135]
	ds_read_b128 v[194:197], v152 offset:32768
	ds_read_b128 v[198:201], v152 offset:33792
	ds_read_b128 v[202:205], v152 offset:34816
	ds_read_b128 v[206:209], v152 offset:35840
	ds_read_b128 v[210:213], v152 offset:36864
	ds_read_b128 v[214:217], v152 offset:37888
	ds_read_b128 v[218:221], v152 offset:38912
	ds_read_b128 v[222:225], v152 offset:39936
	global_load_lds_dwordx4 v[230:231], off
	v_lshl_add_u64 v[230:231], s[34:35], 0, v[130:131]
	s_mov_b32 m0, s43
	s_nop 0
	global_load_lds_dwordx4 v[230:231], off
	s_waitcnt vmcnt(8)
	s_barrier
	s_setprio 1
	s_waitcnt lgkmcnt(0)
	v_mfma_f32_16x16x32_bf16 v[124:127], v[154:157], v[194:197], v[124:127]
	v_mfma_f32_16x16x32_bf16 v[120:123], v[162:165], v[194:197], v[120:123]
	v_mfma_f32_16x16x32_bf16 v[112:115], v[154:157], v[202:205], v[112:115]
	v_mfma_f32_16x16x32_bf16 v[104:107], v[162:165], v[202:205], v[104:107]
	v_mfma_f32_16x16x32_bf16 v[96:99], v[154:157], v[210:213], v[96:99]
	v_mfma_f32_16x16x32_bf16 v[88:91], v[162:165], v[210:213], v[88:91]
	v_mfma_f32_16x16x32_bf16 v[80:83], v[154:157], v[218:221], v[80:83]
	v_mfma_f32_16x16x32_bf16 v[72:75], v[162:165], v[218:221], v[72:75]
	v_mfma_f32_16x16x32_bf16 v[124:127], v[158:161], v[198:201], v[124:127]
	v_mfma_f32_16x16x32_bf16 v[120:123], v[168:171], v[198:201], v[120:123]
	v_mfma_f32_16x16x32_bf16 v[112:115], v[158:161], v[206:209], v[112:115]
	v_mfma_f32_16x16x32_bf16 v[104:107], v[168:171], v[206:209], v[104:107]
	v_mfma_f32_16x16x32_bf16 v[96:99], v[158:161], v[214:217], v[96:99]
	v_mfma_f32_16x16x32_bf16 v[88:91], v[168:171], v[214:217], v[88:91]
	v_mfma_f32_16x16x32_bf16 v[80:83], v[158:161], v[222:225], v[80:83]
	v_mfma_f32_16x16x32_bf16 v[72:75], v[168:171], v[222:225], v[72:75]
	s_setprio 0
	s_setprio 1
	v_mfma_f32_16x16x32_bf16 v[116:119], v[172:175], v[194:197], v[116:119]
	v_mfma_f32_16x16x32_bf16 v[108:111], v[186:189], v[194:197], v[108:111]
	v_mfma_f32_16x16x32_bf16 v[100:103], v[172:175], v[202:205], v[100:103]
	v_mfma_f32_16x16x32_bf16 v[92:95], v[186:189], v[202:205], v[92:95]
	v_mfma_f32_16x16x32_bf16 v[84:87], v[172:175], v[210:213], v[84:87]
	v_mfma_f32_16x16x32_bf16 v[76:79], v[186:189], v[210:213], v[76:79]
	v_mfma_f32_16x16x32_bf16 v[68:71], v[172:175], v[218:221], v[68:71]
	v_mfma_f32_16x16x32_bf16 v[64:67], v[186:189], v[218:221], v[64:67]
	v_mfma_f32_16x16x32_bf16 v[116:119], v[182:185], v[198:201], v[116:119]
	v_mfma_f32_16x16x32_bf16 v[108:111], v[190:193], v[198:201], v[108:111]
	v_mfma_f32_16x16x32_bf16 v[100:103], v[182:185], v[206:209], v[100:103]
	v_mfma_f32_16x16x32_bf16 v[92:95], v[190:193], v[206:209], v[92:95]
	v_mfma_f32_16x16x32_bf16 v[84:87], v[182:185], v[214:217], v[84:87]
	v_mfma_f32_16x16x32_bf16 v[76:79], v[190:193], v[214:217], v[76:79]
	v_mfma_f32_16x16x32_bf16 v[68:71], v[182:185], v[222:225], v[68:71]
	v_mfma_f32_16x16x32_bf16 v[64:67], v[190:193], v[222:225], v[64:67]
	s_setprio 0
	s_barrier
; #define PG8_STAGE(bufoff, gbase, voff) do { _Pragma("unroll") for (int _i = 0; _i < 2; ++_i) \
;         __builtin_amdgcn_global_load_lds((const unsigned*)((const char*)(gbase) + (voff)[_i]), (PG8_LAS unsigned*)(lds + (bufoff) + ldsw + _i * 8192), 16, 0, 0); } while (0)
; #define PG8_LDA(dst, b, h) do { _Pragma("unroll") for (int m = 0; m < 4; ++m) _Pragma("unroll") for (int k = 0; k < 2; ++k) dst[m][k] = *(const PG8_LAS bf16x8*)(lds + PG8_SA(b, h) + aoff + m * 2048 + k * 1024); } while (0)
; #define PG8_MMA(ai, bj, At, Bt) do { __builtin_amdgcn_s_setprio(1); _Pragma("unroll") for (int m = 0; m < 4; ++m) _Pragma("unroll") for (int n = 0; n < 2; ++n) _Pragma("unroll") for (int k = 0; k < 2; ++k) \
;         acc[ai][bj][m][n] = __builtin_amdgcn_mfma_f32_16x16x32_bf16(Bt[n][k], At[m][k], acc[ai][bj][m][n], 0, 0, 0); __builtin_amdgcn_s_setprio(0); } while (0)
; #define PG8_WAIT_V(n) asm volatile("s_waitcnt vmcnt(" #n ")" ::: "memory")
; #define PG8_WAIT_L(n) asm volatile("s_waitcnt lgkmcnt(" #n ")" ::: "memory")
; #define PG8_BAR __builtin_amdgcn_s_barrier()
; #define PG8_SCHED __builtin_amdgcn_sched_barrier(0)
; template <class Epi, class Sched, bool ALIGN_EPI = false, bool SP2 = false>
; __device__ __forceinline__ void gemm_phase(PG8_LAS unsigned char* lds, const Gemm g, const Sched& S, const Epi& E) {
;     ...
;             PG8_LDA(At, 1, 1); PG8_STAGE(PG8_SB(1, 0), b3, voffB); PG8_STAGE(PG8_SB(1, 1), b3 + hstep, voffB); PG8_STAGE(PG8_SA(1, 0), a3, voffA);
;             PG8_WAIT_V(8); PG8_WAIT_L(0); PG8_BAR; PG8_MMA(1, 0, At, B0); PG8_MMA(1, 1, At, B1); PG8_BAR; PG8_SCHED;
	s_add_i32 s34, s55, s39
	v_lshl_add_u64 v[146:147], v[146:147], 0, s[14:15]
	s_mov_b32 m0, s34
	ds_read_b128 v[194:197], v152 offset:49152
	ds_read_b128 v[198:201], v152 offset:50176
	ds_read_b128 v[202:205], v152 offset:51200
	ds_read_b128 v[206:209], v152 offset:52224
	ds_read_b128 v[210:213], v152 offset:53248
	ds_read_b128 v[214:217], v152 offset:54272
	ds_read_b128 v[218:221], v152 offset:55296
	ds_read_b128 v[222:225], v152 offset:56320
	global_load_lds_dwordx4 v[146:147], off
	s_add_i32 m0, s34, 0x2000
	s_add_u32 s30, s30, 0x80080
	v_lshl_add_u64 v[146:147], v[176:177], 0, s[14:15]
	s_addc_u32 s31, s31, 0
	s_add_i32 s34, s56, s39
	global_load_lds_dwordx4 v[146:147], off
	v_lshl_add_u64 v[146:147], s[30:31], 0, v[132:133]
	s_mov_b32 m0, s34
	s_nop 0
	global_load_lds_dwordx4 v[146:147], off
	v_lshl_add_u64 v[146:147], s[30:31], 0, v[128:129]
	s_add_i32 m0, s34, 0x2000
	s_nop 0
	global_load_lds_dwordx4 v[146:147], off
	v_lshl_add_u64 v[146:147], v[226:227], 0, s[14:15]
	s_mov_b32 m0, s45
	s_nop 0
	global_load_lds_dwordx4 v[146:147], off
	v_lshl_add_u64 v[146:147], v[228:229], 0, s[14:15]
	s_mov_b32 m0, s46
	s_nop 0
	global_load_lds_dwordx4 v[146:147], off
	s_waitcnt vmcnt(8)
	s_barrier
	s_setprio 1
	s_waitcnt lgkmcnt(0)
	v_mfma_f32_16x16x32_bf16 v[60:63], v[154:157], v[194:197], v[60:63]
	v_mfma_f32_16x16x32_bf16 v[56:59], v[162:165], v[194:197], v[56:59]
	v_mfma_f32_16x16x32_bf16 v[48:51], v[154:157], v[202:205], v[48:51]
	v_mfma_f32_16x16x32_bf16 v[40:43], v[162:165], v[202:205], v[40:43]
	v_mfma_f32_16x16x32_bf16 v[32:35], v[154:157], v[210:213], v[32:35]
	v_mfma_f32_16x16x32_bf16 v[24:27], v[162:165], v[210:213], v[24:27]
	v_mfma_f32_16x16x32_bf16 v[16:19], v[154:157], v[218:221], v[16:19]
	v_mfma_f32_16x16x32_bf16 v[8:11], v[162:165], v[218:221], v[8:11]
	v_mfma_f32_16x16x32_bf16 v[60:63], v[158:161], v[198:201], v[60:63]
	v_mfma_f32_16x16x32_bf16 v[56:59], v[168:171], v[198:201], v[56:59]
	v_mfma_f32_16x16x32_bf16 v[48:51], v[158:161], v[206:209], v[48:51]
	v_mfma_f32_16x16x32_bf16 v[40:43], v[168:171], v[206:209], v[40:43]
	v_mfma_f32_16x16x32_bf16 v[32:35], v[158:161], v[214:217], v[32:35]
	v_mfma_f32_16x16x32_bf16 v[24:27], v[168:171], v[214:217], v[24:27]
	v_mfma_f32_16x16x32_bf16 v[16:19], v[158:161], v[222:225], v[16:19]
	v_mfma_f32_16x16x32_bf16 v[8:11], v[168:171], v[222:225], v[8:11]
	s_setprio 0
	s_setprio 1
	v_mfma_f32_16x16x32_bf16 v[52:55], v[172:175], v[194:197], v[52:55]
	v_mfma_f32_16x16x32_bf16 v[44:47], v[186:189], v[194:197], v[44:47]
	v_mfma_f32_16x16x32_bf16 v[36:39], v[172:175], v[202:205], v[36:39]
	v_mfma_f32_16x16x32_bf16 v[28:31], v[186:189], v[202:205], v[28:31]
	v_mfma_f32_16x16x32_bf16 v[20:23], v[172:175], v[210:213], v[20:23]
	v_mfma_f32_16x16x32_bf16 v[12:15], v[186:189], v[210:213], v[12:15]
	v_mfma_f32_16x16x32_bf16 v[4:7], v[172:175], v[218:221], v[4:7]
	v_mfma_f32_16x16x32_bf16 v[0:3], v[186:189], v[218:221], v[0:3]
	v_mfma_f32_16x16x32_bf16 v[52:55], v[182:185], v[198:201], v[52:55]
	v_mfma_f32_16x16x32_bf16 v[44:47], v[190:193], v[198:201], v[44:47]
	v_mfma_f32_16x16x32_bf16 v[36:39], v[182:185], v[206:209], v[36:39]
	v_mfma_f32_16x16x32_bf16 v[28:31], v[190:193], v[206:209], v[28:31]
	v_mfma_f32_16x16x32_bf16 v[20:23], v[182:185], v[214:217], v[20:23]
	v_mfma_f32_16x16x32_bf16 v[12:15], v[190:193], v[214:217], v[12:15]
	v_mfma_f32_16x16x32_bf16 v[4:7], v[182:185], v[222:225], v[4:7]
	v_mfma_f32_16x16x32_bf16 v[0:3], v[190:193], v[222:225], v[0:3]
	s_setprio 0
	s_barrier
	s_add_i32 s53, s53, 2
	s_add_u32 s28, s28, 0x100
	s_addc_u32 s29, s29, 0
	s_add_u32 s51, s51, 0x100
	s_addc_u32 s52, s52, 0
	s_cmp_gt_u32 s53, 29
	s_cbranch_scc0 .LBB0_1294
	s_and_b64 vcc, exec, s[16:17]
	s_cbranch_vccz .LBB0_1297
	s_barrier

; #define PG8_STAGE(bufoff, gbase, voff) do { _Pragma("unroll") for (int _i = 0; _i < 2; ++_i) \
;         __builtin_amdgcn_global_load_lds((const unsigned*)((const char*)(gbase) + (voff)[_i]), (PG8_LAS unsigned*)(lds + (bufoff) + ldsw + _i * 8192), 16, 0, 0); } while (0)
; #define PG8_LDA(dst, b, h) do { _Pragma("unroll") for (int m = 0; m < 4; ++m) _Pragma("unroll") for (int k = 0; k < 2; ++k) dst[m][k] = *(const PG8_LAS bf16x8*)(lds + PG8_SA(b, h) + aoff + m * 2048 + k * 1024); } while (0)
; #define PG8_LDB(dst, b, h) do { _Pragma("unroll") for (int n = 0; n < 2; ++n) _Pragma("unroll") for (int k = 0; k < 2; ++k) dst[n][k] = *(const PG8_LAS bf16x8*)(lds + PG8_SB(b, h) + boff + n * 2048 + k * 1024); } while (0)
; #define PG8_MMA(ai, bj, At, Bt) do { __builtin_amdgcn_s_setprio(1); _Pragma("unroll") for (int m = 0; m < 4; ++m) _Pragma("unroll") for (int n = 0; n < 2; ++n) _Pragma("unroll") for (int k = 0; k < 2; ++k) \
;         acc[ai][bj][m][n] = __builtin_amdgcn_mfma_f32_16x16x32_bf16(Bt[n][k], At[m][k], acc[ai][bj][m][n], 0, 0, 0); __builtin_amdgcn_s_setprio(0); } while (0)
; #define PG8_WAIT_V(n) asm volatile("s_waitcnt vmcnt(" #n ")" ::: "memory")
; #define PG8_WAIT_L(n) asm volatile("s_waitcnt lgkmcnt(" #n ")" ::: "memory")
; #define PG8_BAR __builtin_amdgcn_s_barrier()
; #define PG8_SCHED __builtin_amdgcn_sched_barrier(0)
; template <class Epi, class Sched, bool ALIGN_EPI = false, bool SP2 = false>
; __device__ __forceinline__ void gemm_phase(PG8_LAS unsigned char* lds, const Gemm g, const Sched& S, const Epi& E) {
;     ...
;             const char* a1 = cA + (size_t)(t + 1) * kstep;
;             const char* a2 = last ? nA : cA + (size_t)(t + 2) * kstep; const char* b2 = last ? nB : cB + (size_t)(t + 2) * kstep;
;             const char* a3 = a2 + kstep; const char* b3 = b2 + kstep;
;             if (last && has_next) S.a_ready(nxt);
;             if constexpr (SP2) {
;             PG8_LDB(B0, 0, 0); PG8_LDB(B1, 0, 1); PG8_SCHED; PG8_LDA(At, 0, 0); PG8_STAGE(PG8_SA(1, 1), a1 + hstep, voffA);
;             PG8_WAIT_V(8); PG8_WAIT_L(0); PG8_BAR; PG8_MMA(0, 0, At, B0); PG8_MMA(0, 1, At, B1); PG8_BAR; PG8_SCHED;
;             PG8_LDA(At, 0, 1); PG8_STAGE(PG8_SB(0, 0), b2, voffB); PG8_STAGE(PG8_SB(0, 1), b2 + hstep, voffB); PG8_STAGE(PG8_SA(0, 0), a2, voffA);
.LBB0_1320:
	s_add_u32 s45, s38, s44
	s_addc_u32 s50, s39, 0
	s_add_u32 s48, s45, 0x100
	s_addc_u32 s49, s50, 0
	s_and_b64 s[46:47], s[42:43], exec
	s_cselect_b32 s47, s25, s49
	s_cselect_b32 s46, s31, s48
	s_add_u32 s44, s36, s44
	s_addc_u32 s48, s37, 0
	s_add_u32 s44, s44, 0x100
	s_addc_u32 s48, s48, 0
	s_and_b64 s[42:43], s[42:43], exec
	s_cselect_b32 s49, s23, s48
	s_cselect_b32 s48, s35, s44
	s_add_u32 s52, s45, 0x10080
	ds_read_b128 v[150:153], v146
	ds_read_b128 v[154:157], v146 offset:1024
	ds_read_b128 v[158:161], v146 offset:2048
	ds_read_b128 v[162:165], v146 offset:3072
	ds_read_b128 v[168:171], v147
	ds_read_b128 v[172:175], v147 offset:1024
	ds_read_b128 v[182:185], v147 offset:2048
	ds_read_b128 v[186:189], v147 offset:3072
	s_addc_u32 s53, s50, 0
	s_add_i32 s77, s66, s58
	s_add_i32 m0, s59, 0xc000
	s_add_i32 s81, s59, 0xe000
	s_add_i32 s72, s77, 0x2000
	s_add_u32 s50, s48, 0x10000
	s_addc_u32 s51, s49, 0
	s_add_i32 s76, s67, s58
	s_add_i32 s73, s76, 0x2000
	s_add_i32 s71, 0, 0x18000
	s_add_i32 s70, 0, 0x1c000
	s_add_u32 s44, s46, 0x10000
	s_addc_u32 s45, s47, 0
	s_add_i32 s69, s71, s58
	s_add_i32 s68, s69, 0x2000
	s_add_u32 s42, s48, 0x10080
	s_addc_u32 s43, s49, 0
	s_add_i32 s79, s70, s58
	s_add_i32 s78, s79, 0x2000
	v_lshl_add_u64 v[142:143], s[52:53], 0, v[128:129]
	ds_read_b128 v[190:193], v148
	ds_read_b128 v[194:197], v148 offset:1024
	ds_read_b128 v[198:201], v148 offset:2048
	ds_read_b128 v[202:205], v148 offset:3072
	ds_read_b128 v[206:209], v148 offset:4096
	ds_read_b128 v[210:213], v148 offset:5120
	ds_read_b128 v[214:217], v148 offset:6144
	ds_read_b128 v[218:221], v148 offset:7168
	global_load_lds_dwordx4 v[142:143], off
	v_lshl_add_u64 v[142:143], s[52:53], 0, v[132:133]
	s_mov_b32 m0, s81
	s_nop 0
	global_load_lds_dwordx4 v[142:143], off
	s_waitcnt vmcnt(8)
	s_barrier
	s_setprio 1
	s_waitcnt lgkmcnt(0)
	v_mfma_f32_16x16x32_bf16 v[124:127], v[150:153], v[190:193], v[124:127]
	v_mfma_f32_16x16x32_bf16 v[120:123], v[158:161], v[190:193], v[120:123]
	v_mfma_f32_16x16x32_bf16 v[108:111], v[150:153], v[198:201], v[108:111]
	v_mfma_f32_16x16x32_bf16 v[104:107], v[158:161], v[198:201], v[104:107]
	v_mfma_f32_16x16x32_bf16 v[92:95], v[150:153], v[206:209], v[92:95]
	v_mfma_f32_16x16x32_bf16 v[88:91], v[158:161], v[206:209], v[88:91]
	v_mfma_f32_16x16x32_bf16 v[76:79], v[150:153], v[214:217], v[76:79]
	v_mfma_f32_16x16x32_bf16 v[72:75], v[158:161], v[214:217], v[72:75]
	v_mfma_f32_16x16x32_bf16 v[124:127], v[154:157], v[194:197], v[124:127]
	v_mfma_f32_16x16x32_bf16 v[120:123], v[162:165], v[194:197], v[120:123]
	v_mfma_f32_16x16x32_bf16 v[108:111], v[154:157], v[202:205], v[108:111]
	v_mfma_f32_16x16x32_bf16 v[104:107], v[162:165], v[202:205], v[104:107]
	v_mfma_f32_16x16x32_bf16 v[92:95], v[154:157], v[210:213], v[92:95]
	v_mfma_f32_16x16x32_bf16 v[88:91], v[162:165], v[210:213], v[88:91]
	v_mfma_f32_16x16x32_bf16 v[76:79], v[154:157], v[218:221], v[76:79]
	v_mfma_f32_16x16x32_bf16 v[72:75], v[162:165], v[218:221], v[72:75]
	s_setprio 0
	s_setprio 1
	v_mfma_f32_16x16x32_bf16 v[116:119], v[168:171], v[190:193], v[116:119]
	v_mfma_f32_16x16x32_bf16 v[112:115], v[182:185], v[190:193], v[112:115]
	v_mfma_f32_16x16x32_bf16 v[100:103], v[168:171], v[198:201], v[100:103]
	v_mfma_f32_16x16x32_bf16 v[96:99], v[182:185], v[198:201], v[96:99]
	v_mfma_f32_16x16x32_bf16 v[84:87], v[168:171], v[206:209], v[84:87]
	v_mfma_f32_16x16x32_bf16 v[80:83], v[182:185], v[206:209], v[80:83]
	v_mfma_f32_16x16x32_bf16 v[68:71], v[168:171], v[214:217], v[68:71]
	v_mfma_f32_16x16x32_bf16 v[64:67], v[182:185], v[214:217], v[64:67]
	v_mfma_f32_16x16x32_bf16 v[116:119], v[172:175], v[194:197], v[116:119]
	v_mfma_f32_16x16x32_bf16 v[112:115], v[186:189], v[194:197], v[112:115]
	v_mfma_f32_16x16x32_bf16 v[100:103], v[172:175], v[202:205], v[100:103]
	v_mfma_f32_16x16x32_bf16 v[96:99], v[186:189], v[202:205], v[96:99]
	v_mfma_f32_16x16x32_bf16 v[84:87], v[172:175], v[210:213], v[84:87]
	v_mfma_f32_16x16x32_bf16 v[80:83], v[186:189], v[210:213], v[80:83]
	v_mfma_f32_16x16x32_bf16 v[68:71], v[172:175], v[218:221], v[68:71]
	v_mfma_f32_16x16x32_bf16 v[64:67], v[186:189], v[218:221], v[64:67]
	s_setprio 0
	s_barrier
	s_mov_b32 m0, s77
	v_lshl_add_u64 v[142:143], s[48:49], 0, v[130:131]
	ds_read_b128 v[190:193], v148 offset:16384
	ds_read_b128 v[194:197], v148 offset:17408
	ds_read_b128 v[198:201], v148 offset:18432
	ds_read_b128 v[202:205], v148 offset:19456
	ds_read_b128 v[206:209], v148 offset:20480
	ds_read_b128 v[210:213], v148 offset:21504
	ds_read_b128 v[214:217], v148 offset:22528
	ds_read_b128 v[218:221], v148 offset:23552
	global_load_lds_dwordx4 v[142:143], off
	v_lshl_add_u64 v[176:177], s[48:49], 0, v[134:135]
	s_mov_b32 m0, s72
	v_lshl_add_u64 v[222:223], s[50:51], 0, v[130:131]
	global_load_lds_dwordx4 v[176:177], off
	s_mov_b32 m0, s76
	v_lshl_add_u64 v[224:225], s[46:47], 0, v[132:133]
	global_load_lds_dwordx4 v[222:223], off
	v_lshl_add_u64 v[222:223], s[50:51], 0, v[134:135]
	s_mov_b32 m0, s73
	s_nop 0
	global_load_lds_dwordx4 v[222:223], off
	v_lshl_add_u64 v[222:223], s[46:47], 0, v[128:129]
	s_mov_b32 m0, s59
	s_nop 0
	global_load_lds_dwordx4 v[222:223], off
	s_mov_b32 m0, s60
	s_nop 0
	global_load_lds_dwordx4 v[224:225], off
	s_waitcnt vmcnt(8)
	s_barrier
; #define PG8_STAGE(bufoff, gbase, voff) do { _Pragma("unroll") for (int _i = 0; _i < 2; ++_i) \
;         __builtin_amdgcn_global_load_lds((const unsigned*)((const char*)(gbase) + (voff)[_i]), (PG8_LAS unsigned*)(lds + (bufoff) + ldsw + _i * 8192), 16, 0, 0); } while (0)
; #define PG8_LDA(dst, b, h) do { _Pragma("unroll") for (int m = 0; m < 4; ++m) _Pragma("unroll") for (int k = 0; k < 2; ++k) dst[m][k] = *(const PG8_LAS bf16x8*)(lds + PG8_SA(b, h) + aoff + m * 2048 + k * 1024); } while (0)
; #define PG8_LDB(dst, b, h) do { _Pragma("unroll") for (int n = 0; n < 2; ++n) _Pragma("unroll") for (int k = 0; k < 2; ++k) dst[n][k] = *(const PG8_LAS bf16x8*)(lds + PG8_SB(b, h) + boff + n * 2048 + k * 1024); } while (0)
; #define PG8_MMA(ai, bj, At, Bt) do { __builtin_amdgcn_s_setprio(1); _Pragma("unroll") for (int m = 0; m < 4; ++m) _Pragma("unroll") for (int n = 0; n < 2; ++n) _Pragma("unroll") for (int k = 0; k < 2; ++k) \
;         acc[ai][bj][m][n] = __builtin_amdgcn_mfma_f32_16x16x32_bf16(Bt[n][k], At[m][k], acc[ai][bj][m][n], 0, 0, 0); __builtin_amdgcn_s_setprio(0); } while (0)
; #define PG8_WAIT_V(n) asm volatile("s_waitcnt vmcnt(" #n ")" ::: "memory")
; #define PG8_WAIT_L(n) asm volatile("s_waitcnt lgkmcnt(" #n ")" ::: "memory")
; #define PG8_BAR __builtin_amdgcn_s_barrier()
; #define PG8_SCHED __builtin_amdgcn_sched_barrier(0)
; template <class Epi, class Sched, bool ALIGN_EPI = false, bool SP2 = false>
; __device__ __forceinline__ void gemm_phase(PG8_LAS unsigned char* lds, const Gemm g, const Sched& S, const Epi& E) {
;     ...
;             PG8_WAIT_V(8); PG8_WAIT_L(0); PG8_BAR; PG8_MMA(1, 0, At, B0); PG8_MMA(1, 1, At, B1); PG8_BAR; PG8_SCHED;
;             PG8_LDB(B0, 1, 0); PG8_LDB(B1, 1, 1); PG8_SCHED; PG8_LDA(At, 1, 0); PG8_STAGE(PG8_SA(0, 1), a2 + hstep, voffA);
;             PG8_WAIT_V(8); PG8_WAIT_L(0); PG8_BAR; PG8_MMA(0, 0, At, B0); PG8_MMA(0, 1, At, B1); PG8_BAR; PG8_SCHED;
	s_setprio 1
	s_waitcnt lgkmcnt(0)
	v_mfma_f32_16x16x32_bf16 v[60:63], v[150:153], v[190:193], v[60:63]
	v_mfma_f32_16x16x32_bf16 v[56:59], v[158:161], v[190:193], v[56:59]
	v_mfma_f32_16x16x32_bf16 v[44:47], v[150:153], v[198:201], v[44:47]
	v_mfma_f32_16x16x32_bf16 v[40:43], v[158:161], v[198:201], v[40:43]
	v_mfma_f32_16x16x32_bf16 v[28:31], v[150:153], v[206:209], v[28:31]
	v_mfma_f32_16x16x32_bf16 v[24:27], v[158:161], v[206:209], v[24:27]
	v_mfma_f32_16x16x32_bf16 v[12:15], v[150:153], v[214:217], v[12:15]
	v_mfma_f32_16x16x32_bf16 v[8:11], v[158:161], v[214:217], v[8:11]
	v_mfma_f32_16x16x32_bf16 v[60:63], v[154:157], v[194:197], v[60:63]
	v_mfma_f32_16x16x32_bf16 v[56:59], v[162:165], v[194:197], v[56:59]
	v_mfma_f32_16x16x32_bf16 v[44:47], v[154:157], v[202:205], v[44:47]
	v_mfma_f32_16x16x32_bf16 v[40:43], v[162:165], v[202:205], v[40:43]
	v_mfma_f32_16x16x32_bf16 v[28:31], v[154:157], v[210:213], v[28:31]
	v_mfma_f32_16x16x32_bf16 v[24:27], v[162:165], v[210:213], v[24:27]
	v_mfma_f32_16x16x32_bf16 v[12:15], v[154:157], v[218:221], v[12:15]
	v_mfma_f32_16x16x32_bf16 v[8:11], v[162:165], v[218:221], v[8:11]
	s_setprio 0
	s_setprio 1
	v_mfma_f32_16x16x32_bf16 v[52:55], v[168:171], v[190:193], v[52:55]
	v_mfma_f32_16x16x32_bf16 v[48:51], v[182:185], v[190:193], v[48:51]
	v_mfma_f32_16x16x32_bf16 v[36:39], v[168:171], v[198:201], v[36:39]
	v_mfma_f32_16x16x32_bf16 v[32:35], v[182:185], v[198:201], v[32:35]
	v_mfma_f32_16x16x32_bf16 v[20:23], v[168:171], v[206:209], v[20:23]
	v_mfma_f32_16x16x32_bf16 v[16:19], v[182:185], v[206:209], v[16:19]
	v_mfma_f32_16x16x32_bf16 v[4:7], v[168:171], v[214:217], v[4:7]
	v_mfma_f32_16x16x32_bf16 v[0:3], v[182:185], v[214:217], v[0:3]
	v_mfma_f32_16x16x32_bf16 v[52:55], v[172:175], v[194:197], v[52:55]
	v_mfma_f32_16x16x32_bf16 v[48:51], v[186:189], v[194:197], v[48:51]
	v_mfma_f32_16x16x32_bf16 v[36:39], v[172:175], v[202:205], v[36:39]
	v_mfma_f32_16x16x32_bf16 v[32:35], v[186:189], v[202:205], v[32:35]
	v_mfma_f32_16x16x32_bf16 v[20:23], v[172:175], v[210:213], v[20:23]
	v_mfma_f32_16x16x32_bf16 v[16:19], v[186:189], v[210:213], v[16:19]
	v_mfma_f32_16x16x32_bf16 v[4:7], v[172:175], v[218:221], v[4:7]
	v_mfma_f32_16x16x32_bf16 v[0:3], v[186:189], v[218:221], v[0:3]
	s_setprio 0
	s_barrier
	v_add_u32_e32 v162, s71, v145
	v_add_u32_e32 v167, s70, v145
	ds_read_b128 v[150:153], v162
	ds_read_b128 v[154:157], v162 offset:1024
	ds_read_b128 v[158:161], v162 offset:2048
	ds_read_b128 v[162:165], v162 offset:3072
	ds_read_b128 v[168:171], v167
	ds_read_b128 v[172:175], v167 offset:1024
	ds_read_b128 v[182:185], v167 offset:2048
	ds_read_b128 v[186:189], v167 offset:3072
	s_mov_b32 m0, s61
	v_lshl_add_u64 v[226:227], s[44:45], 0, v[128:129]
	ds_read_b128 v[190:193], v148 offset:32768
	ds_read_b128 v[194:197], v148 offset:33792
	ds_read_b128 v[198:201], v148 offset:34816
	ds_read_b128 v[202:205], v148 offset:35840
	ds_read_b128 v[206:209], v148 offset:36864
	ds_read_b128 v[210:213], v148 offset:37888
	ds_read_b128 v[214:217], v148 offset:38912
	ds_read_b128 v[218:221], v148 offset:39936
	global_load_lds_dwordx4 v[226:227], off
	v_lshl_add_u64 v[226:227], s[44:45], 0, v[132:133]
	s_mov_b32 m0, s62
	s_nop 0
	global_load_lds_dwordx4 v[226:227], off
	s_waitcnt vmcnt(8)
	s_barrier
	s_setprio 1
	s_waitcnt lgkmcnt(0)
	v_mfma_f32_16x16x32_bf16 v[124:127], v[150:153], v[190:193], v[124:127]
	v_mfma_f32_16x16x32_bf16 v[120:123], v[158:161], v[190:193], v[120:123]
	v_mfma_f32_16x16x32_bf16 v[108:111], v[150:153], v[198:201], v[108:111]
	v_mfma_f32_16x16x32_bf16 v[104:107], v[158:161], v[198:201], v[104:107]
	v_mfma_f32_16x16x32_bf16 v[92:95], v[150:153], v[206:209], v[92:95]
	v_mfma_f32_16x16x32_bf16 v[88:91], v[158:161], v[206:209], v[88:91]
	v_mfma_f32_16x16x32_bf16 v[76:79], v[150:153], v[214:217], v[76:79]
	v_mfma_f32_16x16x32_bf16 v[72:75], v[158:161], v[214:217], v[72:75]
	v_mfma_f32_16x16x32_bf16 v[124:127], v[154:157], v[194:197], v[124:127]
	v_mfma_f32_16x16x32_bf16 v[120:123], v[162:165], v[194:197], v[120:123]
	v_mfma_f32_16x16x32_bf16 v[108:111], v[154:157], v[202:205], v[108:111]
	v_mfma_f32_16x16x32_bf16 v[104:107], v[162:165], v[202:205], v[104:107]
	v_mfma_f32_16x16x32_bf16 v[92:95], v[154:157], v[210:213], v[92:95]
	v_mfma_f32_16x16x32_bf16 v[88:91], v[162:165], v[210:213], v[88:91]
	v_mfma_f32_16x16x32_bf16 v[76:79], v[154:157], v[218:221], v[76:79]
	v_mfma_f32_16x16x32_bf16 v[72:75], v[162:165], v[218:221], v[72:75]
	s_setprio 0
	s_setprio 1
	v_mfma_f32_16x16x32_bf16 v[116:119], v[168:171], v[190:193], v[116:119]
	v_mfma_f32_16x16x32_bf16 v[112:115], v[182:185], v[190:193], v[112:115]
	v_mfma_f32_16x16x32_bf16 v[100:103], v[168:171], v[198:201], v[100:103]
	v_mfma_f32_16x16x32_bf16 v[96:99], v[182:185], v[198:201], v[96:99]
	v_mfma_f32_16x16x32_bf16 v[84:87], v[168:171], v[206:209], v[84:87]
	v_mfma_f32_16x16x32_bf16 v[80:83], v[182:185], v[206:209], v[80:83]
	v_mfma_f32_16x16x32_bf16 v[68:71], v[168:171], v[214:217], v[68:71]
	v_mfma_f32_16x16x32_bf16 v[64:67], v[182:185], v[214:217], v[64:67]
	v_mfma_f32_16x16x32_bf16 v[116:119], v[172:175], v[194:197], v[116:119]
	v_mfma_f32_16x16x32_bf16 v[112:115], v[186:189], v[194:197], v[112:115]
	v_mfma_f32_16x16x32_bf16 v[100:103], v[172:175], v[202:205], v[100:103]
	v_mfma_f32_16x16x32_bf16 v[96:99], v[186:189], v[202:205], v[96:99]
	v_mfma_f32_16x16x32_bf16 v[84:87], v[172:175], v[210:213], v[84:87]
	v_mfma_f32_16x16x32_bf16 v[80:83], v[186:189], v[210:213], v[80:83]
	v_mfma_f32_16x16x32_bf16 v[68:71], v[172:175], v[218:221], v[68:71]
	v_mfma_f32_16x16x32_bf16 v[64:67], v[186:189], v[218:221], v[64:67]
	s_setprio 0
	s_barrier
; #define PG8_STAGE(bufoff, gbase, voff) do { _Pragma("unroll") for (int _i = 0; _i < 2; ++_i) \
;         __builtin_amdgcn_global_load_lds((const unsigned*)((const char*)(gbase) + (voff)[_i]), (PG8_LAS unsigned*)(lds + (bufoff) + ldsw + _i * 8192), 16, 0, 0); } while (0)
; #define PG8_LDA(dst, b, h) do { _Pragma("unroll") for (int m = 0; m < 4; ++m) _Pragma("unroll") for (int k = 0; k < 2; ++k) dst[m][k] = *(const PG8_LAS bf16x8*)(lds + PG8_SA(b, h) + aoff + m * 2048 + k * 1024); } while (0)
; #define PG8_MMA(ai, bj, At, Bt) do { __builtin_amdgcn_s_setprio(1); _Pragma("unroll") for (int m = 0; m < 4; ++m) _Pragma("unroll") for (int n = 0; n < 2; ++n) _Pragma("unroll") for (int k = 0; k < 2; ++k) \
;         acc[ai][bj][m][n] = __builtin_amdgcn_mfma_f32_16x16x32_bf16(Bt[n][k], At[m][k], acc[ai][bj][m][n], 0, 0, 0); __builtin_amdgcn_s_setprio(0); } while (0)
; #define PG8_WAIT_V(n) asm volatile("s_waitcnt vmcnt(" #n ")" ::: "memory")
; #define PG8_WAIT_L(n) asm volatile("s_waitcnt lgkmcnt(" #n ")" ::: "memory")
; #define PG8_BAR __builtin_amdgcn_s_barrier()
; #define PG8_SCHED __builtin_amdgcn_sched_barrier(0)
; template <class Epi, class Sched, bool ALIGN_EPI = false, bool SP2 = false>
; __device__ __forceinline__ void gemm_phase(PG8_LAS unsigned char* lds, const Gemm g, const Sched& S, const Epi& E) {
;     ...
;             PG8_LDA(At, 1, 1); PG8_STAGE(PG8_SB(1, 0), b3, voffB); PG8_STAGE(PG8_SB(1, 1), b3 + hstep, voffB); PG8_STAGE(PG8_SA(1, 0), a3, voffA);
;             PG8_WAIT_V(8); PG8_WAIT_L(0); PG8_BAR; PG8_MMA(1, 0, At, B0); PG8_MMA(1, 1, At, B1); PG8_BAR; PG8_SCHED;
	s_mov_b32 m0, s69
	v_lshl_add_u64 v[142:143], v[142:143], 0, s[18:19]
	ds_read_b128 v[190:193], v148 offset:49152
	ds_read_b128 v[194:197], v148 offset:50176
	ds_read_b128 v[198:201], v148 offset:51200
	ds_read_b128 v[202:205], v148 offset:52224
	ds_read_b128 v[206:209], v148 offset:53248
	ds_read_b128 v[210:213], v148 offset:54272
	ds_read_b128 v[214:217], v148 offset:55296
	ds_read_b128 v[218:221], v148 offset:56320
	global_load_lds_dwordx4 v[142:143], off
	v_lshl_add_u64 v[142:143], v[176:177], 0, s[18:19]
	s_mov_b32 m0, s68
	s_nop 0
	global_load_lds_dwordx4 v[142:143], off
	v_lshl_add_u64 v[142:143], s[42:43], 0, v[130:131]
	s_mov_b32 m0, s79
	s_nop 0
	global_load_lds_dwordx4 v[142:143], off
	v_lshl_add_u64 v[142:143], s[42:43], 0, v[134:135]
	s_mov_b32 m0, s78
	s_nop 0
	global_load_lds_dwordx4 v[142:143], off
	v_lshl_add_u64 v[142:143], v[222:223], 0, s[18:19]
	s_mov_b32 m0, s64
	s_nop 0
	global_load_lds_dwordx4 v[142:143], off
	v_lshl_add_u64 v[142:143], v[224:225], 0, s[18:19]
	s_mov_b32 m0, s65
	s_nop 0
	global_load_lds_dwordx4 v[142:143], off
	s_waitcnt vmcnt(8)
	s_barrier
	s_setprio 1
	s_waitcnt lgkmcnt(0)
	v_mfma_f32_16x16x32_bf16 v[60:63], v[150:153], v[190:193], v[60:63]
	v_mfma_f32_16x16x32_bf16 v[56:59], v[158:161], v[190:193], v[56:59]
	v_mfma_f32_16x16x32_bf16 v[44:47], v[150:153], v[198:201], v[44:47]
	v_mfma_f32_16x16x32_bf16 v[40:43], v[158:161], v[198:201], v[40:43]
	v_mfma_f32_16x16x32_bf16 v[28:31], v[150:153], v[206:209], v[28:31]
	v_mfma_f32_16x16x32_bf16 v[24:27], v[158:161], v[206:209], v[24:27]
	v_mfma_f32_16x16x32_bf16 v[12:15], v[150:153], v[214:217], v[12:15]
	v_mfma_f32_16x16x32_bf16 v[8:11], v[158:161], v[214:217], v[8:11]
	v_mfma_f32_16x16x32_bf16 v[60:63], v[154:157], v[194:197], v[60:63]
	v_mfma_f32_16x16x32_bf16 v[56:59], v[162:165], v[194:197], v[56:59]
	v_mfma_f32_16x16x32_bf16 v[44:47], v[154:157], v[202:205], v[44:47]
	v_mfma_f32_16x16x32_bf16 v[40:43], v[162:165], v[202:205], v[40:43]
	v_mfma_f32_16x16x32_bf16 v[28:31], v[154:157], v[210:213], v[28:31]
	v_mfma_f32_16x16x32_bf16 v[24:27], v[162:165], v[210:213], v[24:27]
	v_mfma_f32_16x16x32_bf16 v[12:15], v[154:157], v[218:221], v[12:15]
	v_mfma_f32_16x16x32_bf16 v[8:11], v[162:165], v[218:221], v[8:11]
	s_setprio 0
	s_setprio 1
	v_mfma_f32_16x16x32_bf16 v[52:55], v[168:171], v[190:193], v[52:55]
	v_mfma_f32_16x16x32_bf16 v[48:51], v[182:185], v[190:193], v[48:51]
	v_mfma_f32_16x16x32_bf16 v[36:39], v[168:171], v[198:201], v[36:39]
	v_mfma_f32_16x16x32_bf16 v[32:35], v[182:185], v[198:201], v[32:35]
	v_mfma_f32_16x16x32_bf16 v[20:23], v[168:171], v[206:209], v[20:23]
	v_mfma_f32_16x16x32_bf16 v[16:19], v[182:185], v[206:209], v[16:19]
	v_mfma_f32_16x16x32_bf16 v[4:7], v[168:171], v[214:217], v[4:7]
	v_mfma_f32_16x16x32_bf16 v[0:3], v[182:185], v[214:217], v[0:3]
	v_mfma_f32_16x16x32_bf16 v[52:55], v[172:175], v[194:197], v[52:55]
	v_mfma_f32_16x16x32_bf16 v[48:51], v[186:189], v[194:197], v[48:51]
	v_mfma_f32_16x16x32_bf16 v[36:39], v[172:175], v[202:205], v[36:39]
	v_mfma_f32_16x16x32_bf16 v[32:35], v[186:189], v[202:205], v[32:35]
	v_mfma_f32_16x16x32_bf16 v[20:23], v[172:175], v[210:213], v[20:23]
	v_mfma_f32_16x16x32_bf16 v[16:19], v[186:189], v[210:213], v[16:19]
	v_mfma_f32_16x16x32_bf16 v[4:7], v[172:175], v[218:221], v[4:7]
	v_mfma_f32_16x16x32_bf16 v[0:3], v[186:189], v[218:221], v[0:3]
	s_setprio 0
	s_barrier
	s_movk_i32 s44, 0x100
	s_andn2_b64 vcc, exec, s[40:41]
	s_mov_b64 s[42:43], -1
	s_mov_b64 s[40:41], 0
	s_cbranch_vccz .LBB0_1320
	s_and_b64 vcc, exec, s[20:21]
	s_cbranch_vccz .LBB0_1323
	s_barrier

; #define PG8_STAGE(bufoff, gbase, voff) do { _Pragma("unroll") for (int _i = 0; _i < 2; ++_i) \
;         __builtin_amdgcn_global_load_lds((const unsigned*)((const char*)(gbase) + (voff)[_i]), (PG8_LAS unsigned*)(lds + (bufoff) + ldsw + _i * 8192), 16, 0, 0); } while (0)
; #define PG8_LDA(dst, b, h) do { _Pragma("unroll") for (int m = 0; m < 4; ++m) _Pragma("unroll") for (int k = 0; k < 2; ++k) dst[m][k] = *(const PG8_LAS bf16x8*)(lds + PG8_SA(b, h) + aoff + m * 2048 + k * 1024); } while (0)
; #define PG8_LDB(dst, b, h) do { _Pragma("unroll") for (int n = 0; n < 2; ++n) _Pragma("unroll") for (int k = 0; k < 2; ++k) dst[n][k] = *(const PG8_LAS bf16x8*)(lds + PG8_SB(b, h) + boff + n * 2048 + k * 1024); } while (0)
; #define PG8_MMA(ai, bj, At, Bt) do { __builtin_amdgcn_s_setprio(1); _Pragma("unroll") for (int m = 0; m < 4; ++m) _Pragma("unroll") for (int n = 0; n < 2; ++n) _Pragma("unroll") for (int k = 0; k < 2; ++k) \
;         acc[ai][bj][m][n] = __builtin_amdgcn_mfma_f32_16x16x32_bf16(Bt[n][k], At[m][k], acc[ai][bj][m][n], 0, 0, 0); __builtin_amdgcn_s_setprio(0); } while (0)
; #define PG8_WAIT_V(n) asm volatile("s_waitcnt vmcnt(" #n ")" ::: "memory")
; #define PG8_WAIT_L(n) asm volatile("s_waitcnt lgkmcnt(" #n ")" ::: "memory")
; #define PG8_BAR __builtin_amdgcn_s_barrier()
; #define PG8_SCHED __builtin_amdgcn_sched_barrier(0)
; template <class Epi, class Sched, bool ALIGN_EPI = false, bool SP2 = false>
; __device__ __forceinline__ void gemm_phase(PG8_LAS unsigned char* lds, const Gemm g, const Sched& S, const Epi& E) {
;     ...
;             const char* a2 = last ? nA : cA + (size_t)(t + 2) * kstep; const char* b2 = last ? nB : cB + (size_t)(t + 2) * kstep;
;             const char* a3 = a2 + kstep; const char* b3 = b2 + kstep;
;             if (last && has_next) S.a_ready(nxt);
;             if constexpr (SP2) {
;             PG8_LDB(B0, 0, 0); PG8_LDB(B1, 0, 1); PG8_SCHED; PG8_LDA(At, 0, 0); PG8_STAGE(PG8_SA(1, 1), a1 + hstep, voffA);
;             PG8_WAIT_V(8); PG8_WAIT_L(0); PG8_BAR; PG8_MMA(0, 0, At, B0); PG8_MMA(0, 1, At, B1); PG8_BAR; PG8_SCHED;
;             PG8_LDA(At, 0, 1); PG8_STAGE(PG8_SB(0, 0), b2, voffB); PG8_STAGE(PG8_SB(0, 1), b2 + hstep, voffB); PG8_STAGE(PG8_SA(0, 0), a2, voffA);
.LBB0_1414:
	ds_read_b128 v[154:157], v150
	ds_read_b128 v[158:161], v150 offset:1024
	ds_read_b128 v[162:165], v150 offset:2048
	ds_read_b128 v[168:171], v150 offset:3072
	ds_read_b128 v[172:175], v151
	ds_read_b128 v[180:183], v151 offset:1024
	ds_read_b128 v[184:187], v151 offset:2048
	ds_read_b128 v[188:191], v151 offset:3072
	s_add_u32 s38, s36, 0xffe00080
	s_addc_u32 s39, s37, -1
	s_cmpk_eq_i32 s58, 0x7c
	s_cselect_b32 s41, s25, s39
	s_cselect_b32 s40, s31, s38
	s_cselect_b32 s39, s23, s57
	s_cselect_b32 s38, s35, s56
	v_lshl_add_u64 v[146:147], s[36:37], 0, v[138:139]
	s_add_i32 m0, s46, 0xc000
	ds_read_b128 v[192:195], v152
	ds_read_b128 v[196:199], v152 offset:1024
	ds_read_b128 v[200:203], v152 offset:2048
	ds_read_b128 v[204:207], v152 offset:3072
	ds_read_b128 v[208:211], v152 offset:4096
	ds_read_b128 v[212:215], v152 offset:5120
	ds_read_b128 v[216:219], v152 offset:6144
	ds_read_b128 v[220:223], v152 offset:7168
	global_load_lds_dwordx4 v[146:147], off
	v_lshl_add_u64 v[146:147], s[36:37], 0, v[140:141]
	s_add_i32 m0, s46, 0xe000
	s_nop 0
	global_load_lds_dwordx4 v[146:147], off
	s_waitcnt vmcnt(8)
	s_barrier
	s_setprio 1
	s_waitcnt lgkmcnt(0)
	v_mfma_f32_16x16x32_bf16 v[124:127], v[154:157], v[192:195], v[124:127]
	v_mfma_f32_16x16x32_bf16 v[120:123], v[162:165], v[192:195], v[120:123]
	v_mfma_f32_16x16x32_bf16 v[108:111], v[154:157], v[200:203], v[108:111]
	v_mfma_f32_16x16x32_bf16 v[104:107], v[162:165], v[200:203], v[104:107]
	v_mfma_f32_16x16x32_bf16 v[92:95], v[154:157], v[208:211], v[92:95]
	v_mfma_f32_16x16x32_bf16 v[88:91], v[162:165], v[208:211], v[88:91]
	v_mfma_f32_16x16x32_bf16 v[76:79], v[154:157], v[216:219], v[76:79]
	v_mfma_f32_16x16x32_bf16 v[72:75], v[162:165], v[216:219], v[72:75]
	v_mfma_f32_16x16x32_bf16 v[124:127], v[158:161], v[196:199], v[124:127]
	v_mfma_f32_16x16x32_bf16 v[120:123], v[168:171], v[196:199], v[120:123]
	v_mfma_f32_16x16x32_bf16 v[108:111], v[158:161], v[204:207], v[108:111]
	v_mfma_f32_16x16x32_bf16 v[104:107], v[168:171], v[204:207], v[104:107]
	v_mfma_f32_16x16x32_bf16 v[92:95], v[158:161], v[212:215], v[92:95]
	v_mfma_f32_16x16x32_bf16 v[88:91], v[168:171], v[212:215], v[88:91]
	v_mfma_f32_16x16x32_bf16 v[76:79], v[158:161], v[220:223], v[76:79]
	v_mfma_f32_16x16x32_bf16 v[72:75], v[168:171], v[220:223], v[72:75]
	s_setprio 0
	s_setprio 1
	v_mfma_f32_16x16x32_bf16 v[116:119], v[172:175], v[192:195], v[116:119]
	v_mfma_f32_16x16x32_bf16 v[112:115], v[184:187], v[192:195], v[112:115]
	v_mfma_f32_16x16x32_bf16 v[100:103], v[172:175], v[200:203], v[100:103]
	v_mfma_f32_16x16x32_bf16 v[96:99], v[184:187], v[200:203], v[96:99]
	v_mfma_f32_16x16x32_bf16 v[84:87], v[172:175], v[208:211], v[84:87]
	v_mfma_f32_16x16x32_bf16 v[80:83], v[184:187], v[208:211], v[80:83]
	v_mfma_f32_16x16x32_bf16 v[68:71], v[172:175], v[216:219], v[68:71]
	v_mfma_f32_16x16x32_bf16 v[64:67], v[184:187], v[216:219], v[64:67]
	v_mfma_f32_16x16x32_bf16 v[116:119], v[180:183], v[196:199], v[116:119]
	v_mfma_f32_16x16x32_bf16 v[112:115], v[188:191], v[196:199], v[112:115]
	v_mfma_f32_16x16x32_bf16 v[100:103], v[180:183], v[204:207], v[100:103]
	v_mfma_f32_16x16x32_bf16 v[96:99], v[188:191], v[204:207], v[96:99]
	v_mfma_f32_16x16x32_bf16 v[84:87], v[180:183], v[212:215], v[84:87]
	v_mfma_f32_16x16x32_bf16 v[80:83], v[188:191], v[212:215], v[80:83]
	v_mfma_f32_16x16x32_bf16 v[68:71], v[180:183], v[220:223], v[68:71]
	v_mfma_f32_16x16x32_bf16 v[64:67], v[188:191], v[220:223], v[64:67]
	s_setprio 0
	s_barrier
	s_add_i32 s59, s53, s45
	v_lshl_add_u64 v[146:147], s[38:39], 0, v[130:131]
	s_mov_b32 m0, s59
	ds_read_b128 v[192:195], v152 offset:16384
	ds_read_b128 v[196:199], v152 offset:17408
	ds_read_b128 v[200:203], v152 offset:18432
	ds_read_b128 v[204:207], v152 offset:19456
	ds_read_b128 v[208:211], v152 offset:20480
	ds_read_b128 v[212:215], v152 offset:21504
	ds_read_b128 v[216:219], v152 offset:22528
	ds_read_b128 v[220:223], v152 offset:23552
	global_load_lds_dwordx4 v[146:147], off
	s_add_i32 m0, s59, 0x2000
	s_add_u32 s60, s38, 0x200000
	v_lshl_add_u64 v[176:177], s[38:39], 0, v[134:135]
	s_addc_u32 s61, s39, 0
	s_add_i32 s59, s55, s45
	global_load_lds_dwordx4 v[176:177], off
	v_lshl_add_u64 v[224:225], s[60:61], 0, v[130:131]
	s_mov_b32 m0, s59
	v_lshl_add_u64 v[226:227], s[40:41], 0, v[132:133]
	global_load_lds_dwordx4 v[224:225], off
	v_lshl_add_u64 v[224:225], s[60:61], 0, v[134:135]
	s_add_i32 m0, s59, 0x2000
	s_nop 0
	global_load_lds_dwordx4 v[224:225], off
	v_lshl_add_u64 v[224:225], s[40:41], 0, v[128:129]
	s_mov_b32 m0, s46
	s_nop 0
	global_load_lds_dwordx4 v[224:225], off
	s_mov_b32 m0, s47
	s_nop 0
	global_load_lds_dwordx4 v[226:227], off
	s_waitcnt vmcnt(8)
	s_barrier
; #define PG8_STAGE(bufoff, gbase, voff) do { _Pragma("unroll") for (int _i = 0; _i < 2; ++_i) \
;         __builtin_amdgcn_global_load_lds((const unsigned*)((const char*)(gbase) + (voff)[_i]), (PG8_LAS unsigned*)(lds + (bufoff) + ldsw + _i * 8192), 16, 0, 0); } while (0)
; #define PG8_LDA(dst, b, h) do { _Pragma("unroll") for (int m = 0; m < 4; ++m) _Pragma("unroll") for (int k = 0; k < 2; ++k) dst[m][k] = *(const PG8_LAS bf16x8*)(lds + PG8_SA(b, h) + aoff + m * 2048 + k * 1024); } while (0)
; #define PG8_LDB(dst, b, h) do { _Pragma("unroll") for (int n = 0; n < 2; ++n) _Pragma("unroll") for (int k = 0; k < 2; ++k) dst[n][k] = *(const PG8_LAS bf16x8*)(lds + PG8_SB(b, h) + boff + n * 2048 + k * 1024); } while (0)
; #define PG8_MMA(ai, bj, At, Bt) do { __builtin_amdgcn_s_setprio(1); _Pragma("unroll") for (int m = 0; m < 4; ++m) _Pragma("unroll") for (int n = 0; n < 2; ++n) _Pragma("unroll") for (int k = 0; k < 2; ++k) \
;         acc[ai][bj][m][n] = __builtin_amdgcn_mfma_f32_16x16x32_bf16(Bt[n][k], At[m][k], acc[ai][bj][m][n], 0, 0, 0); __builtin_amdgcn_s_setprio(0); } while (0)
; #define PG8_WAIT_V(n) asm volatile("s_waitcnt vmcnt(" #n ")" ::: "memory")
; #define PG8_WAIT_L(n) asm volatile("s_waitcnt lgkmcnt(" #n ")" ::: "memory")
; #define PG8_BAR __builtin_amdgcn_s_barrier()
; #define PG8_SCHED __builtin_amdgcn_sched_barrier(0)
; template <class Epi, class Sched, bool ALIGN_EPI = false, bool SP2 = false>
; __device__ __forceinline__ void gemm_phase(PG8_LAS unsigned char* lds, const Gemm g, const Sched& S, const Epi& E) {
;     ...
;             PG8_WAIT_V(8); PG8_WAIT_L(0); PG8_BAR; PG8_MMA(1, 0, At, B0); PG8_MMA(1, 1, At, B1); PG8_BAR; PG8_SCHED;
;             PG8_LDB(B0, 1, 0); PG8_LDB(B1, 1, 1); PG8_SCHED; PG8_LDA(At, 1, 0); PG8_STAGE(PG8_SA(0, 1), a2 + hstep, voffA);
;             PG8_WAIT_V(8); PG8_WAIT_L(0); PG8_BAR; PG8_MMA(0, 0, At, B0); PG8_MMA(0, 1, At, B1); PG8_BAR; PG8_SCHED;
	s_setprio 1
	s_waitcnt lgkmcnt(0)
	v_mfma_f32_16x16x32_bf16 v[60:63], v[154:157], v[192:195], v[60:63]
	v_mfma_f32_16x16x32_bf16 v[56:59], v[162:165], v[192:195], v[56:59]
	v_mfma_f32_16x16x32_bf16 v[44:47], v[154:157], v[200:203], v[44:47]
	v_mfma_f32_16x16x32_bf16 v[40:43], v[162:165], v[200:203], v[40:43]
	v_mfma_f32_16x16x32_bf16 v[28:31], v[154:157], v[208:211], v[28:31]
	v_mfma_f32_16x16x32_bf16 v[24:27], v[162:165], v[208:211], v[24:27]
	v_mfma_f32_16x16x32_bf16 v[12:15], v[154:157], v[216:219], v[12:15]
	v_mfma_f32_16x16x32_bf16 v[8:11], v[162:165], v[216:219], v[8:11]
	v_mfma_f32_16x16x32_bf16 v[60:63], v[158:161], v[196:199], v[60:63]
	v_mfma_f32_16x16x32_bf16 v[56:59], v[168:171], v[196:199], v[56:59]
	v_mfma_f32_16x16x32_bf16 v[44:47], v[158:161], v[204:207], v[44:47]
	v_mfma_f32_16x16x32_bf16 v[40:43], v[168:171], v[204:207], v[40:43]
	v_mfma_f32_16x16x32_bf16 v[28:31], v[158:161], v[212:215], v[28:31]
	v_mfma_f32_16x16x32_bf16 v[24:27], v[168:171], v[212:215], v[24:27]
	v_mfma_f32_16x16x32_bf16 v[12:15], v[158:161], v[220:223], v[12:15]
	v_mfma_f32_16x16x32_bf16 v[8:11], v[168:171], v[220:223], v[8:11]
	s_setprio 0
	s_setprio 1
	v_mfma_f32_16x16x32_bf16 v[52:55], v[172:175], v[192:195], v[52:55]
	v_mfma_f32_16x16x32_bf16 v[48:51], v[184:187], v[192:195], v[48:51]
	v_mfma_f32_16x16x32_bf16 v[36:39], v[172:175], v[200:203], v[36:39]
	v_mfma_f32_16x16x32_bf16 v[32:35], v[184:187], v[200:203], v[32:35]
	v_mfma_f32_16x16x32_bf16 v[20:23], v[172:175], v[208:211], v[20:23]
	v_mfma_f32_16x16x32_bf16 v[16:19], v[184:187], v[208:211], v[16:19]
	v_mfma_f32_16x16x32_bf16 v[4:7], v[172:175], v[216:219], v[4:7]
	v_mfma_f32_16x16x32_bf16 v[0:3], v[184:187], v[216:219], v[0:3]
	v_mfma_f32_16x16x32_bf16 v[52:55], v[180:183], v[196:199], v[52:55]
	v_mfma_f32_16x16x32_bf16 v[48:51], v[188:191], v[196:199], v[48:51]
	v_mfma_f32_16x16x32_bf16 v[36:39], v[180:183], v[204:207], v[36:39]
	v_mfma_f32_16x16x32_bf16 v[32:35], v[188:191], v[204:207], v[32:35]
	v_mfma_f32_16x16x32_bf16 v[20:23], v[180:183], v[212:215], v[20:23]
	v_mfma_f32_16x16x32_bf16 v[16:19], v[188:191], v[212:215], v[16:19]
	v_mfma_f32_16x16x32_bf16 v[4:7], v[180:183], v[220:223], v[4:7]
	v_mfma_f32_16x16x32_bf16 v[0:3], v[188:191], v[220:223], v[0:3]
	s_setprio 0
	s_barrier
	s_add_i32 s59, 0, 0x18000
	v_add_u32_e32 v167, s59, v149
	s_add_i32 s60, 0, 0x1c000
	ds_read_b128 v[154:157], v167
	ds_read_b128 v[158:161], v167 offset:1024
	ds_read_b128 v[162:165], v167 offset:2048
	ds_read_b128 v[168:171], v167 offset:3072
	v_add_u32_e32 v167, s60, v149
	ds_read_b128 v[172:175], v167
	ds_read_b128 v[180:183], v167 offset:1024
	ds_read_b128 v[184:187], v167 offset:2048
	ds_read_b128 v[188:191], v167 offset:3072
	s_add_u32 s40, s40, 0x200000
	s_addc_u32 s41, s41, 0
	s_mov_b32 m0, s48
	v_lshl_add_u64 v[228:229], s[40:41], 0, v[128:129]
	ds_read_b128 v[192:195], v152 offset:32768
	ds_read_b128 v[196:199], v152 offset:33792
	ds_read_b128 v[200:203], v152 offset:34816
	ds_read_b128 v[204:207], v152 offset:35840
	ds_read_b128 v[208:211], v152 offset:36864
	ds_read_b128 v[212:215], v152 offset:37888
	ds_read_b128 v[216:219], v152 offset:38912
	ds_read_b128 v[220:223], v152 offset:39936
	global_load_lds_dwordx4 v[228:229], off
	v_lshl_add_u64 v[228:229], s[40:41], 0, v[132:133]
	s_mov_b32 m0, s49
	s_nop 0
	global_load_lds_dwordx4 v[228:229], off
	s_waitcnt vmcnt(8)
	s_barrier
	s_setprio 1
	s_waitcnt lgkmcnt(0)
	v_mfma_f32_16x16x32_bf16 v[124:127], v[154:157], v[192:195], v[124:127]
	v_mfma_f32_16x16x32_bf16 v[120:123], v[162:165], v[192:195], v[120:123]
	v_mfma_f32_16x16x32_bf16 v[108:111], v[154:157], v[200:203], v[108:111]
	v_mfma_f32_16x16x32_bf16 v[104:107], v[162:165], v[200:203], v[104:107]
	v_mfma_f32_16x16x32_bf16 v[92:95], v[154:157], v[208:211], v[92:95]
	v_mfma_f32_16x16x32_bf16 v[88:91], v[162:165], v[208:211], v[88:91]
	v_mfma_f32_16x16x32_bf16 v[76:79], v[154:157], v[216:219], v[76:79]
	v_mfma_f32_16x16x32_bf16 v[72:75], v[162:165], v[216:219], v[72:75]
	v_mfma_f32_16x16x32_bf16 v[124:127], v[158:161], v[196:199], v[124:127]
	v_mfma_f32_16x16x32_bf16 v[120:123], v[168:171], v[196:199], v[120:123]
	v_mfma_f32_16x16x32_bf16 v[108:111], v[158:161], v[204:207], v[108:111]
	v_mfma_f32_16x16x32_bf16 v[104:107], v[168:171], v[204:207], v[104:107]
	v_mfma_f32_16x16x32_bf16 v[92:95], v[158:161], v[212:215], v[92:95]
	v_mfma_f32_16x16x32_bf16 v[88:91], v[168:171], v[212:215], v[88:91]
	v_mfma_f32_16x16x32_bf16 v[76:79], v[158:161], v[220:223], v[76:79]
	v_mfma_f32_16x16x32_bf16 v[72:75], v[168:171], v[220:223], v[72:75]
	s_setprio 0
	s_setprio 1
	v_mfma_f32_16x16x32_bf16 v[116:119], v[172:175], v[192:195], v[116:119]
	v_mfma_f32_16x16x32_bf16 v[112:115], v[184:187], v[192:195], v[112:115]
	v_mfma_f32_16x16x32_bf16 v[100:103], v[172:175], v[200:203], v[100:103]
	v_mfma_f32_16x16x32_bf16 v[96:99], v[184:187], v[200:203], v[96:99]
	v_mfma_f32_16x16x32_bf16 v[84:87], v[172:175], v[208:211], v[84:87]
	v_mfma_f32_16x16x32_bf16 v[80:83], v[184:187], v[208:211], v[80:83]
	v_mfma_f32_16x16x32_bf16 v[68:71], v[172:175], v[216:219], v[68:71]
	v_mfma_f32_16x16x32_bf16 v[64:67], v[184:187], v[216:219], v[64:67]
	v_mfma_f32_16x16x32_bf16 v[116:119], v[180:183], v[196:199], v[116:119]
	v_mfma_f32_16x16x32_bf16 v[112:115], v[188:191], v[196:199], v[112:115]
	v_mfma_f32_16x16x32_bf16 v[100:103], v[180:183], v[204:207], v[100:103]
	v_mfma_f32_16x16x32_bf16 v[96:99], v[188:191], v[204:207], v[96:99]
	v_mfma_f32_16x16x32_bf16 v[84:87], v[180:183], v[212:215], v[84:87]
	v_mfma_f32_16x16x32_bf16 v[80:83], v[188:191], v[212:215], v[80:83]
	v_mfma_f32_16x16x32_bf16 v[68:71], v[180:183], v[220:223], v[68:71]
	v_mfma_f32_16x16x32_bf16 v[64:67], v[188:191], v[220:223], v[64:67]
	s_setprio 0
	s_barrier
; #define PG8_STAGE(bufoff, gbase, voff) do { _Pragma("unroll") for (int _i = 0; _i < 2; ++_i) \
;         __builtin_amdgcn_global_load_lds((const unsigned*)((const char*)(gbase) + (voff)[_i]), (PG8_LAS unsigned*)(lds + (bufoff) + ldsw + _i * 8192), 16, 0, 0); } while (0)
; #define PG8_LDA(dst, b, h) do { _Pragma("unroll") for (int m = 0; m < 4; ++m) _Pragma("unroll") for (int k = 0; k < 2; ++k) dst[m][k] = *(const PG8_LAS bf16x8*)(lds + PG8_SA(b, h) + aoff + m * 2048 + k * 1024); } while (0)
; #define PG8_MMA(ai, bj, At, Bt) do { __builtin_amdgcn_s_setprio(1); _Pragma("unroll") for (int m = 0; m < 4; ++m) _Pragma("unroll") for (int n = 0; n < 2; ++n) _Pragma("unroll") for (int k = 0; k < 2; ++k) \
;         acc[ai][bj][m][n] = __builtin_amdgcn_mfma_f32_16x16x32_bf16(Bt[n][k], At[m][k], acc[ai][bj][m][n], 0, 0, 0); __builtin_amdgcn_s_setprio(0); } while (0)
; #define PG8_WAIT_V(n) asm volatile("s_waitcnt vmcnt(" #n ")" ::: "memory")
; #define PG8_WAIT_L(n) asm volatile("s_waitcnt lgkmcnt(" #n ")" ::: "memory")
; #define PG8_BAR __builtin_amdgcn_s_barrier()
; #define PG8_SCHED __builtin_amdgcn_sched_barrier(0)
; template <class Epi, class Sched, bool ALIGN_EPI = false, bool SP2 = false>
; __device__ __forceinline__ void gemm_phase(PG8_LAS unsigned char* lds, const Gemm g, const Sched& S, const Epi& E) {
;     ...
;             PG8_LDA(At, 1, 1); PG8_STAGE(PG8_SB(1, 0), b3, voffB); PG8_STAGE(PG8_SB(1, 1), b3 + hstep, voffB); PG8_STAGE(PG8_SA(1, 0), a3, voffA);
;             PG8_WAIT_V(8); PG8_WAIT_L(0); PG8_BAR; PG8_MMA(1, 0, At, B0); PG8_MMA(1, 1, At, B1); PG8_BAR; PG8_SCHED;
	s_add_i32 s40, s59, s45
	v_lshl_add_u64 v[146:147], v[146:147], 0, s[18:19]
	s_mov_b32 m0, s40
	ds_read_b128 v[192:195], v152 offset:49152
	ds_read_b128 v[196:199], v152 offset:50176
	ds_read_b128 v[200:203], v152 offset:51200
	ds_read_b128 v[204:207], v152 offset:52224
	ds_read_b128 v[208:211], v152 offset:53248
	ds_read_b128 v[212:215], v152 offset:54272
	ds_read_b128 v[216:219], v152 offset:55296
	ds_read_b128 v[220:223], v152 offset:56320
	global_load_lds_dwordx4 v[146:147], off
	s_add_i32 m0, s40, 0x2000
	s_add_u32 s38, s38, 0x200080
	v_lshl_add_u64 v[146:147], v[176:177], 0, s[18:19]
	s_addc_u32 s39, s39, 0
	s_add_i32 s40, s60, s45
	global_load_lds_dwordx4 v[146:147], off
	v_lshl_add_u64 v[146:147], s[38:39], 0, v[130:131]
	s_mov_b32 m0, s40
	s_nop 0
	global_load_lds_dwordx4 v[146:147], off
	v_lshl_add_u64 v[146:147], s[38:39], 0, v[134:135]
	s_add_i32 m0, s40, 0x2000
	s_nop 0
	global_load_lds_dwordx4 v[146:147], off
	v_lshl_add_u64 v[146:147], v[224:225], 0, s[18:19]
	s_mov_b32 m0, s51
	s_nop 0
	global_load_lds_dwordx4 v[146:147], off
	v_lshl_add_u64 v[146:147], v[226:227], 0, s[18:19]
	s_mov_b32 m0, s52
	s_nop 0
	global_load_lds_dwordx4 v[146:147], off
	s_waitcnt vmcnt(8)
	s_barrier
	s_setprio 1
	s_waitcnt lgkmcnt(0)
	v_mfma_f32_16x16x32_bf16 v[60:63], v[154:157], v[192:195], v[60:63]
	v_mfma_f32_16x16x32_bf16 v[56:59], v[162:165], v[192:195], v[56:59]
	v_mfma_f32_16x16x32_bf16 v[44:47], v[154:157], v[200:203], v[44:47]
	v_mfma_f32_16x16x32_bf16 v[40:43], v[162:165], v[200:203], v[40:43]
	v_mfma_f32_16x16x32_bf16 v[28:31], v[154:157], v[208:211], v[28:31]
	v_mfma_f32_16x16x32_bf16 v[24:27], v[162:165], v[208:211], v[24:27]
	v_mfma_f32_16x16x32_bf16 v[12:15], v[154:157], v[216:219], v[12:15]
	v_mfma_f32_16x16x32_bf16 v[8:11], v[162:165], v[216:219], v[8:11]
	v_mfma_f32_16x16x32_bf16 v[60:63], v[158:161], v[196:199], v[60:63]
	v_mfma_f32_16x16x32_bf16 v[56:59], v[168:171], v[196:199], v[56:59]
	v_mfma_f32_16x16x32_bf16 v[44:47], v[158:161], v[204:207], v[44:47]
	v_mfma_f32_16x16x32_bf16 v[40:43], v[168:171], v[204:207], v[40:43]
	v_mfma_f32_16x16x32_bf16 v[28:31], v[158:161], v[212:215], v[28:31]
	v_mfma_f32_16x16x32_bf16 v[24:27], v[168:171], v[212:215], v[24:27]
	v_mfma_f32_16x16x32_bf16 v[12:15], v[158:161], v[220:223], v[12:15]
	v_mfma_f32_16x16x32_bf16 v[8:11], v[168:171], v[220:223], v[8:11]
	s_setprio 0
	s_setprio 1
	v_mfma_f32_16x16x32_bf16 v[52:55], v[172:175], v[192:195], v[52:55]
	v_mfma_f32_16x16x32_bf16 v[48:51], v[184:187], v[192:195], v[48:51]
	v_mfma_f32_16x16x32_bf16 v[36:39], v[172:175], v[200:203], v[36:39]
	v_mfma_f32_16x16x32_bf16 v[32:35], v[184:187], v[200:203], v[32:35]
	v_mfma_f32_16x16x32_bf16 v[20:23], v[172:175], v[208:211], v[20:23]
	v_mfma_f32_16x16x32_bf16 v[16:19], v[184:187], v[208:211], v[16:19]
	v_mfma_f32_16x16x32_bf16 v[4:7], v[172:175], v[216:219], v[4:7]
	v_mfma_f32_16x16x32_bf16 v[0:3], v[184:187], v[216:219], v[0:3]
	v_mfma_f32_16x16x32_bf16 v[52:55], v[180:183], v[196:199], v[52:55]
	v_mfma_f32_16x16x32_bf16 v[48:51], v[188:191], v[196:199], v[48:51]
	v_mfma_f32_16x16x32_bf16 v[36:39], v[180:183], v[204:207], v[36:39]
	v_mfma_f32_16x16x32_bf16 v[32:35], v[188:191], v[204:207], v[32:35]
	v_mfma_f32_16x16x32_bf16 v[20:23], v[180:183], v[212:215], v[20:23]
	v_mfma_f32_16x16x32_bf16 v[16:19], v[188:191], v[212:215], v[16:19]
	v_mfma_f32_16x16x32_bf16 v[4:7], v[180:183], v[220:223], v[4:7]
	v_mfma_f32_16x16x32_bf16 v[0:3], v[188:191], v[220:223], v[0:3]
	s_setprio 0
	s_barrier
	s_add_i32 s58, s58, 2
	s_add_u32 s36, s36, 0x100
	s_addc_u32 s37, s37, 0
	s_add_u32 s56, s56, 0x100
	s_addc_u32 s57, s57, 0
	s_cmpk_gt_u32 s58, 0x7d
	s_cbranch_scc0 .LBB0_1414
	s_and_b64 vcc, exec, s[20:21]
	s_cbranch_vccz .LBB0_1417
	s_barrier

; #define PG8_STAGE(bufoff, gbase, voff) do { _Pragma("unroll") for (int _i = 0; _i < 2; ++_i) \
;         __builtin_amdgcn_global_load_lds((const unsigned*)((const char*)(gbase) + (voff)[_i]), (PG8_LAS unsigned*)(lds + (bufoff) + ldsw + _i * 8192), 16, 0, 0); } while (0)
; #define PG8_LDA(dst, b, h) do { _Pragma("unroll") for (int m = 0; m < 4; ++m) _Pragma("unroll") for (int k = 0; k < 2; ++k) dst[m][k] = *(const PG8_LAS bf16x8*)(lds + PG8_SA(b, h) + aoff + m * 2048 + k * 1024); } while (0)
; #define PG8_LDB(dst, b, h) do { _Pragma("unroll") for (int n = 0; n < 2; ++n) _Pragma("unroll") for (int k = 0; k < 2; ++k) dst[n][k] = *(const PG8_LAS bf16x8*)(lds + PG8_SB(b, h) + boff + n * 2048 + k * 1024); } while (0)
; #define PG8_MMA(ai, bj, At, Bt) do { __builtin_amdgcn_s_setprio(1); _Pragma("unroll") for (int m = 0; m < 4; ++m) _Pragma("unroll") for (int n = 0; n < 2; ++n) _Pragma("unroll") for (int k = 0; k < 2; ++k) \
;         acc[ai][bj][m][n] = __builtin_amdgcn_mfma_f32_16x16x32_bf16(Bt[n][k], At[m][k], acc[ai][bj][m][n], 0, 0, 0); __builtin_amdgcn_s_setprio(0); } while (0)
; #define PG8_WAIT_V(n) asm volatile("s_waitcnt vmcnt(" #n ")" ::: "memory")
; #define PG8_WAIT_L(n) asm volatile("s_waitcnt lgkmcnt(" #n ")" ::: "memory")
; #define PG8_BAR __builtin_amdgcn_s_barrier()
; #define PG8_SCHED __builtin_amdgcn_sched_barrier(0)
; template <class Epi, class Sched, bool ALIGN_EPI = false, bool SP2 = false>
; __device__ __forceinline__ void gemm_phase(PG8_LAS unsigned char* lds, const Gemm g, const Sched& S, const Epi& E) {
;     ...
;             const char* a2 = last ? nA : cA + (size_t)(t + 2) * kstep; const char* b2 = last ? nB : cB + (size_t)(t + 2) * kstep;
;             const char* a3 = a2 + kstep; const char* b3 = b2 + kstep;
;             if (last && has_next) S.a_ready(nxt);
;             if constexpr (SP2) {
;             PG8_LDB(B0, 0, 0); PG8_LDB(B1, 0, 1); PG8_SCHED; PG8_LDA(At, 0, 0); PG8_STAGE(PG8_SA(1, 1), a1 + hstep, voffA);
;             PG8_WAIT_V(8); PG8_WAIT_L(0); PG8_BAR; PG8_MMA(0, 0, At, B0); PG8_MMA(0, 1, At, B1); PG8_BAR; PG8_SCHED;
;             PG8_LDA(At, 0, 1); PG8_STAGE(PG8_SB(0, 0), b2, voffB); PG8_STAGE(PG8_SB(0, 1), b2 + hstep, voffB); PG8_STAGE(PG8_SA(0, 0), a2, voffA);
.LBB0_1562:
	ds_read_b128 v[144:147], v155
	ds_read_b128 v[148:151], v155 offset:1024
	ds_read_b128 v[160:163], v155 offset:2048
	ds_read_b128 v[164:167], v155 offset:3072
	ds_read_b128 v[168:171], v156
	ds_read_b128 v[172:175], v156 offset:1024
	ds_read_b128 v[176:179], v156 offset:2048
	ds_read_b128 v[180:183], v156 offset:3072
	s_add_u32 s30, s28, 0xfff80080
	s_addc_u32 s31, s29, -1
	s_cmp_eq_u32 s53, 28
	s_cselect_b32 s35, s21, s31
	s_cselect_b32 s34, s49, s30
	s_cselect_b32 s31, s19, s52
	s_cselect_b32 s30, s50, s51
	v_lshl_add_u64 v[216:217], s[28:29], 0, v[136:137]
	s_add_i32 m0, s27, 0xc000
	ds_read_b128 v[184:187], v157
	ds_read_b128 v[188:191], v157 offset:1024
	ds_read_b128 v[192:195], v157 offset:2048
	ds_read_b128 v[196:199], v157 offset:3072
	ds_read_b128 v[200:203], v157 offset:4096
	ds_read_b128 v[204:207], v157 offset:5120
	ds_read_b128 v[208:211], v157 offset:6144
	ds_read_b128 v[212:215], v157 offset:7168
	global_load_lds_dwordx4 v[216:217], off
	v_lshl_add_u64 v[216:217], s[28:29], 0, v[138:139]
	s_add_i32 m0, s27, 0xe000
	s_nop 0
	global_load_lds_dwordx4 v[216:217], off
	s_waitcnt vmcnt(8)
	s_barrier
	s_setprio 1
	s_waitcnt lgkmcnt(0)
	v_mfma_f32_16x16x32_bf16 v[124:127], v[144:147], v[184:187], v[124:127]
	v_mfma_f32_16x16x32_bf16 v[120:123], v[160:163], v[184:187], v[120:123]
	v_mfma_f32_16x16x32_bf16 v[108:111], v[144:147], v[192:195], v[108:111]
	v_mfma_f32_16x16x32_bf16 v[104:107], v[160:163], v[192:195], v[104:107]
	v_mfma_f32_16x16x32_bf16 v[92:95], v[144:147], v[200:203], v[92:95]
	v_mfma_f32_16x16x32_bf16 v[88:91], v[160:163], v[200:203], v[88:91]
	v_mfma_f32_16x16x32_bf16 v[76:79], v[144:147], v[208:211], v[76:79]
	v_mfma_f32_16x16x32_bf16 v[72:75], v[160:163], v[208:211], v[72:75]
	v_mfma_f32_16x16x32_bf16 v[124:127], v[148:151], v[188:191], v[124:127]
	v_mfma_f32_16x16x32_bf16 v[120:123], v[164:167], v[188:191], v[120:123]
	v_mfma_f32_16x16x32_bf16 v[108:111], v[148:151], v[196:199], v[108:111]
	v_mfma_f32_16x16x32_bf16 v[104:107], v[164:167], v[196:199], v[104:107]
	v_mfma_f32_16x16x32_bf16 v[92:95], v[148:151], v[204:207], v[92:95]
	v_mfma_f32_16x16x32_bf16 v[88:91], v[164:167], v[204:207], v[88:91]
	v_mfma_f32_16x16x32_bf16 v[76:79], v[148:151], v[212:215], v[76:79]
	v_mfma_f32_16x16x32_bf16 v[72:75], v[164:167], v[212:215], v[72:75]
	s_setprio 0
	s_setprio 1
	v_mfma_f32_16x16x32_bf16 v[116:119], v[168:171], v[184:187], v[116:119]
	v_mfma_f32_16x16x32_bf16 v[112:115], v[176:179], v[184:187], v[112:115]
	v_mfma_f32_16x16x32_bf16 v[100:103], v[168:171], v[192:195], v[100:103]
	v_mfma_f32_16x16x32_bf16 v[96:99], v[176:179], v[192:195], v[96:99]
	v_mfma_f32_16x16x32_bf16 v[84:87], v[168:171], v[200:203], v[84:87]
	v_mfma_f32_16x16x32_bf16 v[80:83], v[176:179], v[200:203], v[80:83]
	v_mfma_f32_16x16x32_bf16 v[68:71], v[168:171], v[208:211], v[68:71]
	v_mfma_f32_16x16x32_bf16 v[64:67], v[176:179], v[208:211], v[64:67]
	v_mfma_f32_16x16x32_bf16 v[116:119], v[172:175], v[188:191], v[116:119]
	v_mfma_f32_16x16x32_bf16 v[112:115], v[180:183], v[188:191], v[112:115]
	v_mfma_f32_16x16x32_bf16 v[100:103], v[172:175], v[196:199], v[100:103]
	v_mfma_f32_16x16x32_bf16 v[96:99], v[180:183], v[196:199], v[96:99]
	v_mfma_f32_16x16x32_bf16 v[84:87], v[172:175], v[204:207], v[84:87]
	v_mfma_f32_16x16x32_bf16 v[80:83], v[180:183], v[204:207], v[80:83]
	v_mfma_f32_16x16x32_bf16 v[68:71], v[172:175], v[212:215], v[68:71]
	v_mfma_f32_16x16x32_bf16 v[64:67], v[180:183], v[212:215], v[64:67]
	s_setprio 0
	s_barrier
	s_add_i32 s55, s46, s39
	v_lshl_add_u64 v[216:217], s[30:31], 0, v[130:131]
	s_mov_b32 m0, s55
	ds_read_b128 v[184:187], v157 offset:16384
	ds_read_b128 v[188:191], v157 offset:17408
	ds_read_b128 v[192:195], v157 offset:18432
	ds_read_b128 v[196:199], v157 offset:19456
	ds_read_b128 v[200:203], v157 offset:20480
	ds_read_b128 v[204:207], v157 offset:21504
	ds_read_b128 v[208:211], v157 offset:22528
	ds_read_b128 v[212:215], v157 offset:23552
	global_load_lds_dwordx4 v[216:217], off
	s_add_i32 m0, s55, 0x2000
	s_add_u32 s56, s30, 0x80000
	v_lshl_add_u64 v[218:219], s[30:31], 0, v[134:135]
	s_addc_u32 s57, s31, 0
	s_add_i32 s55, s47, s39
	global_load_lds_dwordx4 v[218:219], off
	v_lshl_add_u64 v[220:221], s[56:57], 0, v[130:131]
	s_mov_b32 m0, s55
	v_lshl_add_u64 v[222:223], s[34:35], 0, v[132:133]
	global_load_lds_dwordx4 v[220:221], off
	v_lshl_add_u64 v[220:221], s[56:57], 0, v[134:135]
	s_add_i32 m0, s55, 0x2000
	s_nop 0
	global_load_lds_dwordx4 v[220:221], off
	v_lshl_add_u64 v[220:221], s[34:35], 0, v[128:129]
	s_mov_b32 m0, s27
	s_nop 0
	global_load_lds_dwordx4 v[220:221], off
	s_mov_b32 m0, s40
	s_nop 0
	global_load_lds_dwordx4 v[222:223], off
	s_waitcnt vmcnt(8)
	s_barrier
; #define PG8_STAGE(bufoff, gbase, voff) do { _Pragma("unroll") for (int _i = 0; _i < 2; ++_i) \
;         __builtin_amdgcn_global_load_lds((const unsigned*)((const char*)(gbase) + (voff)[_i]), (PG8_LAS unsigned*)(lds + (bufoff) + ldsw + _i * 8192), 16, 0, 0); } while (0)
; #define PG8_LDA(dst, b, h) do { _Pragma("unroll") for (int m = 0; m < 4; ++m) _Pragma("unroll") for (int k = 0; k < 2; ++k) dst[m][k] = *(const PG8_LAS bf16x8*)(lds + PG8_SA(b, h) + aoff + m * 2048 + k * 1024); } while (0)
; #define PG8_LDB(dst, b, h) do { _Pragma("unroll") for (int n = 0; n < 2; ++n) _Pragma("unroll") for (int k = 0; k < 2; ++k) dst[n][k] = *(const PG8_LAS bf16x8*)(lds + PG8_SB(b, h) + boff + n * 2048 + k * 1024); } while (0)
; #define PG8_MMA(ai, bj, At, Bt) do { __builtin_amdgcn_s_setprio(1); _Pragma("unroll") for (int m = 0; m < 4; ++m) _Pragma("unroll") for (int n = 0; n < 2; ++n) _Pragma("unroll") for (int k = 0; k < 2; ++k) \
;         acc[ai][bj][m][n] = __builtin_amdgcn_mfma_f32_16x16x32_bf16(Bt[n][k], At[m][k], acc[ai][bj][m][n], 0, 0, 0); __builtin_amdgcn_s_setprio(0); } while (0)
; #define PG8_WAIT_V(n) asm volatile("s_waitcnt vmcnt(" #n ")" ::: "memory")
; #define PG8_WAIT_L(n) asm volatile("s_waitcnt lgkmcnt(" #n ")" ::: "memory")
; #define PG8_BAR __builtin_amdgcn_s_barrier()
; #define PG8_SCHED __builtin_amdgcn_sched_barrier(0)
; template <class Epi, class Sched, bool ALIGN_EPI = false, bool SP2 = false>
; __device__ __forceinline__ void gemm_phase(PG8_LAS unsigned char* lds, const Gemm g, const Sched& S, const Epi& E) {
;     ...
;             PG8_WAIT_V(8); PG8_WAIT_L(0); PG8_BAR; PG8_MMA(1, 0, At, B0); PG8_MMA(1, 1, At, B1); PG8_BAR; PG8_SCHED;
;             PG8_LDB(B0, 1, 0); PG8_LDB(B1, 1, 1); PG8_SCHED; PG8_LDA(At, 1, 0); PG8_STAGE(PG8_SA(0, 1), a2 + hstep, voffA);
;             PG8_WAIT_V(8); PG8_WAIT_L(0); PG8_BAR; PG8_MMA(0, 0, At, B0); PG8_MMA(0, 1, At, B1); PG8_BAR; PG8_SCHED;
	s_setprio 1
	s_waitcnt lgkmcnt(0)
	v_mfma_f32_16x16x32_bf16 v[60:63], v[144:147], v[184:187], v[60:63]
	v_mfma_f32_16x16x32_bf16 v[56:59], v[160:163], v[184:187], v[56:59]
	v_mfma_f32_16x16x32_bf16 v[44:47], v[144:147], v[192:195], v[44:47]
	v_mfma_f32_16x16x32_bf16 v[40:43], v[160:163], v[192:195], v[40:43]
	v_mfma_f32_16x16x32_bf16 v[28:31], v[144:147], v[200:203], v[28:31]
	v_mfma_f32_16x16x32_bf16 v[24:27], v[160:163], v[200:203], v[24:27]
	v_mfma_f32_16x16x32_bf16 v[12:15], v[144:147], v[208:211], v[12:15]
	v_mfma_f32_16x16x32_bf16 v[8:11], v[160:163], v[208:211], v[8:11]
	v_mfma_f32_16x16x32_bf16 v[60:63], v[148:151], v[188:191], v[60:63]
	v_mfma_f32_16x16x32_bf16 v[56:59], v[164:167], v[188:191], v[56:59]
	v_mfma_f32_16x16x32_bf16 v[44:47], v[148:151], v[196:199], v[44:47]
	v_mfma_f32_16x16x32_bf16 v[40:43], v[164:167], v[196:199], v[40:43]
	v_mfma_f32_16x16x32_bf16 v[28:31], v[148:151], v[204:207], v[28:31]
	v_mfma_f32_16x16x32_bf16 v[24:27], v[164:167], v[204:207], v[24:27]
	v_mfma_f32_16x16x32_bf16 v[12:15], v[148:151], v[212:215], v[12:15]
	v_mfma_f32_16x16x32_bf16 v[8:11], v[164:167], v[212:215], v[8:11]
	s_setprio 0
	s_setprio 1
	v_mfma_f32_16x16x32_bf16 v[52:55], v[168:171], v[184:187], v[52:55]
	v_mfma_f32_16x16x32_bf16 v[48:51], v[176:179], v[184:187], v[48:51]
	v_mfma_f32_16x16x32_bf16 v[36:39], v[168:171], v[192:195], v[36:39]
	v_mfma_f32_16x16x32_bf16 v[32:35], v[176:179], v[192:195], v[32:35]
	v_mfma_f32_16x16x32_bf16 v[20:23], v[168:171], v[200:203], v[20:23]
	v_mfma_f32_16x16x32_bf16 v[16:19], v[176:179], v[200:203], v[16:19]
	v_mfma_f32_16x16x32_bf16 v[4:7], v[168:171], v[208:211], v[4:7]
	v_mfma_f32_16x16x32_bf16 v[0:3], v[176:179], v[208:211], v[0:3]
	v_mfma_f32_16x16x32_bf16 v[52:55], v[172:175], v[188:191], v[52:55]
	v_mfma_f32_16x16x32_bf16 v[48:51], v[180:183], v[188:191], v[48:51]
	v_mfma_f32_16x16x32_bf16 v[36:39], v[172:175], v[196:199], v[36:39]
	v_mfma_f32_16x16x32_bf16 v[32:35], v[180:183], v[196:199], v[32:35]
	v_mfma_f32_16x16x32_bf16 v[20:23], v[172:175], v[204:207], v[20:23]
	v_mfma_f32_16x16x32_bf16 v[16:19], v[180:183], v[204:207], v[16:19]
	v_mfma_f32_16x16x32_bf16 v[4:7], v[172:175], v[212:215], v[4:7]
	v_mfma_f32_16x16x32_bf16 v[0:3], v[180:183], v[212:215], v[0:3]
	s_setprio 0
	s_barrier
	s_add_i32 s55, 0, 0x18000
	v_add_u32_e32 v159, s55, v153
	s_add_i32 s56, 0, 0x1c000
	ds_read_b128 v[144:147], v159
	ds_read_b128 v[148:151], v159 offset:1024
	ds_read_b128 v[160:163], v159 offset:2048
	ds_read_b128 v[164:167], v159 offset:3072
	v_add_u32_e32 v159, s56, v153
	ds_read_b128 v[168:171], v159
	ds_read_b128 v[172:175], v159 offset:1024
	ds_read_b128 v[176:179], v159 offset:2048
	ds_read_b128 v[180:183], v159 offset:3072
	s_add_u32 s34, s34, 0x80000
	s_addc_u32 s35, s35, 0
	s_mov_b32 m0, s41
	v_lshl_add_u64 v[224:225], s[34:35], 0, v[128:129]
	ds_read_b128 v[184:187], v157 offset:32768
	ds_read_b128 v[188:191], v157 offset:33792
	ds_read_b128 v[192:195], v157 offset:34816
	ds_read_b128 v[196:199], v157 offset:35840
	ds_read_b128 v[200:203], v157 offset:36864
	ds_read_b128 v[204:207], v157 offset:37888
	ds_read_b128 v[208:211], v157 offset:38912
	ds_read_b128 v[212:215], v157 offset:39936
	global_load_lds_dwordx4 v[224:225], off
	v_lshl_add_u64 v[224:225], s[34:35], 0, v[132:133]
	s_mov_b32 m0, s42
	s_nop 0
	global_load_lds_dwordx4 v[224:225], off
	s_waitcnt vmcnt(8)
	s_barrier
	s_setprio 1
	s_waitcnt lgkmcnt(0)
	v_mfma_f32_16x16x32_bf16 v[124:127], v[144:147], v[184:187], v[124:127]
	v_mfma_f32_16x16x32_bf16 v[120:123], v[160:163], v[184:187], v[120:123]
	v_mfma_f32_16x16x32_bf16 v[108:111], v[144:147], v[192:195], v[108:111]
	v_mfma_f32_16x16x32_bf16 v[104:107], v[160:163], v[192:195], v[104:107]
	v_mfma_f32_16x16x32_bf16 v[92:95], v[144:147], v[200:203], v[92:95]
	v_mfma_f32_16x16x32_bf16 v[88:91], v[160:163], v[200:203], v[88:91]
	v_mfma_f32_16x16x32_bf16 v[76:79], v[144:147], v[208:211], v[76:79]
	v_mfma_f32_16x16x32_bf16 v[72:75], v[160:163], v[208:211], v[72:75]
	v_mfma_f32_16x16x32_bf16 v[124:127], v[148:151], v[188:191], v[124:127]
	v_mfma_f32_16x16x32_bf16 v[120:123], v[164:167], v[188:191], v[120:123]
	v_mfma_f32_16x16x32_bf16 v[108:111], v[148:151], v[196:199], v[108:111]
	v_mfma_f32_16x16x32_bf16 v[104:107], v[164:167], v[196:199], v[104:107]
	v_mfma_f32_16x16x32_bf16 v[92:95], v[148:151], v[204:207], v[92:95]
	v_mfma_f32_16x16x32_bf16 v[88:91], v[164:167], v[204:207], v[88:91]
	v_mfma_f32_16x16x32_bf16 v[76:79], v[148:151], v[212:215], v[76:79]
	v_mfma_f32_16x16x32_bf16 v[72:75], v[164:167], v[212:215], v[72:75]
	s_setprio 0
	s_setprio 1
	v_mfma_f32_16x16x32_bf16 v[116:119], v[168:171], v[184:187], v[116:119]
	v_mfma_f32_16x16x32_bf16 v[112:115], v[176:179], v[184:187], v[112:115]
	v_mfma_f32_16x16x32_bf16 v[100:103], v[168:171], v[192:195], v[100:103]
	v_mfma_f32_16x16x32_bf16 v[96:99], v[176:179], v[192:195], v[96:99]
	v_mfma_f32_16x16x32_bf16 v[84:87], v[168:171], v[200:203], v[84:87]
	v_mfma_f32_16x16x32_bf16 v[80:83], v[176:179], v[200:203], v[80:83]
	v_mfma_f32_16x16x32_bf16 v[68:71], v[168:171], v[208:211], v[68:71]
	v_mfma_f32_16x16x32_bf16 v[64:67], v[176:179], v[208:211], v[64:67]
	v_mfma_f32_16x16x32_bf16 v[116:119], v[172:175], v[188:191], v[116:119]
	v_mfma_f32_16x16x32_bf16 v[112:115], v[180:183], v[188:191], v[112:115]
	v_mfma_f32_16x16x32_bf16 v[100:103], v[172:175], v[196:199], v[100:103]
	v_mfma_f32_16x16x32_bf16 v[96:99], v[180:183], v[196:199], v[96:99]
	v_mfma_f32_16x16x32_bf16 v[84:87], v[172:175], v[204:207], v[84:87]
	v_mfma_f32_16x16x32_bf16 v[80:83], v[180:183], v[204:207], v[80:83]
	v_mfma_f32_16x16x32_bf16 v[68:71], v[172:175], v[212:215], v[68:71]
	v_mfma_f32_16x16x32_bf16 v[64:67], v[180:183], v[212:215], v[64:67]
	s_setprio 0
	s_barrier
; #define PG8_STAGE(bufoff, gbase, voff) do { _Pragma("unroll") for (int _i = 0; _i < 2; ++_i) \
;         __builtin_amdgcn_global_load_lds((const unsigned*)((const char*)(gbase) + (voff)[_i]), (PG8_LAS unsigned*)(lds + (bufoff) + ldsw + _i * 8192), 16, 0, 0); } while (0)
; #define PG8_LDA(dst, b, h) do { _Pragma("unroll") for (int m = 0; m < 4; ++m) _Pragma("unroll") for (int k = 0; k < 2; ++k) dst[m][k] = *(const PG8_LAS bf16x8*)(lds + PG8_SA(b, h) + aoff + m * 2048 + k * 1024); } while (0)
; #define PG8_MMA(ai, bj, At, Bt) do { __builtin_amdgcn_s_setprio(1); _Pragma("unroll") for (int m = 0; m < 4; ++m) _Pragma("unroll") for (int n = 0; n < 2; ++n) _Pragma("unroll") for (int k = 0; k < 2; ++k) \
;         acc[ai][bj][m][n] = __builtin_amdgcn_mfma_f32_16x16x32_bf16(Bt[n][k], At[m][k], acc[ai][bj][m][n], 0, 0, 0); __builtin_amdgcn_s_setprio(0); } while (0)
; #define PG8_WAIT_V(n) asm volatile("s_waitcnt vmcnt(" #n ")" ::: "memory")
; #define PG8_WAIT_L(n) asm volatile("s_waitcnt lgkmcnt(" #n ")" ::: "memory")
; #define PG8_BAR __builtin_amdgcn_s_barrier()
; #define PG8_SCHED __builtin_amdgcn_sched_barrier(0)
; template <class Epi, class Sched, bool ALIGN_EPI = false, bool SP2 = false>
; __device__ __forceinline__ void gemm_phase(PG8_LAS unsigned char* lds, const Gemm g, const Sched& S, const Epi& E) {
;     ...
;             PG8_LDA(At, 1, 1); PG8_STAGE(PG8_SB(1, 0), b3, voffB); PG8_STAGE(PG8_SB(1, 1), b3 + hstep, voffB); PG8_STAGE(PG8_SA(1, 0), a3, voffA);
;             PG8_WAIT_V(8); PG8_WAIT_L(0); PG8_BAR; PG8_MMA(1, 0, At, B0); PG8_MMA(1, 1, At, B1); PG8_BAR; PG8_SCHED;
;     ...
;         if constexpr (ALIGN_EPI) { if (wr == 0) PG8_BAR; }
	s_add_i32 s34, s55, s39
	v_lshl_add_u64 v[216:217], v[216:217], 0, s[14:15]
	s_mov_b32 m0, s34
	ds_read_b128 v[184:187], v157 offset:49152
	ds_read_b128 v[188:191], v157 offset:50176
	ds_read_b128 v[192:195], v157 offset:51200
	ds_read_b128 v[196:199], v157 offset:52224
	ds_read_b128 v[200:203], v157 offset:53248
	ds_read_b128 v[204:207], v157 offset:54272
	ds_read_b128 v[208:211], v157 offset:55296
	ds_read_b128 v[212:215], v157 offset:56320
	global_load_lds_dwordx4 v[216:217], off
	s_add_i32 m0, s34, 0x2000
	s_add_u32 s30, s30, 0x80080
	v_lshl_add_u64 v[216:217], v[218:219], 0, s[14:15]
	s_addc_u32 s31, s31, 0
	s_add_i32 s34, s56, s39
	global_load_lds_dwordx4 v[216:217], off
	v_lshl_add_u64 v[216:217], s[30:31], 0, v[130:131]
	s_mov_b32 m0, s34
	s_nop 0
	global_load_lds_dwordx4 v[216:217], off
	v_lshl_add_u64 v[216:217], s[30:31], 0, v[134:135]
	s_add_i32 m0, s34, 0x2000
	s_nop 0
	global_load_lds_dwordx4 v[216:217], off
	v_lshl_add_u64 v[216:217], v[220:221], 0, s[14:15]
	s_mov_b32 m0, s44
	s_nop 0
	global_load_lds_dwordx4 v[216:217], off
	v_lshl_add_u64 v[216:217], v[222:223], 0, s[14:15]
	s_mov_b32 m0, s45
	s_nop 0
	global_load_lds_dwordx4 v[216:217], off
	s_waitcnt vmcnt(8)
	s_barrier
	s_setprio 1
	s_waitcnt lgkmcnt(0)
	v_mfma_f32_16x16x32_bf16 v[60:63], v[144:147], v[184:187], v[60:63]
	v_mfma_f32_16x16x32_bf16 v[56:59], v[160:163], v[184:187], v[56:59]
	v_mfma_f32_16x16x32_bf16 v[44:47], v[144:147], v[192:195], v[44:47]
	v_mfma_f32_16x16x32_bf16 v[40:43], v[160:163], v[192:195], v[40:43]
	v_mfma_f32_16x16x32_bf16 v[28:31], v[144:147], v[200:203], v[28:31]
	v_mfma_f32_16x16x32_bf16 v[24:27], v[160:163], v[200:203], v[24:27]
	v_mfma_f32_16x16x32_bf16 v[12:15], v[144:147], v[208:211], v[12:15]
	v_mfma_f32_16x16x32_bf16 v[8:11], v[160:163], v[208:211], v[8:11]
	v_mfma_f32_16x16x32_bf16 v[60:63], v[148:151], v[188:191], v[60:63]
	v_mfma_f32_16x16x32_bf16 v[56:59], v[164:167], v[188:191], v[56:59]
	v_mfma_f32_16x16x32_bf16 v[44:47], v[148:151], v[196:199], v[44:47]
	v_mfma_f32_16x16x32_bf16 v[40:43], v[164:167], v[196:199], v[40:43]
	v_mfma_f32_16x16x32_bf16 v[28:31], v[148:151], v[204:207], v[28:31]
	v_mfma_f32_16x16x32_bf16 v[24:27], v[164:167], v[204:207], v[24:27]
	v_mfma_f32_16x16x32_bf16 v[12:15], v[148:151], v[212:215], v[12:15]
	v_mfma_f32_16x16x32_bf16 v[8:11], v[164:167], v[212:215], v[8:11]
	s_setprio 0
	s_setprio 1
	v_mfma_f32_16x16x32_bf16 v[52:55], v[168:171], v[184:187], v[52:55]
	v_mfma_f32_16x16x32_bf16 v[48:51], v[176:179], v[184:187], v[48:51]
	v_mfma_f32_16x16x32_bf16 v[36:39], v[168:171], v[192:195], v[36:39]
	v_mfma_f32_16x16x32_bf16 v[32:35], v[176:179], v[192:195], v[32:35]
	v_mfma_f32_16x16x32_bf16 v[20:23], v[168:171], v[200:203], v[20:23]
	v_mfma_f32_16x16x32_bf16 v[16:19], v[176:179], v[200:203], v[16:19]
	v_mfma_f32_16x16x32_bf16 v[4:7], v[168:171], v[208:211], v[4:7]
	v_mfma_f32_16x16x32_bf16 v[0:3], v[176:179], v[208:211], v[0:3]
	v_mfma_f32_16x16x32_bf16 v[52:55], v[172:175], v[188:191], v[52:55]
	v_mfma_f32_16x16x32_bf16 v[48:51], v[180:183], v[188:191], v[48:51]
	v_mfma_f32_16x16x32_bf16 v[36:39], v[172:175], v[196:199], v[36:39]
	v_mfma_f32_16x16x32_bf16 v[32:35], v[180:183], v[196:199], v[32:35]
	v_mfma_f32_16x16x32_bf16 v[20:23], v[172:175], v[204:207], v[20:23]
	v_mfma_f32_16x16x32_bf16 v[16:19], v[180:183], v[204:207], v[16:19]
	v_mfma_f32_16x16x32_bf16 v[4:7], v[172:175], v[212:215], v[4:7]
	v_mfma_f32_16x16x32_bf16 v[0:3], v[180:183], v[212:215], v[0:3]
	s_setprio 0
	s_barrier
	s_add_i32 s53, s53, 2
	s_add_u32 s28, s28, 0x100
	s_addc_u32 s29, s29, 0
	s_add_u32 s51, s51, 0x100
	s_addc_u32 s52, s52, 0
	s_cmp_gt_u32 s53, 29
	s_cbranch_scc0 .LBB0_1562
	s_and_b64 vcc, exec, s[16:17]
	s_cbranch_vccz .LBB0_1565
	s_barrier
